# hazard-pad replacement: the M0-write to LDS-DMA wait state in all GEMM K-loops is now supplied by the address VALU op instead of s_nop (56 sites)
# speedup vs baseline: 1.0015x; 1.0015x over previous
; #define PG8_STAGE(bufoff, gbase, voff) do { _Pragma("unroll") for (int _i = 0; _i < 2; ++_i) \
;         __builtin_amdgcn_global_load_lds((const unsigned*)((const char*)(gbase) + (voff)[_i]), (LAS unsigned*)(lds + (bufoff) + ldsw + _i * 8192), 16, 0, 0); } while (0)
; #define PG8_LDA(dst, b, h) do { _Pragma("unroll") for (int m = 0; m < 4; ++m) _Pragma("unroll") for (int k = 0; k < 2; ++k) dst[m][k] = *(const LAS bf16x8*)(lds + PG8_SA(b, h) + aoff + m * 2048 + k * 1024); } while (0)
; #define PG8_LDB(dst, b, h) do { _Pragma("unroll") for (int n = 0; n < 2; ++n) _Pragma("unroll") for (int k = 0; k < 2; ++k) dst[n][k] = *(const LAS bf16x8*)(lds + PG8_SB(b, h) + boff + n * 2048 + k * 1024); } while (0)
; #define PG8_MMA(ai, bj, At, Bt) do { __builtin_amdgcn_s_setprio(1); _Pragma("unroll") for (int m = 0; m < 4; ++m) _Pragma("unroll") for (int n = 0; n < 2; ++n) _Pragma("unroll") for (int k = 0; k < 2; ++k) \
;         acc[ai][bj][m][n] = __builtin_amdgcn_mfma_f32_16x16x32_bf16(Bt[n][k], At[m][k], acc[ai][bj][m][n], 0, 0, 0); __builtin_amdgcn_s_setprio(0); } while (0)
; #define PG8_WAIT_V(n) asm volatile("s_waitcnt vmcnt(" #n ")" ::: "memory")
; #define PG8_WAIT_L(n) asm volatile("s_waitcnt lgkmcnt(" #n ")" ::: "memory")
; #define PG8_BAR __builtin_amdgcn_s_barrier()
; #define PG8_SCHED __builtin_amdgcn_sched_barrier(0)
; template <class Epi, class Sched>
; __device__ __forceinline__ void gemm_phase(const int TID, LAS unsigned char* lds, const int lda, const int ldb, const Sched& S, const Epi& E) {
;     ...
;             PG8_LDB(B0, 0, 0); PG8_SCHED; PG8_LDA(At, 0, 0); PG8_STAGE(PG8_SA(1, 1), a1 + hA, voffA);
;             PG8_WAIT_L(8); PG8_BAR; PG8_WAIT_L(0); PG8_MMA(0, 0, At, B0); PG8_BAR; PG8_SCHED;
;             PG8_LDB(B1, 0, 1); PG8_STAGE(PG8_SB(0, 0), b2, voffB);
;             PG8_BAR; PG8_WAIT_L(0); PG8_MMA(0, 1, At, B1); PG8_BAR;
;             PG8_LDA(At, 0, 1); PG8_STAGE(PG8_SA(0, 0), a2, voffA);
;             PG8_BAR; PG8_WAIT_L(0); PG8_MMA(1, 0, At, B0); PG8_BAR; PG8_SCHED;
;             PG8_STAGE(PG8_SB(0, 1), b2 + hB, voffB);
;             PG8_WAIT_V(6); PG8_BAR; PG8_MMA(1, 1, At, B1); PG8_BAR;
.Lk7_noprio:
.Lk7_pbody:
	s_add_u32 s8, s50, 0xfff80080
	s_addc_u32 s9, s51, -1
	s_add_i32 s10, 0, 0x10000
	v_add_u32_e32 v158, s10, v155
	ds_read_b128 v[140:143], v158
	ds_read_b128 v[144:147], v158 offset:1024
	ds_read_b128 v[148:151], v158 offset:2048
	ds_read_b128 v[158:161], v158 offset:3072
	s_cmp_eq_u32 s49, 28
	s_cselect_b32 s55, s45, s9
	s_cselect_b32 s54, s44, s8
	s_cselect_b32 s53, s47, s43
	s_cselect_b32 s52, s46, s41
	v_lshl_add_u64 v[204:205], s[50:51], 0, v[138:139]
	s_add_i32 m0, s24, 0xc000
	ds_read_b128 v[162:165], v157
	ds_read_b128 v[166:169], v157 offset:1024
	ds_read_b128 v[170:173], v157 offset:2048
	ds_read_b128 v[174:177], v157 offset:3072
	ds_read_b128 v[178:181], v157 offset:4096
	ds_read_b128 v[186:189], v157 offset:5120
	ds_read_b128 v[196:199], v157 offset:6144
	ds_read_b128 v[200:203], v157 offset:7168
	global_load_lds_dwordx4 v[204:205], off
	s_add_i32 m0, s24, 0xe000
	v_lshl_add_u64 v[204:205], s[50:51], 0, v[136:137]
	global_load_lds_dwordx4 v[204:205], off
	s_waitcnt lgkmcnt(8)
	s_barrier
	s_waitcnt lgkmcnt(0)
	s_waitcnt lgkmcnt(0)
	v_mfma_f32_16x16x32_bf16 v[130:133], v[140:143], v[162:165], v[130:133]
	v_mfma_f32_16x16x32_bf16 v[126:129], v[148:151], v[162:165], v[126:129]
	v_mfma_f32_16x16x32_bf16 v[114:117], v[140:143], v[170:173], v[114:117]
	v_mfma_f32_16x16x32_bf16 v[110:113], v[148:151], v[170:173], v[110:113]
	v_mfma_f32_16x16x32_bf16 v[98:101], v[140:143], v[178:181], v[98:101]
	v_mfma_f32_16x16x32_bf16 v[94:97], v[148:151], v[178:181], v[94:97]
	v_mfma_f32_16x16x32_bf16 v[82:85], v[140:143], v[196:199], v[82:85]
	v_mfma_f32_16x16x32_bf16 v[78:81], v[148:151], v[196:199], v[78:81]
	v_mfma_f32_16x16x32_bf16 v[130:133], v[144:147], v[166:169], v[130:133]
	v_mfma_f32_16x16x32_bf16 v[126:129], v[158:161], v[166:169], v[126:129]
	v_mfma_f32_16x16x32_bf16 v[114:117], v[144:147], v[174:177], v[114:117]
	v_mfma_f32_16x16x32_bf16 v[110:113], v[158:161], v[174:177], v[110:113]
	v_mfma_f32_16x16x32_bf16 v[98:101], v[144:147], v[186:189], v[98:101]
	v_mfma_f32_16x16x32_bf16 v[94:97], v[158:161], v[186:189], v[94:97]
	v_mfma_f32_16x16x32_bf16 v[82:85], v[144:147], v[200:203], v[82:85]
	v_mfma_f32_16x16x32_bf16 v[78:81], v[158:161], v[200:203], v[78:81]
	s_barrier
	s_add_i32 s11, 0, 0x14000
	s_add_i32 s8, s10, s23
	v_add_u32_e32 v182, s11, v155
	v_lshl_add_u64 v[220:221], s[52:53], 0, v[12:13]
	s_mov_b32 m0, s8
	ds_read_b128 v[204:207], v182
	ds_read_b128 v[208:211], v182 offset:1024
	ds_read_b128 v[212:215], v182 offset:2048
	ds_read_b128 v[216:219], v182 offset:3072
	global_load_lds_dwordx4 v[220:221], off
	s_add_i32 m0, s8, 0x2000
	v_lshl_add_u64 v[222:223], s[52:53], 0, v[134:135]
	global_load_lds_dwordx4 v[222:223], off
	s_barrier
	s_waitcnt lgkmcnt(0)
	s_waitcnt lgkmcnt(0)
	v_mfma_f32_16x16x32_bf16 v[122:125], v[204:207], v[162:165], v[122:125]
	v_mfma_f32_16x16x32_bf16 v[118:121], v[212:215], v[162:165], v[118:121]
	v_mfma_f32_16x16x32_bf16 v[106:109], v[204:207], v[170:173], v[106:109]
	v_mfma_f32_16x16x32_bf16 v[102:105], v[212:215], v[170:173], v[102:105]
	v_mfma_f32_16x16x32_bf16 v[90:93], v[204:207], v[178:181], v[90:93]
	v_mfma_f32_16x16x32_bf16 v[86:89], v[212:215], v[178:181], v[86:89]
	v_mfma_f32_16x16x32_bf16 v[74:77], v[204:207], v[196:199], v[74:77]
	v_mfma_f32_16x16x32_bf16 v[70:73], v[212:215], v[196:199], v[70:73]
	v_mfma_f32_16x16x32_bf16 v[122:125], v[208:211], v[166:169], v[122:125]
	v_mfma_f32_16x16x32_bf16 v[118:121], v[216:219], v[166:169], v[118:121]
	v_mfma_f32_16x16x32_bf16 v[106:109], v[208:211], v[174:177], v[106:109]
	v_mfma_f32_16x16x32_bf16 v[102:105], v[216:219], v[174:177], v[102:105]
	v_mfma_f32_16x16x32_bf16 v[90:93], v[208:211], v[186:189], v[90:93]
	v_mfma_f32_16x16x32_bf16 v[86:89], v[216:219], v[186:189], v[86:89]
	v_mfma_f32_16x16x32_bf16 v[74:77], v[208:211], v[200:203], v[74:77]
	v_mfma_f32_16x16x32_bf16 v[70:73], v[216:219], v[200:203], v[70:73]
	s_mov_b32 m0, s24
	v_lshl_add_u64 v[236:237], s[54:55], 0, v[12:13]
	s_barrier
	ds_read_b128 v[162:165], v157 offset:16384
	ds_read_b128 v[166:169], v157 offset:17408
	ds_read_b128 v[170:173], v157 offset:18432
	ds_read_b128 v[174:177], v157 offset:19456
	ds_read_b128 v[178:181], v157 offset:20480
	ds_read_b128 v[186:189], v157 offset:21504
	ds_read_b128 v[196:199], v157 offset:22528
	ds_read_b128 v[200:203], v157 offset:23552
	global_load_lds_dwordx4 v[236:237], off
	s_mov_b32 m0, s56
	v_lshl_add_u64 v[238:239], s[54:55], 0, v[134:135]
	global_load_lds_dwordx4 v[238:239], off
	s_barrier
	s_waitcnt lgkmcnt(0)
	s_waitcnt lgkmcnt(0)
	v_mfma_f32_16x16x32_bf16 v[66:69], v[140:143], v[162:165], v[66:69]
	v_mfma_f32_16x16x32_bf16 v[62:65], v[148:151], v[162:165], v[62:65]
	v_mfma_f32_16x16x32_bf16 v[50:53], v[140:143], v[170:173], v[50:53]
	v_mfma_f32_16x16x32_bf16 v[46:49], v[148:151], v[170:173], v[46:49]
	v_mfma_f32_16x16x32_bf16 v[34:37], v[140:143], v[178:181], v[34:37]
	v_mfma_f32_16x16x32_bf16 v[30:33], v[148:151], v[178:181], v[30:33]
	v_mfma_f32_16x16x32_bf16 v[18:21], v[140:143], v[196:199], v[18:21]
	v_mfma_f32_16x16x32_bf16 v[8:11], v[148:151], v[196:199], v[8:11]
	v_mfma_f32_16x16x32_bf16 v[66:69], v[144:147], v[166:169], v[66:69]
	v_mfma_f32_16x16x32_bf16 v[62:65], v[158:161], v[166:169], v[62:65]
	v_mfma_f32_16x16x32_bf16 v[50:53], v[144:147], v[174:177], v[50:53]
	v_mfma_f32_16x16x32_bf16 v[46:49], v[158:161], v[174:177], v[46:49]
	v_mfma_f32_16x16x32_bf16 v[34:37], v[144:147], v[186:189], v[34:37]
	v_mfma_f32_16x16x32_bf16 v[30:33], v[158:161], v[186:189], v[30:33]
	v_mfma_f32_16x16x32_bf16 v[18:21], v[144:147], v[200:203], v[18:21]
	v_mfma_f32_16x16x32_bf16 v[8:11], v[158:161], v[200:203], v[8:11]
	s_barrier
; #define PG8_STAGE(bufoff, gbase, voff) do { _Pragma("unroll") for (int _i = 0; _i < 2; ++_i) \
;         __builtin_amdgcn_global_load_lds((const unsigned*)((const char*)(gbase) + (voff)[_i]), (LAS unsigned*)(lds + (bufoff) + ldsw + _i * 8192), 16, 0, 0); } while (0)
; #define PG8_LDA(dst, b, h) do { _Pragma("unroll") for (int m = 0; m < 4; ++m) _Pragma("unroll") for (int k = 0; k < 2; ++k) dst[m][k] = *(const LAS bf16x8*)(lds + PG8_SA(b, h) + aoff + m * 2048 + k * 1024); } while (0)
; #define PG8_LDB(dst, b, h) do { _Pragma("unroll") for (int n = 0; n < 2; ++n) _Pragma("unroll") for (int k = 0; k < 2; ++k) dst[n][k] = *(const LAS bf16x8*)(lds + PG8_SB(b, h) + boff + n * 2048 + k * 1024); } while (0)
; #define PG8_MMA(ai, bj, At, Bt) do { __builtin_amdgcn_s_setprio(1); _Pragma("unroll") for (int m = 0; m < 4; ++m) _Pragma("unroll") for (int n = 0; n < 2; ++n) _Pragma("unroll") for (int k = 0; k < 2; ++k) \
;         acc[ai][bj][m][n] = __builtin_amdgcn_mfma_f32_16x16x32_bf16(Bt[n][k], At[m][k], acc[ai][bj][m][n], 0, 0, 0); __builtin_amdgcn_s_setprio(0); } while (0)
; #define PG8_WAIT_V(n) asm volatile("s_waitcnt vmcnt(" #n ")" ::: "memory")
; #define PG8_WAIT_L(n) asm volatile("s_waitcnt lgkmcnt(" #n ")" ::: "memory")
; #define PG8_BAR __builtin_amdgcn_s_barrier()
; #define PG8_SCHED __builtin_amdgcn_sched_barrier(0)
; template <class Epi, class Sched>
; __device__ __forceinline__ void gemm_phase(const int TID, LAS unsigned char* lds, const int lda, const int ldb, const Sched& S, const Epi& E) {
;     ...
;             PG8_WAIT_V(6); PG8_BAR; PG8_MMA(1, 1, At, B1); PG8_BAR;
;             PG8_LDB(B0, 1, 0); PG8_SCHED; PG8_LDA(At, 1, 0); PG8_STAGE(PG8_SA(0, 1), a2 + hA, voffA);
;             PG8_WAIT_L(8); PG8_BAR; PG8_WAIT_L(0); PG8_MMA(0, 0, At, B0); PG8_BAR; PG8_SCHED;
;             PG8_LDB(B1, 1, 1); PG8_STAGE(PG8_SB(1, 0), b3, voffB);
;             PG8_BAR; PG8_WAIT_L(0); PG8_MMA(0, 1, At, B1); PG8_BAR;
;             PG8_LDA(At, 1, 1); PG8_STAGE(PG8_SA(1, 0), a3, voffA);
;             PG8_BAR; PG8_WAIT_L(0); PG8_MMA(1, 0, At, B0); PG8_BAR; PG8_SCHED;
	s_add_u32 s8, s52, 0x80000
	s_addc_u32 s9, s53, 0
	s_add_i32 s10, s11, s23
	s_mov_b32 m0, s10
	v_lshl_add_u64 v[140:141], s[8:9], 0, v[12:13]
	global_load_lds_dwordx4 v[140:141], off
	s_add_i32 m0, s10, 0x2000
	v_lshl_add_u64 v[140:141], s[8:9], 0, v[134:135]
	global_load_lds_dwordx4 v[140:141], off
	s_waitcnt vmcnt(6)
	s_barrier
	v_mfma_f32_16x16x32_bf16 v[58:61], v[204:207], v[162:165], v[58:61]
	v_mfma_f32_16x16x32_bf16 v[54:57], v[212:215], v[162:165], v[54:57]
	v_mfma_f32_16x16x32_bf16 v[42:45], v[204:207], v[170:173], v[42:45]
	v_mfma_f32_16x16x32_bf16 v[38:41], v[212:215], v[170:173], v[38:41]
	v_mfma_f32_16x16x32_bf16 v[26:29], v[204:207], v[178:181], v[26:29]
	v_mfma_f32_16x16x32_bf16 v[22:25], v[212:215], v[178:181], v[22:25]
	v_mfma_f32_16x16x32_bf16 v[4:7], v[204:207], v[196:199], v[4:7]
	v_mfma_f32_16x16x32_bf16 v[0:3], v[212:215], v[196:199], v[0:3]
	v_mfma_f32_16x16x32_bf16 v[58:61], v[208:211], v[166:169], v[58:61]
	v_mfma_f32_16x16x32_bf16 v[54:57], v[216:219], v[166:169], v[54:57]
	v_mfma_f32_16x16x32_bf16 v[42:45], v[208:211], v[174:177], v[42:45]
	v_mfma_f32_16x16x32_bf16 v[38:41], v[216:219], v[174:177], v[38:41]
	v_mfma_f32_16x16x32_bf16 v[26:29], v[208:211], v[186:189], v[26:29]
	v_mfma_f32_16x16x32_bf16 v[22:25], v[216:219], v[186:189], v[22:25]
	v_mfma_f32_16x16x32_bf16 v[4:7], v[208:211], v[200:203], v[4:7]
	v_mfma_f32_16x16x32_bf16 v[0:3], v[216:219], v[200:203], v[0:3]
	s_add_i32 s10, 0, 0x18000
	v_add_u32_e32 v158, s10, v155
	s_barrier
	ds_read_b128 v[140:143], v158
	ds_read_b128 v[144:147], v158 offset:1024
	ds_read_b128 v[148:151], v158 offset:2048
	ds_read_b128 v[158:161], v158 offset:3072
	s_add_u32 s8, s54, 0x80000
	s_addc_u32 s9, s55, 0
	s_mov_b32 m0, s57
	v_lshl_add_u64 v[204:205], s[8:9], 0, v[12:13]
	ds_read_b128 v[162:165], v157 offset:32768
	ds_read_b128 v[166:169], v157 offset:33792
	ds_read_b128 v[170:173], v157 offset:34816
	ds_read_b128 v[174:177], v157 offset:35840
	ds_read_b128 v[178:181], v157 offset:36864
	ds_read_b128 v[186:189], v157 offset:37888
	ds_read_b128 v[196:199], v157 offset:38912
	ds_read_b128 v[200:203], v157 offset:39936
	global_load_lds_dwordx4 v[204:205], off
	s_mov_b32 m0, s58
	v_lshl_add_u64 v[204:205], s[8:9], 0, v[134:135]
	global_load_lds_dwordx4 v[204:205], off
	s_waitcnt lgkmcnt(8)
	s_barrier
	s_waitcnt lgkmcnt(0)
	s_waitcnt lgkmcnt(0)
	v_mfma_f32_16x16x32_bf16 v[130:133], v[140:143], v[162:165], v[130:133]
	v_mfma_f32_16x16x32_bf16 v[126:129], v[148:151], v[162:165], v[126:129]
	v_mfma_f32_16x16x32_bf16 v[114:117], v[140:143], v[170:173], v[114:117]
	v_mfma_f32_16x16x32_bf16 v[110:113], v[148:151], v[170:173], v[110:113]
	v_mfma_f32_16x16x32_bf16 v[98:101], v[140:143], v[178:181], v[98:101]
	v_mfma_f32_16x16x32_bf16 v[94:97], v[148:151], v[178:181], v[94:97]
	v_mfma_f32_16x16x32_bf16 v[82:85], v[140:143], v[196:199], v[82:85]
	v_mfma_f32_16x16x32_bf16 v[78:81], v[148:151], v[196:199], v[78:81]
	v_mfma_f32_16x16x32_bf16 v[130:133], v[144:147], v[166:169], v[130:133]
	v_mfma_f32_16x16x32_bf16 v[126:129], v[158:161], v[166:169], v[126:129]
	v_mfma_f32_16x16x32_bf16 v[114:117], v[144:147], v[174:177], v[114:117]
	v_mfma_f32_16x16x32_bf16 v[110:113], v[158:161], v[174:177], v[110:113]
	v_mfma_f32_16x16x32_bf16 v[98:101], v[144:147], v[186:189], v[98:101]
	v_mfma_f32_16x16x32_bf16 v[94:97], v[158:161], v[186:189], v[94:97]
	v_mfma_f32_16x16x32_bf16 v[82:85], v[144:147], v[200:203], v[82:85]
	v_mfma_f32_16x16x32_bf16 v[78:81], v[158:161], v[200:203], v[78:81]
	s_barrier
	s_add_i32 s11, 0, 0x1c000
	s_add_i32 s8, s10, s23
	v_add_u32_e32 v182, s11, v155
	v_lshl_add_u64 v[220:221], v[220:221], 0, s[36:37]
	s_mov_b32 m0, s8
	ds_read_b128 v[204:207], v182
	ds_read_b128 v[208:211], v182 offset:1024
	ds_read_b128 v[212:215], v182 offset:2048
	ds_read_b128 v[216:219], v182 offset:3072
	global_load_lds_dwordx4 v[220:221], off
	s_add_i32 m0, s8, 0x2000
	v_lshl_add_u64 v[220:221], v[222:223], 0, s[36:37]
	global_load_lds_dwordx4 v[220:221], off
	s_barrier
	s_waitcnt lgkmcnt(0)
	s_waitcnt lgkmcnt(0)
	v_mfma_f32_16x16x32_bf16 v[122:125], v[204:207], v[162:165], v[122:125]
	v_mfma_f32_16x16x32_bf16 v[118:121], v[212:215], v[162:165], v[118:121]
	v_mfma_f32_16x16x32_bf16 v[106:109], v[204:207], v[170:173], v[106:109]
	v_mfma_f32_16x16x32_bf16 v[102:105], v[212:215], v[170:173], v[102:105]
	v_mfma_f32_16x16x32_bf16 v[90:93], v[204:207], v[178:181], v[90:93]
	v_mfma_f32_16x16x32_bf16 v[86:89], v[212:215], v[178:181], v[86:89]
	v_mfma_f32_16x16x32_bf16 v[74:77], v[204:207], v[196:199], v[74:77]
	v_mfma_f32_16x16x32_bf16 v[70:73], v[212:215], v[196:199], v[70:73]
	v_mfma_f32_16x16x32_bf16 v[122:125], v[208:211], v[166:169], v[122:125]
	v_mfma_f32_16x16x32_bf16 v[118:121], v[216:219], v[166:169], v[118:121]
	v_mfma_f32_16x16x32_bf16 v[106:109], v[208:211], v[174:177], v[106:109]
	v_mfma_f32_16x16x32_bf16 v[102:105], v[216:219], v[174:177], v[102:105]
	v_mfma_f32_16x16x32_bf16 v[90:93], v[208:211], v[186:189], v[90:93]
	v_mfma_f32_16x16x32_bf16 v[86:89], v[216:219], v[186:189], v[86:89]
	v_mfma_f32_16x16x32_bf16 v[74:77], v[208:211], v[200:203], v[74:77]
	v_mfma_f32_16x16x32_bf16 v[70:73], v[216:219], v[200:203], v[70:73]
	s_mov_b32 m0, s59
	v_lshl_add_u64 v[220:221], v[236:237], 0, s[36:37]
	s_barrier
	ds_read_b128 v[162:165], v157 offset:49152
	ds_read_b128 v[166:169], v157 offset:50176
	ds_read_b128 v[170:173], v157 offset:51200
	ds_read_b128 v[174:177], v157 offset:52224
	ds_read_b128 v[178:181], v157 offset:53248
	ds_read_b128 v[186:189], v157 offset:54272
	ds_read_b128 v[196:199], v157 offset:55296
	ds_read_b128 v[200:203], v157 offset:56320
	global_load_lds_dwordx4 v[220:221], off
	s_mov_b32 m0, s60
	v_lshl_add_u64 v[220:221], v[238:239], 0, s[36:37]
	global_load_lds_dwordx4 v[220:221], off
	s_barrier
; #define PG8_STAGE(bufoff, gbase, voff) do { _Pragma("unroll") for (int _i = 0; _i < 2; ++_i) \
;         __builtin_amdgcn_global_load_lds((const unsigned*)((const char*)(gbase) + (voff)[_i]), (LAS unsigned*)(lds + (bufoff) + ldsw + _i * 8192), 16, 0, 0); } while (0)
; #define PG8_MMA(ai, bj, At, Bt) do { __builtin_amdgcn_s_setprio(1); _Pragma("unroll") for (int m = 0; m < 4; ++m) _Pragma("unroll") for (int n = 0; n < 2; ++n) _Pragma("unroll") for (int k = 0; k < 2; ++k) \
;         acc[ai][bj][m][n] = __builtin_amdgcn_mfma_f32_16x16x32_bf16(Bt[n][k], At[m][k], acc[ai][bj][m][n], 0, 0, 0); __builtin_amdgcn_s_setprio(0); } while (0)
; #define PG8_WAIT_V(n) asm volatile("s_waitcnt vmcnt(" #n ")" ::: "memory")
; #define PG8_WAIT_L(n) asm volatile("s_waitcnt lgkmcnt(" #n ")" ::: "memory")
; #define PG8_BAR __builtin_amdgcn_s_barrier()
; #define PG8_SCHED __builtin_amdgcn_sched_barrier(0)
; template <class Epi, class Sched>
; __device__ __forceinline__ void gemm_phase(const int TID, LAS unsigned char* lds, const int lda, const int ldb, const Sched& S, const Epi& E) {
;     ...
;             PG8_BAR; PG8_WAIT_L(0); PG8_MMA(1, 0, At, B0); PG8_BAR; PG8_SCHED;
;             PG8_STAGE(PG8_SB(1, 1), b3 + hB, voffB);
;             PG8_WAIT_V(6); PG8_BAR; PG8_MMA(1, 1, At, B1); PG8_BAR;
; __device__ __forceinline__ const float* src_row(const Params& p, int r) {
;     int s, pos; if (r < 8224) { s = r / 4112; pos = r - s * 4112; } else { const int t = r - 8224; const int q = t / 2064; s = 2 + q; pos = t - q * 2064; }
;     if (pos < 16) return p.in[2] + (size_t)pos * D;
;     return s < 2 ? p.in[0] + ((size_t)s * 4096 + (pos - 16)) * D : p.in[1] + ((size_t)(s - 2) * 2048 + (pos - 16)) * D;
	s_waitcnt lgkmcnt(0)
	s_waitcnt lgkmcnt(0)
	v_mfma_f32_16x16x32_bf16 v[66:69], v[140:143], v[162:165], v[66:69]
	v_mfma_f32_16x16x32_bf16 v[62:65], v[148:151], v[162:165], v[62:65]
	v_mfma_f32_16x16x32_bf16 v[50:53], v[140:143], v[170:173], v[50:53]
	v_mfma_f32_16x16x32_bf16 v[46:49], v[148:151], v[170:173], v[46:49]
	v_mfma_f32_16x16x32_bf16 v[34:37], v[140:143], v[178:181], v[34:37]
	v_mfma_f32_16x16x32_bf16 v[30:33], v[148:151], v[178:181], v[30:33]
	v_mfma_f32_16x16x32_bf16 v[18:21], v[140:143], v[196:199], v[18:21]
	v_mfma_f32_16x16x32_bf16 v[8:11], v[148:151], v[196:199], v[8:11]
	v_mfma_f32_16x16x32_bf16 v[66:69], v[144:147], v[166:169], v[66:69]
	v_mfma_f32_16x16x32_bf16 v[62:65], v[158:161], v[166:169], v[62:65]
	v_mfma_f32_16x16x32_bf16 v[50:53], v[144:147], v[174:177], v[50:53]
	v_mfma_f32_16x16x32_bf16 v[46:49], v[158:161], v[174:177], v[46:49]
	v_mfma_f32_16x16x32_bf16 v[34:37], v[144:147], v[186:189], v[34:37]
	v_mfma_f32_16x16x32_bf16 v[30:33], v[158:161], v[186:189], v[30:33]
	v_mfma_f32_16x16x32_bf16 v[18:21], v[144:147], v[200:203], v[18:21]
	v_mfma_f32_16x16x32_bf16 v[8:11], v[158:161], v[200:203], v[8:11]
	s_barrier
	s_add_u32 s8, s52, 0x80080
	s_addc_u32 s9, s53, 0
	s_add_i32 s10, s11, s23
	s_mov_b32 m0, s10
	v_lshl_add_u64 v[140:141], s[8:9], 0, v[12:13]
	global_load_lds_dwordx4 v[140:141], off
	s_add_i32 m0, s10, 0x2000
	v_lshl_add_u64 v[140:141], s[8:9], 0, v[134:135]
	global_load_lds_dwordx4 v[140:141], off
	s_waitcnt vmcnt(6)
	s_barrier
	v_mfma_f32_16x16x32_bf16 v[58:61], v[204:207], v[162:165], v[58:61]
	v_mfma_f32_16x16x32_bf16 v[54:57], v[212:215], v[162:165], v[54:57]
	v_mfma_f32_16x16x32_bf16 v[42:45], v[204:207], v[170:173], v[42:45]
	v_mfma_f32_16x16x32_bf16 v[38:41], v[212:215], v[170:173], v[38:41]
	v_mfma_f32_16x16x32_bf16 v[26:29], v[204:207], v[178:181], v[26:29]
	v_mfma_f32_16x16x32_bf16 v[22:25], v[212:215], v[178:181], v[22:25]
	v_mfma_f32_16x16x32_bf16 v[4:7], v[204:207], v[196:199], v[4:7]
	v_mfma_f32_16x16x32_bf16 v[0:3], v[212:215], v[196:199], v[0:3]
	v_mfma_f32_16x16x32_bf16 v[58:61], v[208:211], v[166:169], v[58:61]
	v_mfma_f32_16x16x32_bf16 v[54:57], v[216:219], v[166:169], v[54:57]
	v_mfma_f32_16x16x32_bf16 v[42:45], v[208:211], v[174:177], v[42:45]
	v_mfma_f32_16x16x32_bf16 v[38:41], v[216:219], v[174:177], v[38:41]
	v_mfma_f32_16x16x32_bf16 v[26:29], v[208:211], v[186:189], v[26:29]
	v_mfma_f32_16x16x32_bf16 v[22:25], v[216:219], v[186:189], v[22:25]
	v_mfma_f32_16x16x32_bf16 v[4:7], v[208:211], v[200:203], v[4:7]
	v_mfma_f32_16x16x32_bf16 v[0:3], v[216:219], v[200:203], v[0:3]
	s_add_i32 s49, s49, 2
	s_add_u32 s41, s41, 0x100
	s_addc_u32 s43, s43, 0
	s_add_u32 s50, s50, 0x100
	s_addc_u32 s51, s51, 0
	s_cmp_gt_u32 s49, 29
	s_barrier
	s_cbranch_scc0 .Lk7_pbody
	s_setprio 0
	v_lshl_add_u32 v142, s48, 8, v154
	v_lshl_or_b32 v140, s63, 8, v156
	s_movk_i32 s8, 0x60a0
	v_ashrrev_i32_e32 v141, 31, v140
	v_cmp_gt_i32_e32 vcc, s8, v142
	s_and_saveexec_b64 s[48:49], vcc
	s_cbranch_execz .LBB0_44
	v_ashrrev_i32_e32 v143, 31, v142
	v_lshlrev_b64 v[144:145], 13, v[142:143]
	v_lshl_add_u64 v[144:145], s[94:95], 0, v[144:145]
	s_andn2_b64 vcc, exec, s[28:29]
	v_mov_b64_e32 v[146:147], v[144:145]
	s_cbranch_vccnz .LBB0_43
	s_movk_i32 s8, 0x201f
	v_cmp_lt_i32_e32 vcc, s8, v142
	s_and_saveexec_b64 s[8:9], vcc
	s_xor_b64 s[50:51], exec, s[8:9]
	v_add_u32_e32 v143, 0xffffdfe0, v142
	v_mul_u32_u24_e32 v146, 0x3f81, v143
	v_lshrrev_b32_e32 v146, 25, v146
	s_movk_i32 s8, 0xf7f0
	v_add_u32_e32 v148, 2, v146
	v_mad_i32_i24 v146, v146, s8, v143
	s_andn2_saveexec_b64 s[50:51], s[50:51]
	s_mov_b32 s8, 0x7f807f81
	v_mul_hi_i32 v143, v142, s8
	v_lshrrev_b32_e32 v146, 31, v143
	v_ashrrev_i32_e32 v143, 11, v143
	v_add_u32_e32 v148, v143, v146
	s_movk_i32 s8, 0xeff0
	v_mad_i32_i24 v146, v148, s8, v142
	s_or_b64 exec, exec, s[50:51]
	v_readlane_b32 s64, v254, 0
	v_readlane_b32 s68, v254, 4
	v_readlane_b32 s69, v254, 5
	v_cmp_lt_i32_e32 vcc, 15, v146
	v_readlane_b32 s65, v254, 1
	v_mov_b64_e32 v[150:151], s[68:69]
	v_readlane_b32 s66, v254, 2
	v_readlane_b32 s67, v254, 3
	v_readlane_b32 s70, v254, 6
	v_readlane_b32 s71, v254, 7
	v_readlane_b32 s72, v254, 8
	v_readlane_b32 s73, v254, 9
	v_readlane_b32 s74, v254, 10
	v_readlane_b32 s75, v254, 11
	v_readlane_b32 s76, v254, 12
	v_readlane_b32 s77, v254, 13
	v_readlane_b32 s78, v254, 14
	v_readlane_b32 s79, v254, 15
	s_and_saveexec_b64 s[8:9], vcc
	s_xor_b64 s[50:51], exec, s[8:9]
	s_cbranch_execz .LBB0_40
	v_cmp_lt_i32_e32 vcc, 1, v148
	v_add_u32_e32 v182, -16, v146
	s_and_saveexec_b64 s[8:9], vcc
	s_xor_b64 s[52:53], exec, s[8:9]
	s_cbranch_execz .LBB0_37
	v_add_u32_e32 v146, -2, v148
	v_mov_b32_e32 v147, v183
	v_readlane_b32 s64, v254, 0
	v_lshlrev_b64 v[146:147], 24, v[146:147]
	v_readlane_b32 s66, v254, 2
	v_readlane_b32 s67, v254, 3
	v_readlane_b32 s65, v254, 1
	v_readlane_b32 s68, v254, 4
	v_readlane_b32 s69, v254, 5
	v_readlane_b32 s70, v254, 6
	v_readlane_b32 s71, v254, 7
	v_readlane_b32 s72, v254, 8
	v_readlane_b32 s73, v254, 9
	v_readlane_b32 s74, v254, 10
	v_readlane_b32 s75, v254, 11
	v_readlane_b32 s76, v254, 12
	v_readlane_b32 s77, v254, 13
	v_readlane_b32 s78, v254, 14
	v_readlane_b32 s79, v254, 15
	v_lshl_add_u64 v[150:151], s[66:67], 0, v[146:147]
	v_mov_b64_e32 v[146:147], v[182:183]

; #define PG8_STAGE(bufoff, gbase, voff) do { _Pragma("unroll") for (int _i = 0; _i < 2; ++_i) \
;         __builtin_amdgcn_global_load_lds((const unsigned*)((const char*)(gbase) + (voff)[_i]), (LAS unsigned*)(lds + (bufoff) + ldsw + _i * 8192), 16, 0, 0); } while (0)
; #define PG8_LDA(dst, b, h) do { _Pragma("unroll") for (int m = 0; m < 4; ++m) _Pragma("unroll") for (int k = 0; k < 2; ++k) dst[m][k] = *(const LAS bf16x8*)(lds + PG8_SA(b, h) + aoff + m * 2048 + k * 1024); } while (0)
; #define PG8_LDB(dst, b, h) do { _Pragma("unroll") for (int n = 0; n < 2; ++n) _Pragma("unroll") for (int k = 0; k < 2; ++k) dst[n][k] = *(const LAS bf16x8*)(lds + PG8_SB(b, h) + boff + n * 2048 + k * 1024); } while (0)
; #define PG8_MMA(ai, bj, At, Bt) do { __builtin_amdgcn_s_setprio(1); _Pragma("unroll") for (int m = 0; m < 4; ++m) _Pragma("unroll") for (int n = 0; n < 2; ++n) _Pragma("unroll") for (int k = 0; k < 2; ++k) \
;         acc[ai][bj][m][n] = __builtin_amdgcn_mfma_f32_16x16x32_bf16(Bt[n][k], At[m][k], acc[ai][bj][m][n], 0, 0, 0); __builtin_amdgcn_s_setprio(0); } while (0)
; #define PG8_WAIT_V(n) asm volatile("s_waitcnt vmcnt(" #n ")" ::: "memory")
; #define PG8_WAIT_L(n) asm volatile("s_waitcnt lgkmcnt(" #n ")" ::: "memory")
; template <class Epi, class Sched>
; __device__ __forceinline__ void gemm_phase(const int TID, LAS unsigned char* lds, const int lda, const int ldb, const Sched& S, const Epi& E) {
;     ...
;         for (int t = 0; t < nt; t += 2) {
;             const bool last = (t == nt - 2);
;             const char* a1 = cA + (size_t)(t + 1) * kstep;
;             const char* a2 = last ? nA : cA + (size_t)(t + 2) * kstep; const char* b2 = last ? nB : cB + (size_t)(t + 2) * kstep;
;             const char* a3 = a2 + kstep; const char* b3 = b2 + kstep;
;             PG8_LDB(B0, 0, 0); PG8_SCHED; PG8_LDA(At, 0, 0); PG8_STAGE(PG8_SA(1, 1), a1 + hA, voffA);
;             PG8_WAIT_L(8); PG8_BAR; PG8_WAIT_L(0); PG8_MMA(0, 0, At, B0); PG8_BAR; PG8_SCHED;
;             PG8_LDB(B1, 0, 1); PG8_STAGE(PG8_SB(0, 0), b2, voffB);
;             PG8_BAR; PG8_WAIT_L(0); PG8_MMA(0, 1, At, B1); PG8_BAR;
;             PG8_LDA(At, 0, 1); PG8_STAGE(PG8_SA(0, 0), a2, voffA);
;             PG8_BAR; PG8_WAIT_L(0); PG8_MMA(1, 0, At, B0); PG8_BAR; PG8_SCHED;
;             PG8_STAGE(PG8_SB(0, 1), b2 + hB, voffB);
;             PG8_WAIT_V(6); PG8_BAR; PG8_MMA(1, 1, At, B1); PG8_BAR;
.Lk6_noprio:
.Lk6_pbody:
	s_add_i32 s70, s54, 2
	s_add_u32 s8, s52, 0xfff80080
	s_addc_u32 s9, s53, -1
	s_add_i32 s10, 0, 0x10000
	v_add_u32_e32 v146, s10, v238
	ds_read_b128 v[106:109], v146
	ds_read_b128 v[118:121], v146 offset:1024
	ds_read_b128 v[134:137], v146 offset:2048
	ds_read_b128 v[146:149], v146 offset:3072
	s_cmp_eq_u32 s45, s54
	s_cselect_b32 s54, s50, s47
	s_cselect_b32 s57, s49, s9
	s_cselect_b32 s56, s48, s8
	s_cselect_b32 s55, s51, s69
	v_lshl_add_u64 v[186:187], s[52:53], 0, v[204:205]
	s_add_i32 m0, s24, 0xc000
	ds_read_b128 v[150:153], v240
	ds_read_b128 v[154:157], v240 offset:1024
	ds_read_b128 v[158:161], v240 offset:2048
	ds_read_b128 v[162:165], v240 offset:3072
	ds_read_b128 v[166:169], v240 offset:4096
	ds_read_b128 v[170:173], v240 offset:5120
	ds_read_b128 v[174:177], v240 offset:6144
	ds_read_b128 v[178:181], v240 offset:7168
	global_load_lds_dwordx4 v[186:187], off
	s_add_i32 m0, s24, 0xe000
	v_lshl_add_u64 v[186:187], s[52:53], 0, v[202:203]
	global_load_lds_dwordx4 v[186:187], off
	s_waitcnt lgkmcnt(8)
	s_barrier
	s_waitcnt lgkmcnt(0)
	s_waitcnt lgkmcnt(0)
	v_mfma_f32_16x16x32_bf16 v[142:145], v[106:109], v[150:153], v[142:145]
	v_mfma_f32_16x16x32_bf16 v[138:141], v[134:137], v[150:153], v[138:141]
	v_mfma_f32_16x16x32_bf16 v[122:125], v[106:109], v[158:161], v[122:125]
	v_mfma_f32_16x16x32_bf16 v[114:117], v[134:137], v[158:161], v[114:117]
	v_mfma_f32_16x16x32_bf16 v[98:101], v[106:109], v[166:169], v[98:101]
	v_mfma_f32_16x16x32_bf16 v[94:97], v[134:137], v[166:169], v[94:97]
	v_mfma_f32_16x16x32_bf16 v[82:85], v[106:109], v[174:177], v[82:85]
	v_mfma_f32_16x16x32_bf16 v[78:81], v[134:137], v[174:177], v[78:81]
	v_mfma_f32_16x16x32_bf16 v[142:145], v[118:121], v[154:157], v[142:145]
	v_mfma_f32_16x16x32_bf16 v[138:141], v[146:149], v[154:157], v[138:141]
	v_mfma_f32_16x16x32_bf16 v[122:125], v[118:121], v[162:165], v[122:125]
	v_mfma_f32_16x16x32_bf16 v[114:117], v[146:149], v[162:165], v[114:117]
	v_mfma_f32_16x16x32_bf16 v[98:101], v[118:121], v[170:173], v[98:101]
	v_mfma_f32_16x16x32_bf16 v[94:97], v[146:149], v[170:173], v[94:97]
	v_mfma_f32_16x16x32_bf16 v[82:85], v[118:121], v[178:181], v[82:85]
	v_mfma_f32_16x16x32_bf16 v[78:81], v[146:149], v[178:181], v[78:81]
	s_barrier
	s_add_i32 s11, 0, 0x14000
	s_add_i32 s8, s10, s23
	v_add_u32_e32 v214, s11, v238
	v_lshl_add_u64 v[218:219], s[54:55], 0, v[182:183]
	s_mov_b32 m0, s8
	ds_read_b128 v[186:189], v214
	ds_read_b128 v[206:209], v214 offset:1024
	ds_read_b128 v[210:213], v214 offset:2048
	ds_read_b128 v[214:217], v214 offset:3072
	global_load_lds_dwordx4 v[218:219], off
	s_add_i32 m0, s8, 0x2000
	v_lshl_add_u64 v[220:221], s[54:55], 0, v[198:199]
	global_load_lds_dwordx4 v[220:221], off
	s_barrier
	s_waitcnt lgkmcnt(0)
	s_waitcnt lgkmcnt(0)
	v_mfma_f32_16x16x32_bf16 v[130:133], v[186:189], v[150:153], v[130:133]
	v_mfma_f32_16x16x32_bf16 v[126:129], v[210:213], v[150:153], v[126:129]
	v_mfma_f32_16x16x32_bf16 v[110:113], v[186:189], v[158:161], v[110:113]
	v_mfma_f32_16x16x32_bf16 v[102:105], v[210:213], v[158:161], v[102:105]
	v_mfma_f32_16x16x32_bf16 v[90:93], v[186:189], v[166:169], v[90:93]
	v_mfma_f32_16x16x32_bf16 v[86:89], v[210:213], v[166:169], v[86:89]
	v_mfma_f32_16x16x32_bf16 v[74:77], v[186:189], v[174:177], v[74:77]
	v_mfma_f32_16x16x32_bf16 v[70:73], v[210:213], v[174:177], v[70:73]
	v_mfma_f32_16x16x32_bf16 v[130:133], v[206:209], v[154:157], v[130:133]
	v_mfma_f32_16x16x32_bf16 v[126:129], v[214:217], v[154:157], v[126:129]
	v_mfma_f32_16x16x32_bf16 v[110:113], v[206:209], v[162:165], v[110:113]
	v_mfma_f32_16x16x32_bf16 v[102:105], v[214:217], v[162:165], v[102:105]
	v_mfma_f32_16x16x32_bf16 v[90:93], v[206:209], v[170:173], v[90:93]
	v_mfma_f32_16x16x32_bf16 v[86:89], v[214:217], v[170:173], v[86:89]
	v_mfma_f32_16x16x32_bf16 v[74:77], v[206:209], v[178:181], v[74:77]
	v_mfma_f32_16x16x32_bf16 v[70:73], v[214:217], v[178:181], v[70:73]
	s_mov_b32 m0, s24
	v_lshl_add_u64 v[222:223], s[56:57], 0, v[12:13]
	s_barrier
	ds_read_b128 v[150:153], v240 offset:16384
	ds_read_b128 v[154:157], v240 offset:17408
	ds_read_b128 v[158:161], v240 offset:18432
	ds_read_b128 v[162:165], v240 offset:19456
	ds_read_b128 v[166:169], v240 offset:20480
	ds_read_b128 v[170:173], v240 offset:21504
	ds_read_b128 v[174:177], v240 offset:22528
	ds_read_b128 v[178:181], v240 offset:23552
	global_load_lds_dwordx4 v[222:223], off
	s_mov_b32 m0, s58
	v_lshl_add_u64 v[242:243], s[56:57], 0, v[196:197]
	global_load_lds_dwordx4 v[242:243], off
	s_barrier
	s_waitcnt lgkmcnt(0)
	s_waitcnt lgkmcnt(0)
	v_mfma_f32_16x16x32_bf16 v[66:69], v[106:109], v[150:153], v[66:69]
	v_mfma_f32_16x16x32_bf16 v[62:65], v[134:137], v[150:153], v[62:65]
	v_mfma_f32_16x16x32_bf16 v[50:53], v[106:109], v[158:161], v[50:53]
	v_mfma_f32_16x16x32_bf16 v[46:49], v[134:137], v[158:161], v[46:49]
	v_mfma_f32_16x16x32_bf16 v[34:37], v[106:109], v[166:169], v[34:37]
	v_mfma_f32_16x16x32_bf16 v[30:33], v[134:137], v[166:169], v[30:33]
	v_mfma_f32_16x16x32_bf16 v[18:21], v[106:109], v[174:177], v[18:21]
	v_mfma_f32_16x16x32_bf16 v[8:11], v[134:137], v[174:177], v[8:11]
	v_mfma_f32_16x16x32_bf16 v[66:69], v[118:121], v[154:157], v[66:69]
	v_mfma_f32_16x16x32_bf16 v[62:65], v[146:149], v[154:157], v[62:65]
	v_mfma_f32_16x16x32_bf16 v[50:53], v[118:121], v[162:165], v[50:53]
	v_mfma_f32_16x16x32_bf16 v[46:49], v[146:149], v[162:165], v[46:49]
	v_mfma_f32_16x16x32_bf16 v[34:37], v[118:121], v[170:173], v[34:37]
	v_mfma_f32_16x16x32_bf16 v[30:33], v[146:149], v[170:173], v[30:33]
	v_mfma_f32_16x16x32_bf16 v[18:21], v[118:121], v[178:181], v[18:21]
	v_mfma_f32_16x16x32_bf16 v[8:11], v[146:149], v[178:181], v[8:11]
	s_barrier
; #define PG8_STAGE(bufoff, gbase, voff) do { _Pragma("unroll") for (int _i = 0; _i < 2; ++_i) \
;         __builtin_amdgcn_global_load_lds((const unsigned*)((const char*)(gbase) + (voff)[_i]), (LAS unsigned*)(lds + (bufoff) + ldsw + _i * 8192), 16, 0, 0); } while (0)
; #define PG8_LDA(dst, b, h) do { _Pragma("unroll") for (int m = 0; m < 4; ++m) _Pragma("unroll") for (int k = 0; k < 2; ++k) dst[m][k] = *(const LAS bf16x8*)(lds + PG8_SA(b, h) + aoff + m * 2048 + k * 1024); } while (0)
; #define PG8_LDB(dst, b, h) do { _Pragma("unroll") for (int n = 0; n < 2; ++n) _Pragma("unroll") for (int k = 0; k < 2; ++k) dst[n][k] = *(const LAS bf16x8*)(lds + PG8_SB(b, h) + boff + n * 2048 + k * 1024); } while (0)
; #define PG8_WAIT_V(n) asm volatile("s_waitcnt vmcnt(" #n ")" ::: "memory")
; #define PG8_WAIT_L(n) asm volatile("s_waitcnt lgkmcnt(" #n ")" ::: "memory")
; #define PG8_BAR __builtin_amdgcn_s_barrier()
; #define PG8_SCHED __builtin_amdgcn_sched_barrier(0)
; template <class Epi, class Sched>
; __device__ __forceinline__ void gemm_phase(const int TID, LAS unsigned char* lds, const int lda, const int ldb, const Sched& S, const Epi& E) {
;     ...
;             PG8_LDB(B0, 0, 0); PG8_SCHED; PG8_LDA(At, 0, 0); PG8_STAGE(PG8_SA(1, 1), a1 + hA, voffA);
;             PG8_WAIT_L(8); PG8_BAR; PG8_WAIT_L(0); PG8_MMA(0, 0, At, B0); PG8_BAR; PG8_SCHED;
;             PG8_LDB(B1, 0, 1); PG8_STAGE(PG8_SB(0, 0), b2, voffB);
;             PG8_BAR; PG8_WAIT_L(0); PG8_MMA(0, 1, At, B1); PG8_BAR;
;             PG8_LDA(At, 0, 1); PG8_STAGE(PG8_SA(0, 0), a2, voffA);
;             PG8_BAR; PG8_WAIT_L(0); PG8_MMA(1, 0, At, B0); PG8_BAR; PG8_SCHED;
;             PG8_STAGE(PG8_SB(0, 1), b2 + hB, voffB);
;             PG8_WAIT_V(6); PG8_BAR; PG8_MMA(1, 1, At, B1); PG8_BAR;
;             PG8_LDB(B0, 1, 0); PG8_SCHED; PG8_LDA(At, 1, 0); PG8_STAGE(PG8_SA(0, 1), a2 + hA, voffA);
;             PG8_WAIT_L(8); PG8_BAR; PG8_WAIT_L(0); PG8_MMA(0, 0, At, B0); PG8_BAR; PG8_SCHED;
;             PG8_LDB(B1, 1, 1); PG8_STAGE(PG8_SB(1, 0), b3, voffB);
;             PG8_BAR; PG8_WAIT_L(0); PG8_MMA(0, 1, At, B1); PG8_BAR;
;             PG8_LDA(At, 1, 1); PG8_STAGE(PG8_SA(1, 0), a3, voffA);
;             PG8_BAR; PG8_WAIT_L(0); PG8_MMA(1, 0, At, B0); PG8_BAR; PG8_SCHED;
;             PG8_STAGE(PG8_SB(1, 1), b3 + hB, voffB);
;             PG8_WAIT_V(6); PG8_BAR; PG8_MMA(1, 1, At, B1); PG8_BAR;
	s_add_u32 s8, s54, 0x80000
	s_addc_u32 s9, s55, 0
	s_add_i32 s10, s11, s23
	s_mov_b32 m0, s10
	v_lshl_add_u64 v[106:107], s[8:9], 0, v[182:183]
	global_load_lds_dwordx4 v[106:107], off
	s_add_i32 m0, s10, 0x2000
	v_lshl_add_u64 v[106:107], s[8:9], 0, v[198:199]
	global_load_lds_dwordx4 v[106:107], off
	s_waitcnt vmcnt(6)
	s_barrier
	v_mfma_f32_16x16x32_bf16 v[58:61], v[186:189], v[150:153], v[58:61]
	v_mfma_f32_16x16x32_bf16 v[54:57], v[210:213], v[150:153], v[54:57]
	v_mfma_f32_16x16x32_bf16 v[42:45], v[186:189], v[158:161], v[42:45]
	v_mfma_f32_16x16x32_bf16 v[38:41], v[210:213], v[158:161], v[38:41]
	v_mfma_f32_16x16x32_bf16 v[26:29], v[186:189], v[166:169], v[26:29]
	v_mfma_f32_16x16x32_bf16 v[22:25], v[210:213], v[166:169], v[22:25]
	v_mfma_f32_16x16x32_bf16 v[4:7], v[186:189], v[174:177], v[4:7]
	v_mfma_f32_16x16x32_bf16 v[0:3], v[210:213], v[174:177], v[0:3]
	v_mfma_f32_16x16x32_bf16 v[58:61], v[206:209], v[154:157], v[58:61]
	v_mfma_f32_16x16x32_bf16 v[54:57], v[214:217], v[154:157], v[54:57]
	v_mfma_f32_16x16x32_bf16 v[42:45], v[206:209], v[162:165], v[42:45]
	v_mfma_f32_16x16x32_bf16 v[38:41], v[214:217], v[162:165], v[38:41]
	v_mfma_f32_16x16x32_bf16 v[26:29], v[206:209], v[170:173], v[26:29]
	v_mfma_f32_16x16x32_bf16 v[22:25], v[214:217], v[170:173], v[22:25]
	v_mfma_f32_16x16x32_bf16 v[4:7], v[206:209], v[178:181], v[4:7]
	v_mfma_f32_16x16x32_bf16 v[0:3], v[214:217], v[178:181], v[0:3]
	s_add_i32 s10, 0, 0x18000
	v_add_u32_e32 v146, s10, v238
	s_barrier
	ds_read_b128 v[106:109], v146
	ds_read_b128 v[118:121], v146 offset:1024
	ds_read_b128 v[134:137], v146 offset:2048
	ds_read_b128 v[146:149], v146 offset:3072
	s_add_u32 s8, s56, 0x80000
	s_addc_u32 s9, s57, 0
	s_mov_b32 m0, s59
	v_lshl_add_u64 v[186:187], s[8:9], 0, v[12:13]
	ds_read_b128 v[150:153], v240 offset:32768
	ds_read_b128 v[154:157], v240 offset:33792
	ds_read_b128 v[158:161], v240 offset:34816
	ds_read_b128 v[162:165], v240 offset:35840
	ds_read_b128 v[166:169], v240 offset:36864
	ds_read_b128 v[170:173], v240 offset:37888
	ds_read_b128 v[174:177], v240 offset:38912
	ds_read_b128 v[178:181], v240 offset:39936
	global_load_lds_dwordx4 v[186:187], off
	s_mov_b32 m0, s60
	v_lshl_add_u64 v[186:187], s[8:9], 0, v[196:197]
	global_load_lds_dwordx4 v[186:187], off
	s_waitcnt lgkmcnt(8)
	s_barrier
	s_waitcnt lgkmcnt(0)
	s_waitcnt lgkmcnt(0)
	v_mfma_f32_16x16x32_bf16 v[142:145], v[106:109], v[150:153], v[142:145]
	v_mfma_f32_16x16x32_bf16 v[138:141], v[134:137], v[150:153], v[138:141]
	v_mfma_f32_16x16x32_bf16 v[122:125], v[106:109], v[158:161], v[122:125]
	v_mfma_f32_16x16x32_bf16 v[114:117], v[134:137], v[158:161], v[114:117]
	v_mfma_f32_16x16x32_bf16 v[98:101], v[106:109], v[166:169], v[98:101]
	v_mfma_f32_16x16x32_bf16 v[94:97], v[134:137], v[166:169], v[94:97]
	v_mfma_f32_16x16x32_bf16 v[82:85], v[106:109], v[174:177], v[82:85]
	v_mfma_f32_16x16x32_bf16 v[78:81], v[134:137], v[174:177], v[78:81]
	v_mfma_f32_16x16x32_bf16 v[142:145], v[118:121], v[154:157], v[142:145]
	v_mfma_f32_16x16x32_bf16 v[138:141], v[146:149], v[154:157], v[138:141]
	v_mfma_f32_16x16x32_bf16 v[122:125], v[118:121], v[162:165], v[122:125]
	v_mfma_f32_16x16x32_bf16 v[114:117], v[146:149], v[162:165], v[114:117]
	v_mfma_f32_16x16x32_bf16 v[98:101], v[118:121], v[170:173], v[98:101]
	v_mfma_f32_16x16x32_bf16 v[94:97], v[146:149], v[170:173], v[94:97]
	v_mfma_f32_16x16x32_bf16 v[82:85], v[118:121], v[178:181], v[82:85]
	v_mfma_f32_16x16x32_bf16 v[78:81], v[146:149], v[178:181], v[78:81]
	s_barrier
	s_add_i32 s11, 0, 0x1c000
	s_add_i32 s8, s10, s23
	v_add_u32_e32 v214, s11, v238
	v_lshl_add_u64 v[218:219], v[218:219], 0, s[36:37]
	s_mov_b32 m0, s8
	ds_read_b128 v[186:189], v214
	ds_read_b128 v[206:209], v214 offset:1024
	ds_read_b128 v[210:213], v214 offset:2048
	ds_read_b128 v[214:217], v214 offset:3072
	global_load_lds_dwordx4 v[218:219], off
	s_add_i32 m0, s8, 0x2000
	v_lshl_add_u64 v[218:219], v[220:221], 0, s[36:37]
	global_load_lds_dwordx4 v[218:219], off
	s_barrier
	s_waitcnt lgkmcnt(0)
	s_waitcnt lgkmcnt(0)
	v_mfma_f32_16x16x32_bf16 v[130:133], v[186:189], v[150:153], v[130:133]
	v_mfma_f32_16x16x32_bf16 v[126:129], v[210:213], v[150:153], v[126:129]
	v_mfma_f32_16x16x32_bf16 v[110:113], v[186:189], v[158:161], v[110:113]
	v_mfma_f32_16x16x32_bf16 v[102:105], v[210:213], v[158:161], v[102:105]
	v_mfma_f32_16x16x32_bf16 v[90:93], v[186:189], v[166:169], v[90:93]
	v_mfma_f32_16x16x32_bf16 v[86:89], v[210:213], v[166:169], v[86:89]
	v_mfma_f32_16x16x32_bf16 v[74:77], v[186:189], v[174:177], v[74:77]
	v_mfma_f32_16x16x32_bf16 v[70:73], v[210:213], v[174:177], v[70:73]
	v_mfma_f32_16x16x32_bf16 v[130:133], v[206:209], v[154:157], v[130:133]
	v_mfma_f32_16x16x32_bf16 v[126:129], v[214:217], v[154:157], v[126:129]
	v_mfma_f32_16x16x32_bf16 v[110:113], v[206:209], v[162:165], v[110:113]
	v_mfma_f32_16x16x32_bf16 v[102:105], v[214:217], v[162:165], v[102:105]
	v_mfma_f32_16x16x32_bf16 v[90:93], v[206:209], v[170:173], v[90:93]
	v_mfma_f32_16x16x32_bf16 v[86:89], v[214:217], v[170:173], v[86:89]
	v_mfma_f32_16x16x32_bf16 v[74:77], v[206:209], v[178:181], v[74:77]
	v_mfma_f32_16x16x32_bf16 v[70:73], v[214:217], v[178:181], v[70:73]
	s_mov_b32 m0, s61
	v_lshl_add_u64 v[218:219], v[222:223], 0, s[36:37]
	s_barrier
	ds_read_b128 v[150:153], v240 offset:49152
	ds_read_b128 v[154:157], v240 offset:50176
	ds_read_b128 v[158:161], v240 offset:51200
	ds_read_b128 v[162:165], v240 offset:52224
	ds_read_b128 v[166:169], v240 offset:53248
	ds_read_b128 v[170:173], v240 offset:54272
	ds_read_b128 v[174:177], v240 offset:55296
	ds_read_b128 v[178:181], v240 offset:56320
	global_load_lds_dwordx4 v[218:219], off
	s_mov_b32 m0, s62
	v_lshl_add_u64 v[218:219], v[242:243], 0, s[36:37]
	global_load_lds_dwordx4 v[218:219], off
	s_barrier
; #define PG8_STAGE(bufoff, gbase, voff) do { _Pragma("unroll") for (int _i = 0; _i < 2; ++_i) \
;         __builtin_amdgcn_global_load_lds((const unsigned*)((const char*)(gbase) + (voff)[_i]), (LAS unsigned*)(lds + (bufoff) + ldsw + _i * 8192), 16, 0, 0); } while (0)
; #define PG8_LDA(dst, b, h) do { _Pragma("unroll") for (int m = 0; m < 4; ++m) _Pragma("unroll") for (int k = 0; k < 2; ++k) dst[m][k] = *(const LAS bf16x8*)(lds + PG8_SA(b, h) + aoff + m * 2048 + k * 1024); } while (0)
; #define PG8_LDB(dst, b, h) do { _Pragma("unroll") for (int n = 0; n < 2; ++n) _Pragma("unroll") for (int k = 0; k < 2; ++k) dst[n][k] = *(const LAS bf16x8*)(lds + PG8_SB(b, h) + boff + n * 2048 + k * 1024); } while (0)
; #define PG8_MMA(ai, bj, At, Bt) do { __builtin_amdgcn_s_setprio(1); _Pragma("unroll") for (int m = 0; m < 4; ++m) _Pragma("unroll") for (int n = 0; n < 2; ++n) _Pragma("unroll") for (int k = 0; k < 2; ++k) \
;         acc[ai][bj][m][n] = __builtin_amdgcn_mfma_f32_16x16x32_bf16(Bt[n][k], At[m][k], acc[ai][bj][m][n], 0, 0, 0); __builtin_amdgcn_s_setprio(0); } while (0)
; #define PG8_WAIT_V(n) asm volatile("s_waitcnt vmcnt(" #n ")" ::: "memory")
; #define PG8_WAIT_L(n) asm volatile("s_waitcnt lgkmcnt(" #n ")" ::: "memory")
; #define PG8_BAR __builtin_amdgcn_s_barrier()
; #define PG8_SCHED __builtin_amdgcn_sched_barrier(0)
; template <class Epi, class Sched>
; __device__ __forceinline__ void gemm_phase(const int TID, LAS unsigned char* lds, const int lda, const int ldb, const Sched& S, const Epi& E) {
;     ...
;             PG8_WAIT_V(6); PG8_BAR; PG8_MMA(1, 1, At, B1); PG8_BAR;
;             PG8_LDB(B0, 1, 0); PG8_SCHED; PG8_LDA(At, 1, 0); PG8_STAGE(PG8_SA(0, 1), a2 + hA, voffA);
;             PG8_WAIT_L(8); PG8_BAR; PG8_WAIT_L(0); PG8_MMA(0, 0, At, B0); PG8_BAR; PG8_SCHED;
;             PG8_LDB(B1, 1, 1); PG8_STAGE(PG8_SB(1, 0), b3, voffB);
;             PG8_BAR; PG8_WAIT_L(0); PG8_MMA(0, 1, At, B1); PG8_BAR;
;             PG8_LDA(At, 1, 1); PG8_STAGE(PG8_SA(1, 0), a3, voffA);
;             PG8_BAR; PG8_WAIT_L(0); PG8_MMA(1, 0, At, B0); PG8_BAR; PG8_SCHED;
;             PG8_STAGE(PG8_SB(1, 1), b3 + hB, voffB);
;             PG8_WAIT_V(6); PG8_BAR; PG8_MMA(1, 1, At, B1); PG8_BAR;
	s_waitcnt lgkmcnt(0)
	s_waitcnt lgkmcnt(0)
	v_mfma_f32_16x16x32_bf16 v[66:69], v[106:109], v[150:153], v[66:69]
	v_mfma_f32_16x16x32_bf16 v[62:65], v[134:137], v[150:153], v[62:65]
	v_mfma_f32_16x16x32_bf16 v[50:53], v[106:109], v[158:161], v[50:53]
	v_mfma_f32_16x16x32_bf16 v[46:49], v[134:137], v[158:161], v[46:49]
	v_mfma_f32_16x16x32_bf16 v[34:37], v[106:109], v[166:169], v[34:37]
	v_mfma_f32_16x16x32_bf16 v[30:33], v[134:137], v[166:169], v[30:33]
	v_mfma_f32_16x16x32_bf16 v[18:21], v[106:109], v[174:177], v[18:21]
	v_mfma_f32_16x16x32_bf16 v[8:11], v[134:137], v[174:177], v[8:11]
	v_mfma_f32_16x16x32_bf16 v[66:69], v[118:121], v[154:157], v[66:69]
	v_mfma_f32_16x16x32_bf16 v[62:65], v[146:149], v[154:157], v[62:65]
	v_mfma_f32_16x16x32_bf16 v[50:53], v[118:121], v[162:165], v[50:53]
	v_mfma_f32_16x16x32_bf16 v[46:49], v[146:149], v[162:165], v[46:49]
	v_mfma_f32_16x16x32_bf16 v[34:37], v[118:121], v[170:173], v[34:37]
	v_mfma_f32_16x16x32_bf16 v[30:33], v[146:149], v[170:173], v[30:33]
	v_mfma_f32_16x16x32_bf16 v[18:21], v[118:121], v[178:181], v[18:21]
	v_mfma_f32_16x16x32_bf16 v[8:11], v[146:149], v[178:181], v[8:11]
	s_barrier
	s_add_u32 s8, s54, 0x80080
	s_addc_u32 s9, s55, 0
	s_add_i32 s10, s11, s23
	s_mov_b32 m0, s10
	v_lshl_add_u64 v[106:107], s[8:9], 0, v[182:183]
	global_load_lds_dwordx4 v[106:107], off
	s_add_i32 m0, s10, 0x2000
	v_lshl_add_u64 v[106:107], s[8:9], 0, v[198:199]
	global_load_lds_dwordx4 v[106:107], off
	s_waitcnt vmcnt(6)
	s_barrier
	v_mfma_f32_16x16x32_bf16 v[58:61], v[186:189], v[150:153], v[58:61]
	v_mfma_f32_16x16x32_bf16 v[54:57], v[210:213], v[150:153], v[54:57]
	v_mfma_f32_16x16x32_bf16 v[42:45], v[186:189], v[158:161], v[42:45]
	v_mfma_f32_16x16x32_bf16 v[38:41], v[210:213], v[158:161], v[38:41]
	v_mfma_f32_16x16x32_bf16 v[26:29], v[186:189], v[166:169], v[26:29]
	v_mfma_f32_16x16x32_bf16 v[22:25], v[210:213], v[166:169], v[22:25]
	v_mfma_f32_16x16x32_bf16 v[4:7], v[186:189], v[174:177], v[4:7]
	v_mfma_f32_16x16x32_bf16 v[0:3], v[210:213], v[174:177], v[0:3]
	v_mfma_f32_16x16x32_bf16 v[58:61], v[206:209], v[154:157], v[58:61]
	v_mfma_f32_16x16x32_bf16 v[54:57], v[214:217], v[154:157], v[54:57]
	v_mfma_f32_16x16x32_bf16 v[42:45], v[206:209], v[162:165], v[42:45]
	v_mfma_f32_16x16x32_bf16 v[38:41], v[214:217], v[162:165], v[38:41]
	v_mfma_f32_16x16x32_bf16 v[26:29], v[206:209], v[170:173], v[26:29]
	v_mfma_f32_16x16x32_bf16 v[22:25], v[214:217], v[170:173], v[22:25]
	v_mfma_f32_16x16x32_bf16 v[4:7], v[206:209], v[178:181], v[4:7]
	v_mfma_f32_16x16x32_bf16 v[0:3], v[214:217], v[178:181], v[0:3]
	s_add_u32 s47, s47, 0x100
	s_addc_u32 s69, s69, 0
	s_add_u32 s52, s52, 0x100
	s_addc_u32 s53, s53, 0
	s_cmp_ge_i32 s70, s68
	s_mov_b32 s54, s70
	s_barrier
	s_cbranch_scc0 .Lk6_pbody
	s_setprio 0
	s_cmp_eq_u32 s41, 2
	s_cbranch_scc1 .Lk6_final
	v_lshl_add_u32 v206, s40, 8, v237
	s_lshl_b32 s8, s41, 11
	s_lshl_b32 s9, s67, 8
	s_add_i32 s8, s8, s9
	s_addk_i32 s8, 0x2400
	s_add_u32 s10, s42, s8
	s_addc_u32 s11, s43, 0
	v_mad_u32_u24 v206, v206, s4, v200
	s_mov_b32 s9, 0x2f800000
	global_load_dwordx4 v[150:153], v206, s[10:11]
	global_load_dwordx4 v[106:109], v206, s[10:11] offset:2048
	s_add_u32 s10, s10, 0x56000
	s_addc_u32 s11, s11, 0
	global_load_dwordx4 v[154:157], v206, s[10:11]
	global_load_dwordx4 v[118:121], v206, s[10:11] offset:2048
	s_add_u32 s10, s10, 0x56000
	s_addc_u32 s11, s11, 0
	global_load_dwordx4 v[158:161], v206, s[10:11]
	global_load_dwordx4 v[134:137], v206, s[10:11] offset:2048
	s_add_u32 s10, s10, 0x56000
	s_addc_u32 s11, s11, 0
	global_load_dwordx4 v[162:165], v206, s[10:11]
	global_load_dwordx4 v[146:149], v206, s[10:11] offset:2048
	s_add_u32 s10, s10, 0x1ae000
	s_addc_u32 s11, s11, 0
	global_load_dwordx4 v[166:169], v206, s[10:11]
	global_load_dwordx4 v[186:189], v206, s[10:11] offset:2048
	s_add_u32 s10, s10, 0x56000
	s_addc_u32 s11, s11, 0
	global_load_dwordx4 v[170:173], v206, s[10:11]
	global_load_dwordx4 v[208:211], v206, s[10:11] offset:2048
	s_add_u32 s10, s10, 0x56000
	s_addc_u32 s11, s11, 0
	global_load_dwordx4 v[174:177], v206, s[10:11]
	global_load_dwordx4 v[212:215], v206, s[10:11] offset:2048
	s_add_u32 s10, s10, 0x56000
	s_addc_u32 s11, s11, 0
	global_load_dwordx4 v[178:181], v206, s[10:11]
	global_load_dwordx4 v[216:219], v206, s[10:11] offset:2048
	s_waitcnt vmcnt(14)
; __device__ __forceinline__ float ub(unsigned w, int k) { return (float)((w >> (8 * k)) & 255u) * (1.0f / 255.0f); }
	v_cvt_f32_ubyte0_e32 v206, v106
	v_cvt_f32_ubyte1_e32 v207, v106
	v_cvt_f32_ubyte2_e32 v220, v106
	v_cvt_f32_ubyte3_e32 v221, v106
	v_cvt_f32_ubyte0_e32 v222, v150
	v_cvt_f32_ubyte1_e32 v223, v150
	v_cvt_f32_ubyte2_e32 v242, v150
	v_cvt_f32_ubyte3_e32 v243, v150
	v_max_f32_e32 v206, s9, v206
	v_max_f32_e32 v207, s9, v207
	v_max_f32_e32 v220, s9, v220
	v_max_f32_e32 v221, s9, v221
	v_max_f32_e32 v222, s9, v222
	v_max_f32_e32 v223, s9, v223
	v_max_f32_e32 v242, s9, v242
	v_max_f32_e32 v243, s9, v243
	v_rcp_f32_e32 v206, v206
	v_rcp_f32_e32 v207, v207
	v_rcp_f32_e32 v220, v220
	v_rcp_f32_e32 v221, v221
	v_mul_f32_e32 v222, v206, v222
	v_mul_f32_e32 v223, v207, v223
	v_mul_f32_e32 v242, v220, v242
	v_mul_f32_e32 v243, v221, v243
	v_mul_f32_e32 v142, v222, v142
	v_mul_f32_e32 v143, v223, v143
	v_mul_f32_e32 v144, v242, v144
	v_mul_f32_e32 v145, v243, v145
	v_cvt_f32_ubyte0_e32 v206, v107
	v_cvt_f32_ubyte1_e32 v207, v107
	v_cvt_f32_ubyte2_e32 v220, v107
	v_cvt_f32_ubyte3_e32 v221, v107
	v_cvt_f32_ubyte0_e32 v222, v151
	v_cvt_f32_ubyte1_e32 v223, v151
	v_cvt_f32_ubyte2_e32 v242, v151
	v_cvt_f32_ubyte3_e32 v243, v151
	v_max_f32_e32 v206, s9, v206
	v_max_f32_e32 v207, s9, v207
	v_max_f32_e32 v220, s9, v220
	v_max_f32_e32 v221, s9, v221
	v_max_f32_e32 v222, s9, v222
	v_max_f32_e32 v223, s9, v223
	v_max_f32_e32 v242, s9, v242
	v_max_f32_e32 v243, s9, v243
	v_rcp_f32_e32 v206, v206
	v_rcp_f32_e32 v207, v207
	v_rcp_f32_e32 v220, v220
	v_rcp_f32_e32 v221, v221
	v_mul_f32_e32 v222, v206, v222
	v_mul_f32_e32 v223, v207, v223
	v_mul_f32_e32 v242, v220, v242
	v_mul_f32_e32 v243, v221, v243
	v_mul_f32_e32 v138, v222, v138
	v_mul_f32_e32 v139, v223, v139
	v_mul_f32_e32 v140, v242, v140
	v_mul_f32_e32 v141, v243, v141
	v_cvt_f32_ubyte0_e32 v206, v108
	v_cvt_f32_ubyte1_e32 v207, v108
	v_cvt_f32_ubyte2_e32 v220, v108
	v_cvt_f32_ubyte3_e32 v221, v108
	v_cvt_f32_ubyte0_e32 v222, v152
	v_cvt_f32_ubyte1_e32 v223, v152
	v_cvt_f32_ubyte2_e32 v242, v152
	v_cvt_f32_ubyte3_e32 v243, v152
	v_max_f32_e32 v206, s9, v206
	v_max_f32_e32 v207, s9, v207
	v_max_f32_e32 v220, s9, v220
	v_max_f32_e32 v221, s9, v221
	v_max_f32_e32 v222, s9, v222
	v_max_f32_e32 v223, s9, v223
	v_max_f32_e32 v242, s9, v242
	v_max_f32_e32 v243, s9, v243
	v_rcp_f32_e32 v206, v206
	v_rcp_f32_e32 v207, v207
	v_rcp_f32_e32 v220, v220
	v_rcp_f32_e32 v221, v221
	v_mul_f32_e32 v222, v206, v222
	v_mul_f32_e32 v223, v207, v223
	v_mul_f32_e32 v242, v220, v242
	v_mul_f32_e32 v243, v221, v243
	v_mul_f32_e32 v130, v222, v130
	v_mul_f32_e32 v131, v223, v131
	v_mul_f32_e32 v132, v242, v132
	v_mul_f32_e32 v133, v243, v133
	v_cvt_f32_ubyte0_e32 v206, v109
	v_cvt_f32_ubyte1_e32 v207, v109
	v_cvt_f32_ubyte2_e32 v220, v109
	v_cvt_f32_ubyte3_e32 v221, v109
	v_cvt_f32_ubyte0_e32 v222, v153
	v_cvt_f32_ubyte1_e32 v223, v153
	v_cvt_f32_ubyte2_e32 v242, v153
	v_cvt_f32_ubyte3_e32 v243, v153
	v_max_f32_e32 v206, s9, v206
	v_max_f32_e32 v207, s9, v207
	v_max_f32_e32 v220, s9, v220
	v_max_f32_e32 v221, s9, v221
	v_max_f32_e32 v222, s9, v222
	v_max_f32_e32 v223, s9, v223
	v_max_f32_e32 v242, s9, v242
	v_max_f32_e32 v243, s9, v243
	v_rcp_f32_e32 v206, v206
	v_rcp_f32_e32 v207, v207
	v_rcp_f32_e32 v220, v220
	v_rcp_f32_e32 v221, v221
	v_mul_f32_e32 v222, v206, v222
	v_mul_f32_e32 v223, v207, v223
	v_mul_f32_e32 v242, v220, v242
	v_mul_f32_e32 v243, v221, v243
	v_mul_f32_e32 v126, v222, v126
	v_mul_f32_e32 v127, v223, v127
	v_mul_f32_e32 v128, v242, v128
	v_mul_f32_e32 v129, v243, v129
	s_waitcnt vmcnt(12)
	v_cvt_f32_ubyte0_e32 v206, v118
	v_cvt_f32_ubyte1_e32 v207, v118
	v_cvt_f32_ubyte2_e32 v220, v118
	v_cvt_f32_ubyte3_e32 v221, v118
	v_cvt_f32_ubyte0_e32 v222, v154
	v_cvt_f32_ubyte1_e32 v223, v154
	v_cvt_f32_ubyte2_e32 v242, v154
	v_cvt_f32_ubyte3_e32 v243, v154
	v_max_f32_e32 v206, s9, v206
	v_max_f32_e32 v207, s9, v207
	v_max_f32_e32 v220, s9, v220
	v_max_f32_e32 v221, s9, v221
	v_max_f32_e32 v222, s9, v222
	v_max_f32_e32 v223, s9, v223
	v_max_f32_e32 v242, s9, v242
	v_max_f32_e32 v243, s9, v243
	v_rcp_f32_e32 v206, v206
	v_rcp_f32_e32 v207, v207
	v_rcp_f32_e32 v220, v220
	v_rcp_f32_e32 v221, v221
	v_mul_f32_e32 v222, v206, v222
	v_mul_f32_e32 v223, v207, v223
	v_mul_f32_e32 v242, v220, v242
	v_mul_f32_e32 v243, v221, v243
	v_mul_f32_e32 v122, v222, v122
	v_mul_f32_e32 v123, v223, v123
	v_mul_f32_e32 v124, v242, v124
	v_mul_f32_e32 v125, v243, v125
	v_cvt_f32_ubyte0_e32 v206, v119
	v_cvt_f32_ubyte1_e32 v207, v119
	v_cvt_f32_ubyte2_e32 v220, v119
	v_cvt_f32_ubyte3_e32 v221, v119
	v_cvt_f32_ubyte0_e32 v222, v155
	v_cvt_f32_ubyte1_e32 v223, v155
	v_cvt_f32_ubyte2_e32 v242, v155
	v_cvt_f32_ubyte3_e32 v243, v155
	v_max_f32_e32 v206, s9, v206
	v_max_f32_e32 v207, s9, v207
	v_max_f32_e32 v220, s9, v220
	v_max_f32_e32 v221, s9, v221
	v_max_f32_e32 v222, s9, v222
	v_max_f32_e32 v223, s9, v223
	v_max_f32_e32 v242, s9, v242
	v_max_f32_e32 v243, s9, v243
	v_rcp_f32_e32 v206, v206
	v_rcp_f32_e32 v207, v207
	v_rcp_f32_e32 v220, v220
	v_rcp_f32_e32 v221, v221
	v_mul_f32_e32 v222, v206, v222
	v_mul_f32_e32 v223, v207, v223
	v_mul_f32_e32 v242, v220, v242
	v_mul_f32_e32 v243, v221, v243
	v_mul_f32_e32 v114, v222, v114
	v_mul_f32_e32 v115, v223, v115
	v_mul_f32_e32 v116, v242, v116
	v_mul_f32_e32 v117, v243, v117
	v_cvt_f32_ubyte0_e32 v206, v120
	v_cvt_f32_ubyte1_e32 v207, v120
	v_cvt_f32_ubyte2_e32 v220, v120
	v_cvt_f32_ubyte3_e32 v221, v120
	v_cvt_f32_ubyte0_e32 v222, v156
	v_cvt_f32_ubyte1_e32 v223, v156
	v_cvt_f32_ubyte2_e32 v242, v156
	v_cvt_f32_ubyte3_e32 v243, v156
	v_max_f32_e32 v206, s9, v206
	v_max_f32_e32 v207, s9, v207
	v_max_f32_e32 v220, s9, v220
	v_max_f32_e32 v221, s9, v221
	v_max_f32_e32 v222, s9, v222
	v_max_f32_e32 v223, s9, v223
	v_max_f32_e32 v242, s9, v242
	v_max_f32_e32 v243, s9, v243
	v_rcp_f32_e32 v206, v206
	v_rcp_f32_e32 v207, v207
	v_rcp_f32_e32 v220, v220
	v_rcp_f32_e32 v221, v221
	v_mul_f32_e32 v222, v206, v222
	v_mul_f32_e32 v223, v207, v223
	v_mul_f32_e32 v242, v220, v242
	v_mul_f32_e32 v243, v221, v243
	v_mul_f32_e32 v110, v222, v110
	v_mul_f32_e32 v111, v223, v111
	v_mul_f32_e32 v112, v242, v112
	v_mul_f32_e32 v113, v243, v113
	v_cvt_f32_ubyte0_e32 v206, v121
	v_cvt_f32_ubyte1_e32 v207, v121
	v_cvt_f32_ubyte2_e32 v220, v121
	v_cvt_f32_ubyte3_e32 v221, v121
	v_cvt_f32_ubyte0_e32 v222, v157
	v_cvt_f32_ubyte1_e32 v223, v157
	v_cvt_f32_ubyte2_e32 v242, v157
	v_cvt_f32_ubyte3_e32 v243, v157
	v_max_f32_e32 v206, s9, v206
	v_max_f32_e32 v207, s9, v207
	v_max_f32_e32 v220, s9, v220
	v_max_f32_e32 v221, s9, v221
	v_max_f32_e32 v222, s9, v222
	v_max_f32_e32 v223, s9, v223
	v_max_f32_e32 v242, s9, v242
	v_max_f32_e32 v243, s9, v243
	v_rcp_f32_e32 v206, v206
	v_rcp_f32_e32 v207, v207
	v_rcp_f32_e32 v220, v220
	v_rcp_f32_e32 v221, v221
	v_mul_f32_e32 v222, v206, v222
	v_mul_f32_e32 v223, v207, v223
	v_mul_f32_e32 v242, v220, v242
	v_mul_f32_e32 v243, v221, v243
	v_mul_f32_e32 v102, v222, v102
	v_mul_f32_e32 v103, v223, v103
	v_mul_f32_e32 v104, v242, v104
	v_mul_f32_e32 v105, v243, v105
	s_waitcnt vmcnt(10)
; __device__ __forceinline__ float ub(unsigned w, int k) { return (float)((w >> (8 * k)) & 255u) * (1.0f / 255.0f); }
	v_cvt_f32_ubyte0_e32 v206, v134
	v_cvt_f32_ubyte1_e32 v207, v134
	v_cvt_f32_ubyte2_e32 v220, v134
	v_cvt_f32_ubyte3_e32 v221, v134
	v_cvt_f32_ubyte0_e32 v222, v158
	v_cvt_f32_ubyte1_e32 v223, v158
	v_cvt_f32_ubyte2_e32 v242, v158
	v_cvt_f32_ubyte3_e32 v243, v158
	v_max_f32_e32 v206, s9, v206
	v_max_f32_e32 v207, s9, v207
	v_max_f32_e32 v220, s9, v220
	v_max_f32_e32 v221, s9, v221
	v_max_f32_e32 v222, s9, v222
	v_max_f32_e32 v223, s9, v223
	v_max_f32_e32 v242, s9, v242
	v_max_f32_e32 v243, s9, v243
	v_rcp_f32_e32 v206, v206
	v_rcp_f32_e32 v207, v207
	v_rcp_f32_e32 v220, v220
	v_rcp_f32_e32 v221, v221
	v_mul_f32_e32 v222, v206, v222
	v_mul_f32_e32 v223, v207, v223
	v_mul_f32_e32 v242, v220, v242
	v_mul_f32_e32 v243, v221, v243
	v_mul_f32_e32 v98, v222, v98
	v_mul_f32_e32 v99, v223, v99
	v_mul_f32_e32 v100, v242, v100
	v_mul_f32_e32 v101, v243, v101
	v_cvt_f32_ubyte0_e32 v206, v135
	v_cvt_f32_ubyte1_e32 v207, v135
	v_cvt_f32_ubyte2_e32 v220, v135
	v_cvt_f32_ubyte3_e32 v221, v135
	v_cvt_f32_ubyte0_e32 v222, v159
	v_cvt_f32_ubyte1_e32 v223, v159
	v_cvt_f32_ubyte2_e32 v242, v159
	v_cvt_f32_ubyte3_e32 v243, v159
	v_max_f32_e32 v206, s9, v206
	v_max_f32_e32 v207, s9, v207
	v_max_f32_e32 v220, s9, v220
	v_max_f32_e32 v221, s9, v221
	v_max_f32_e32 v222, s9, v222
	v_max_f32_e32 v223, s9, v223
	v_max_f32_e32 v242, s9, v242
	v_max_f32_e32 v243, s9, v243
	v_rcp_f32_e32 v206, v206
	v_rcp_f32_e32 v207, v207
	v_rcp_f32_e32 v220, v220
	v_rcp_f32_e32 v221, v221
	v_mul_f32_e32 v222, v206, v222
	v_mul_f32_e32 v223, v207, v223
	v_mul_f32_e32 v242, v220, v242
	v_mul_f32_e32 v243, v221, v243
	v_mul_f32_e32 v94, v222, v94
	v_mul_f32_e32 v95, v223, v95
	v_mul_f32_e32 v96, v242, v96
	v_mul_f32_e32 v97, v243, v97
	v_cvt_f32_ubyte0_e32 v206, v136
	v_cvt_f32_ubyte1_e32 v207, v136
	v_cvt_f32_ubyte2_e32 v220, v136
	v_cvt_f32_ubyte3_e32 v221, v136
	v_cvt_f32_ubyte0_e32 v222, v160
	v_cvt_f32_ubyte1_e32 v223, v160
	v_cvt_f32_ubyte2_e32 v242, v160
	v_cvt_f32_ubyte3_e32 v243, v160
	v_max_f32_e32 v206, s9, v206
	v_max_f32_e32 v207, s9, v207
	v_max_f32_e32 v220, s9, v220
	v_max_f32_e32 v221, s9, v221
	v_max_f32_e32 v222, s9, v222
	v_max_f32_e32 v223, s9, v223
	v_max_f32_e32 v242, s9, v242
	v_max_f32_e32 v243, s9, v243
	v_rcp_f32_e32 v206, v206
	v_rcp_f32_e32 v207, v207
	v_rcp_f32_e32 v220, v220
	v_rcp_f32_e32 v221, v221
	v_mul_f32_e32 v222, v206, v222
	v_mul_f32_e32 v223, v207, v223
	v_mul_f32_e32 v242, v220, v242
	v_mul_f32_e32 v243, v221, v243
	v_mul_f32_e32 v90, v222, v90
	v_mul_f32_e32 v91, v223, v91
	v_mul_f32_e32 v92, v242, v92
	v_mul_f32_e32 v93, v243, v93
	v_cvt_f32_ubyte0_e32 v206, v137
	v_cvt_f32_ubyte1_e32 v207, v137
	v_cvt_f32_ubyte2_e32 v220, v137
	v_cvt_f32_ubyte3_e32 v221, v137
	v_cvt_f32_ubyte0_e32 v222, v161
	v_cvt_f32_ubyte1_e32 v223, v161
	v_cvt_f32_ubyte2_e32 v242, v161
	v_cvt_f32_ubyte3_e32 v243, v161
	v_max_f32_e32 v206, s9, v206
	v_max_f32_e32 v207, s9, v207
	v_max_f32_e32 v220, s9, v220
	v_max_f32_e32 v221, s9, v221
	v_max_f32_e32 v222, s9, v222
	v_max_f32_e32 v223, s9, v223
	v_max_f32_e32 v242, s9, v242
	v_max_f32_e32 v243, s9, v243
	v_rcp_f32_e32 v206, v206
	v_rcp_f32_e32 v207, v207
	v_rcp_f32_e32 v220, v220
	v_rcp_f32_e32 v221, v221
	v_mul_f32_e32 v222, v206, v222
	v_mul_f32_e32 v223, v207, v223
	v_mul_f32_e32 v242, v220, v242
	v_mul_f32_e32 v243, v221, v243
	v_mul_f32_e32 v86, v222, v86
	v_mul_f32_e32 v87, v223, v87
	v_mul_f32_e32 v88, v242, v88
	v_mul_f32_e32 v89, v243, v89
	s_waitcnt vmcnt(8)
	v_cvt_f32_ubyte0_e32 v206, v146
	v_cvt_f32_ubyte1_e32 v207, v146
	v_cvt_f32_ubyte2_e32 v220, v146
	v_cvt_f32_ubyte3_e32 v221, v146
	v_cvt_f32_ubyte0_e32 v222, v162
	v_cvt_f32_ubyte1_e32 v223, v162
	v_cvt_f32_ubyte2_e32 v242, v162
	v_cvt_f32_ubyte3_e32 v243, v162
	v_max_f32_e32 v206, s9, v206
	v_max_f32_e32 v207, s9, v207
	v_max_f32_e32 v220, s9, v220
	v_max_f32_e32 v221, s9, v221
	v_max_f32_e32 v222, s9, v222
	v_max_f32_e32 v223, s9, v223
	v_max_f32_e32 v242, s9, v242
	v_max_f32_e32 v243, s9, v243
	v_rcp_f32_e32 v206, v206
	v_rcp_f32_e32 v207, v207
	v_rcp_f32_e32 v220, v220
	v_rcp_f32_e32 v221, v221
	v_mul_f32_e32 v222, v206, v222
	v_mul_f32_e32 v223, v207, v223
	v_mul_f32_e32 v242, v220, v242
	v_mul_f32_e32 v243, v221, v243
	v_mul_f32_e32 v82, v222, v82
	v_mul_f32_e32 v83, v223, v83
	v_mul_f32_e32 v84, v242, v84
	v_mul_f32_e32 v85, v243, v85
	v_cvt_f32_ubyte0_e32 v206, v147
	v_cvt_f32_ubyte1_e32 v207, v147
	v_cvt_f32_ubyte2_e32 v220, v147
	v_cvt_f32_ubyte3_e32 v221, v147
	v_cvt_f32_ubyte0_e32 v222, v163
	v_cvt_f32_ubyte1_e32 v223, v163
	v_cvt_f32_ubyte2_e32 v242, v163
	v_cvt_f32_ubyte3_e32 v243, v163
	v_max_f32_e32 v206, s9, v206
	v_max_f32_e32 v207, s9, v207
	v_max_f32_e32 v220, s9, v220
	v_max_f32_e32 v221, s9, v221
	v_max_f32_e32 v222, s9, v222
	v_max_f32_e32 v223, s9, v223
	v_max_f32_e32 v242, s9, v242
	v_max_f32_e32 v243, s9, v243
	v_rcp_f32_e32 v206, v206
	v_rcp_f32_e32 v207, v207
	v_rcp_f32_e32 v220, v220
	v_rcp_f32_e32 v221, v221
	v_mul_f32_e32 v222, v206, v222
	v_mul_f32_e32 v223, v207, v223
	v_mul_f32_e32 v242, v220, v242
	v_mul_f32_e32 v243, v221, v243
	v_mul_f32_e32 v78, v222, v78
	v_mul_f32_e32 v79, v223, v79
	v_mul_f32_e32 v80, v242, v80
	v_mul_f32_e32 v81, v243, v81
	v_cvt_f32_ubyte0_e32 v206, v148
	v_cvt_f32_ubyte1_e32 v207, v148
	v_cvt_f32_ubyte2_e32 v220, v148
	v_cvt_f32_ubyte3_e32 v221, v148
	v_cvt_f32_ubyte0_e32 v222, v164
	v_cvt_f32_ubyte1_e32 v223, v164
	v_cvt_f32_ubyte2_e32 v242, v164
	v_cvt_f32_ubyte3_e32 v243, v164
	v_max_f32_e32 v206, s9, v206
	v_max_f32_e32 v207, s9, v207
	v_max_f32_e32 v220, s9, v220
	v_max_f32_e32 v221, s9, v221
	v_max_f32_e32 v222, s9, v222
	v_max_f32_e32 v223, s9, v223
	v_max_f32_e32 v242, s9, v242
	v_max_f32_e32 v243, s9, v243
	v_rcp_f32_e32 v206, v206
	v_rcp_f32_e32 v207, v207
	v_rcp_f32_e32 v220, v220
	v_rcp_f32_e32 v221, v221
	v_mul_f32_e32 v222, v206, v222
	v_mul_f32_e32 v223, v207, v223
	v_mul_f32_e32 v242, v220, v242
	v_mul_f32_e32 v243, v221, v243
	v_mul_f32_e32 v74, v222, v74
	v_mul_f32_e32 v75, v223, v75
	v_mul_f32_e32 v76, v242, v76
	v_mul_f32_e32 v77, v243, v77
	v_cvt_f32_ubyte0_e32 v206, v149
	v_cvt_f32_ubyte1_e32 v207, v149
	v_cvt_f32_ubyte2_e32 v220, v149
	v_cvt_f32_ubyte3_e32 v221, v149
	v_cvt_f32_ubyte0_e32 v222, v165
	v_cvt_f32_ubyte1_e32 v223, v165
	v_cvt_f32_ubyte2_e32 v242, v165
	v_cvt_f32_ubyte3_e32 v243, v165
	v_max_f32_e32 v206, s9, v206
	v_max_f32_e32 v207, s9, v207
	v_max_f32_e32 v220, s9, v220
	v_max_f32_e32 v221, s9, v221
	v_max_f32_e32 v222, s9, v222
	v_max_f32_e32 v223, s9, v223
	v_max_f32_e32 v242, s9, v242
	v_max_f32_e32 v243, s9, v243
	v_rcp_f32_e32 v206, v206
	v_rcp_f32_e32 v207, v207
	v_rcp_f32_e32 v220, v220
	v_rcp_f32_e32 v221, v221
	v_mul_f32_e32 v222, v206, v222
	v_mul_f32_e32 v223, v207, v223
	v_mul_f32_e32 v242, v220, v242
	v_mul_f32_e32 v243, v221, v243
	v_mul_f32_e32 v70, v222, v70
	v_mul_f32_e32 v71, v223, v71
	v_mul_f32_e32 v72, v242, v72
	v_mul_f32_e32 v73, v243, v73
	s_waitcnt vmcnt(6)
; __device__ __forceinline__ float ub(unsigned w, int k) { return (float)((w >> (8 * k)) & 255u) * (1.0f / 255.0f); }
	v_cvt_f32_ubyte0_e32 v206, v186
	v_cvt_f32_ubyte1_e32 v207, v186
	v_cvt_f32_ubyte2_e32 v220, v186
	v_cvt_f32_ubyte3_e32 v221, v186
	v_cvt_f32_ubyte0_e32 v222, v166
	v_cvt_f32_ubyte1_e32 v223, v166
	v_cvt_f32_ubyte2_e32 v242, v166
	v_cvt_f32_ubyte3_e32 v243, v166
	v_max_f32_e32 v206, s9, v206
	v_max_f32_e32 v207, s9, v207
	v_max_f32_e32 v220, s9, v220
	v_max_f32_e32 v221, s9, v221
	v_max_f32_e32 v222, s9, v222
	v_max_f32_e32 v223, s9, v223
	v_max_f32_e32 v242, s9, v242
	v_max_f32_e32 v243, s9, v243
	v_rcp_f32_e32 v206, v206
	v_rcp_f32_e32 v207, v207
	v_rcp_f32_e32 v220, v220
	v_rcp_f32_e32 v221, v221
	v_mul_f32_e32 v222, v206, v222
	v_mul_f32_e32 v223, v207, v223
	v_mul_f32_e32 v242, v220, v242
	v_mul_f32_e32 v243, v221, v243
	v_mul_f32_e32 v66, v222, v66
	v_mul_f32_e32 v67, v223, v67
	v_mul_f32_e32 v68, v242, v68
	v_mul_f32_e32 v69, v243, v69
	v_cvt_f32_ubyte0_e32 v206, v187
	v_cvt_f32_ubyte1_e32 v207, v187
	v_cvt_f32_ubyte2_e32 v220, v187
	v_cvt_f32_ubyte3_e32 v221, v187
	v_cvt_f32_ubyte0_e32 v222, v167
	v_cvt_f32_ubyte1_e32 v223, v167
	v_cvt_f32_ubyte2_e32 v242, v167
	v_cvt_f32_ubyte3_e32 v243, v167
	v_max_f32_e32 v206, s9, v206
	v_max_f32_e32 v207, s9, v207
	v_max_f32_e32 v220, s9, v220
	v_max_f32_e32 v221, s9, v221
	v_max_f32_e32 v222, s9, v222
	v_max_f32_e32 v223, s9, v223
	v_max_f32_e32 v242, s9, v242
	v_max_f32_e32 v243, s9, v243
	v_rcp_f32_e32 v206, v206
	v_rcp_f32_e32 v207, v207
	v_rcp_f32_e32 v220, v220
	v_rcp_f32_e32 v221, v221
	v_mul_f32_e32 v222, v206, v222
	v_mul_f32_e32 v223, v207, v223
	v_mul_f32_e32 v242, v220, v242
	v_mul_f32_e32 v243, v221, v243
	v_mul_f32_e32 v62, v222, v62
	v_mul_f32_e32 v63, v223, v63
	v_mul_f32_e32 v64, v242, v64
	v_mul_f32_e32 v65, v243, v65
	v_cvt_f32_ubyte0_e32 v206, v188
	v_cvt_f32_ubyte1_e32 v207, v188
	v_cvt_f32_ubyte2_e32 v220, v188
	v_cvt_f32_ubyte3_e32 v221, v188
	v_cvt_f32_ubyte0_e32 v222, v168
	v_cvt_f32_ubyte1_e32 v223, v168
	v_cvt_f32_ubyte2_e32 v242, v168
	v_cvt_f32_ubyte3_e32 v243, v168
	v_max_f32_e32 v206, s9, v206
	v_max_f32_e32 v207, s9, v207
	v_max_f32_e32 v220, s9, v220
	v_max_f32_e32 v221, s9, v221
	v_max_f32_e32 v222, s9, v222
	v_max_f32_e32 v223, s9, v223
	v_max_f32_e32 v242, s9, v242
	v_max_f32_e32 v243, s9, v243
	v_rcp_f32_e32 v206, v206
	v_rcp_f32_e32 v207, v207
	v_rcp_f32_e32 v220, v220
	v_rcp_f32_e32 v221, v221
	v_mul_f32_e32 v222, v206, v222
	v_mul_f32_e32 v223, v207, v223
	v_mul_f32_e32 v242, v220, v242
	v_mul_f32_e32 v243, v221, v243
	v_mul_f32_e32 v58, v222, v58
	v_mul_f32_e32 v59, v223, v59
	v_mul_f32_e32 v60, v242, v60
	v_mul_f32_e32 v61, v243, v61
	v_cvt_f32_ubyte0_e32 v206, v189
	v_cvt_f32_ubyte1_e32 v207, v189
	v_cvt_f32_ubyte2_e32 v220, v189
	v_cvt_f32_ubyte3_e32 v221, v189
	v_cvt_f32_ubyte0_e32 v222, v169
	v_cvt_f32_ubyte1_e32 v223, v169
	v_cvt_f32_ubyte2_e32 v242, v169
	v_cvt_f32_ubyte3_e32 v243, v169
	v_max_f32_e32 v206, s9, v206
	v_max_f32_e32 v207, s9, v207
	v_max_f32_e32 v220, s9, v220
	v_max_f32_e32 v221, s9, v221
	v_max_f32_e32 v222, s9, v222
	v_max_f32_e32 v223, s9, v223
	v_max_f32_e32 v242, s9, v242
	v_max_f32_e32 v243, s9, v243
	v_rcp_f32_e32 v206, v206
	v_rcp_f32_e32 v207, v207
	v_rcp_f32_e32 v220, v220
	v_rcp_f32_e32 v221, v221
	v_mul_f32_e32 v222, v206, v222
	v_mul_f32_e32 v223, v207, v223
	v_mul_f32_e32 v242, v220, v242
	v_mul_f32_e32 v243, v221, v243
	v_mul_f32_e32 v54, v222, v54
	v_mul_f32_e32 v55, v223, v55
	v_mul_f32_e32 v56, v242, v56
	v_mul_f32_e32 v57, v243, v57
	s_waitcnt vmcnt(4)
	v_cvt_f32_ubyte0_e32 v206, v208
	v_cvt_f32_ubyte1_e32 v207, v208
	v_cvt_f32_ubyte2_e32 v220, v208
	v_cvt_f32_ubyte3_e32 v221, v208
	v_cvt_f32_ubyte0_e32 v222, v170
	v_cvt_f32_ubyte1_e32 v223, v170
	v_cvt_f32_ubyte2_e32 v242, v170
	v_cvt_f32_ubyte3_e32 v243, v170
	v_max_f32_e32 v206, s9, v206
	v_max_f32_e32 v207, s9, v207
	v_max_f32_e32 v220, s9, v220
	v_max_f32_e32 v221, s9, v221
	v_max_f32_e32 v222, s9, v222
	v_max_f32_e32 v223, s9, v223
	v_max_f32_e32 v242, s9, v242
	v_max_f32_e32 v243, s9, v243
	v_rcp_f32_e32 v206, v206
	v_rcp_f32_e32 v207, v207
	v_rcp_f32_e32 v220, v220
	v_rcp_f32_e32 v221, v221
	v_mul_f32_e32 v222, v206, v222
	v_mul_f32_e32 v223, v207, v223
	v_mul_f32_e32 v242, v220, v242
	v_mul_f32_e32 v243, v221, v243
	v_mul_f32_e32 v50, v222, v50
	v_mul_f32_e32 v51, v223, v51
	v_mul_f32_e32 v52, v242, v52
	v_mul_f32_e32 v53, v243, v53
	v_cvt_f32_ubyte0_e32 v206, v209
	v_cvt_f32_ubyte1_e32 v207, v209
	v_cvt_f32_ubyte2_e32 v220, v209
	v_cvt_f32_ubyte3_e32 v221, v209
	v_cvt_f32_ubyte0_e32 v222, v171
	v_cvt_f32_ubyte1_e32 v223, v171
	v_cvt_f32_ubyte2_e32 v242, v171
	v_cvt_f32_ubyte3_e32 v243, v171
	v_max_f32_e32 v206, s9, v206
	v_max_f32_e32 v207, s9, v207
	v_max_f32_e32 v220, s9, v220
	v_max_f32_e32 v221, s9, v221
	v_max_f32_e32 v222, s9, v222
	v_max_f32_e32 v223, s9, v223
	v_max_f32_e32 v242, s9, v242
	v_max_f32_e32 v243, s9, v243
	v_rcp_f32_e32 v206, v206
	v_rcp_f32_e32 v207, v207
	v_rcp_f32_e32 v220, v220
	v_rcp_f32_e32 v221, v221
	v_mul_f32_e32 v222, v206, v222
	v_mul_f32_e32 v223, v207, v223
	v_mul_f32_e32 v242, v220, v242
	v_mul_f32_e32 v243, v221, v243
	v_mul_f32_e32 v46, v222, v46
	v_mul_f32_e32 v47, v223, v47
	v_mul_f32_e32 v48, v242, v48
	v_mul_f32_e32 v49, v243, v49
	v_cvt_f32_ubyte0_e32 v206, v210
	v_cvt_f32_ubyte1_e32 v207, v210
	v_cvt_f32_ubyte2_e32 v220, v210
	v_cvt_f32_ubyte3_e32 v221, v210
	v_cvt_f32_ubyte0_e32 v222, v172
	v_cvt_f32_ubyte1_e32 v223, v172
	v_cvt_f32_ubyte2_e32 v242, v172
	v_cvt_f32_ubyte3_e32 v243, v172
	v_max_f32_e32 v206, s9, v206
	v_max_f32_e32 v207, s9, v207
	v_max_f32_e32 v220, s9, v220
	v_max_f32_e32 v221, s9, v221
	v_max_f32_e32 v222, s9, v222
	v_max_f32_e32 v223, s9, v223
	v_max_f32_e32 v242, s9, v242
	v_max_f32_e32 v243, s9, v243
	v_rcp_f32_e32 v206, v206
	v_rcp_f32_e32 v207, v207
	v_rcp_f32_e32 v220, v220
	v_rcp_f32_e32 v221, v221
	v_mul_f32_e32 v222, v206, v222
	v_mul_f32_e32 v223, v207, v223
	v_mul_f32_e32 v242, v220, v242
	v_mul_f32_e32 v243, v221, v243
	v_mul_f32_e32 v42, v222, v42
	v_mul_f32_e32 v43, v223, v43
	v_mul_f32_e32 v44, v242, v44
	v_mul_f32_e32 v45, v243, v45
	v_cvt_f32_ubyte0_e32 v206, v211
	v_cvt_f32_ubyte1_e32 v207, v211
	v_cvt_f32_ubyte2_e32 v220, v211
	v_cvt_f32_ubyte3_e32 v221, v211
	v_cvt_f32_ubyte0_e32 v222, v173
	v_cvt_f32_ubyte1_e32 v223, v173
	v_cvt_f32_ubyte2_e32 v242, v173
	v_cvt_f32_ubyte3_e32 v243, v173
	v_max_f32_e32 v206, s9, v206
	v_max_f32_e32 v207, s9, v207
	v_max_f32_e32 v220, s9, v220
	v_max_f32_e32 v221, s9, v221
	v_max_f32_e32 v222, s9, v222
	v_max_f32_e32 v223, s9, v223
	v_max_f32_e32 v242, s9, v242
	v_max_f32_e32 v243, s9, v243
	v_rcp_f32_e32 v206, v206
	v_rcp_f32_e32 v207, v207
	v_rcp_f32_e32 v220, v220
	v_rcp_f32_e32 v221, v221
	v_mul_f32_e32 v222, v206, v222
	v_mul_f32_e32 v223, v207, v223
	v_mul_f32_e32 v242, v220, v242
	v_mul_f32_e32 v243, v221, v243
	v_mul_f32_e32 v38, v222, v38
	v_mul_f32_e32 v39, v223, v39
	v_mul_f32_e32 v40, v242, v40
	v_mul_f32_e32 v41, v243, v41
	s_waitcnt vmcnt(2)
; __device__ __forceinline__ float ub(unsigned w, int k) { return (float)((w >> (8 * k)) & 255u) * (1.0f / 255.0f); }
	v_cvt_f32_ubyte0_e32 v206, v212
	v_cvt_f32_ubyte1_e32 v207, v212
	v_cvt_f32_ubyte2_e32 v220, v212
	v_cvt_f32_ubyte3_e32 v221, v212
	v_cvt_f32_ubyte0_e32 v222, v174
	v_cvt_f32_ubyte1_e32 v223, v174
	v_cvt_f32_ubyte2_e32 v242, v174
	v_cvt_f32_ubyte3_e32 v243, v174
	v_max_f32_e32 v206, s9, v206
	v_max_f32_e32 v207, s9, v207
	v_max_f32_e32 v220, s9, v220
	v_max_f32_e32 v221, s9, v221
	v_max_f32_e32 v222, s9, v222
	v_max_f32_e32 v223, s9, v223
	v_max_f32_e32 v242, s9, v242
	v_max_f32_e32 v243, s9, v243
	v_rcp_f32_e32 v206, v206
	v_rcp_f32_e32 v207, v207
	v_rcp_f32_e32 v220, v220
	v_rcp_f32_e32 v221, v221
	v_mul_f32_e32 v222, v206, v222
	v_mul_f32_e32 v223, v207, v223
	v_mul_f32_e32 v242, v220, v242
	v_mul_f32_e32 v243, v221, v243
	v_mul_f32_e32 v34, v222, v34
	v_mul_f32_e32 v35, v223, v35
	v_mul_f32_e32 v36, v242, v36
	v_mul_f32_e32 v37, v243, v37
	v_cvt_f32_ubyte0_e32 v206, v213
	v_cvt_f32_ubyte1_e32 v207, v213
	v_cvt_f32_ubyte2_e32 v220, v213
	v_cvt_f32_ubyte3_e32 v221, v213
	v_cvt_f32_ubyte0_e32 v222, v175
	v_cvt_f32_ubyte1_e32 v223, v175
	v_cvt_f32_ubyte2_e32 v242, v175
	v_cvt_f32_ubyte3_e32 v243, v175
	v_max_f32_e32 v206, s9, v206
	v_max_f32_e32 v207, s9, v207
	v_max_f32_e32 v220, s9, v220
	v_max_f32_e32 v221, s9, v221
	v_max_f32_e32 v222, s9, v222
	v_max_f32_e32 v223, s9, v223
	v_max_f32_e32 v242, s9, v242
	v_max_f32_e32 v243, s9, v243
	v_rcp_f32_e32 v206, v206
	v_rcp_f32_e32 v207, v207
	v_rcp_f32_e32 v220, v220
	v_rcp_f32_e32 v221, v221
	v_mul_f32_e32 v222, v206, v222
	v_mul_f32_e32 v223, v207, v223
	v_mul_f32_e32 v242, v220, v242
	v_mul_f32_e32 v243, v221, v243
	v_mul_f32_e32 v30, v222, v30
	v_mul_f32_e32 v31, v223, v31
	v_mul_f32_e32 v32, v242, v32
	v_mul_f32_e32 v33, v243, v33
	v_cvt_f32_ubyte0_e32 v206, v214
	v_cvt_f32_ubyte1_e32 v207, v214
	v_cvt_f32_ubyte2_e32 v220, v214
	v_cvt_f32_ubyte3_e32 v221, v214
	v_cvt_f32_ubyte0_e32 v222, v176
	v_cvt_f32_ubyte1_e32 v223, v176
	v_cvt_f32_ubyte2_e32 v242, v176
	v_cvt_f32_ubyte3_e32 v243, v176
	v_max_f32_e32 v206, s9, v206
	v_max_f32_e32 v207, s9, v207
	v_max_f32_e32 v220, s9, v220
	v_max_f32_e32 v221, s9, v221
	v_max_f32_e32 v222, s9, v222
	v_max_f32_e32 v223, s9, v223
	v_max_f32_e32 v242, s9, v242
	v_max_f32_e32 v243, s9, v243
	v_rcp_f32_e32 v206, v206
	v_rcp_f32_e32 v207, v207
	v_rcp_f32_e32 v220, v220
	v_rcp_f32_e32 v221, v221
	v_mul_f32_e32 v222, v206, v222
	v_mul_f32_e32 v223, v207, v223
	v_mul_f32_e32 v242, v220, v242
	v_mul_f32_e32 v243, v221, v243
	v_mul_f32_e32 v26, v222, v26
	v_mul_f32_e32 v27, v223, v27
	v_mul_f32_e32 v28, v242, v28
	v_mul_f32_e32 v29, v243, v29
	v_cvt_f32_ubyte0_e32 v206, v215
	v_cvt_f32_ubyte1_e32 v207, v215
	v_cvt_f32_ubyte2_e32 v220, v215
	v_cvt_f32_ubyte3_e32 v221, v215
	v_cvt_f32_ubyte0_e32 v222, v177
	v_cvt_f32_ubyte1_e32 v223, v177
	v_cvt_f32_ubyte2_e32 v242, v177
	v_cvt_f32_ubyte3_e32 v243, v177
	v_max_f32_e32 v206, s9, v206
	v_max_f32_e32 v207, s9, v207
	v_max_f32_e32 v220, s9, v220
	v_max_f32_e32 v221, s9, v221
	v_max_f32_e32 v222, s9, v222
	v_max_f32_e32 v223, s9, v223
	v_max_f32_e32 v242, s9, v242
	v_max_f32_e32 v243, s9, v243
	v_rcp_f32_e32 v206, v206
	v_rcp_f32_e32 v207, v207
	v_rcp_f32_e32 v220, v220
	v_rcp_f32_e32 v221, v221
	v_mul_f32_e32 v222, v206, v222
	v_mul_f32_e32 v223, v207, v223
	v_mul_f32_e32 v242, v220, v242
	v_mul_f32_e32 v243, v221, v243
	v_mul_f32_e32 v22, v222, v22
	v_mul_f32_e32 v23, v223, v23
	v_mul_f32_e32 v24, v242, v24
	v_mul_f32_e32 v25, v243, v25
	s_waitcnt vmcnt(0)
	v_cvt_f32_ubyte0_e32 v206, v216
	v_cvt_f32_ubyte1_e32 v207, v216
	v_cvt_f32_ubyte2_e32 v220, v216
	v_cvt_f32_ubyte3_e32 v221, v216
	v_cvt_f32_ubyte0_e32 v222, v178
	v_cvt_f32_ubyte1_e32 v223, v178
	v_cvt_f32_ubyte2_e32 v242, v178
	v_cvt_f32_ubyte3_e32 v243, v178
	v_max_f32_e32 v206, s9, v206
	v_max_f32_e32 v207, s9, v207
	v_max_f32_e32 v220, s9, v220
	v_max_f32_e32 v221, s9, v221
	v_max_f32_e32 v222, s9, v222
	v_max_f32_e32 v223, s9, v223
	v_max_f32_e32 v242, s9, v242
	v_max_f32_e32 v243, s9, v243
	v_rcp_f32_e32 v206, v206
	v_rcp_f32_e32 v207, v207
	v_rcp_f32_e32 v220, v220
	v_rcp_f32_e32 v221, v221
	v_mul_f32_e32 v222, v206, v222
	v_mul_f32_e32 v223, v207, v223
	v_mul_f32_e32 v242, v220, v242
	v_mul_f32_e32 v243, v221, v243
	v_mul_f32_e32 v18, v222, v18
	v_mul_f32_e32 v19, v223, v19
	v_mul_f32_e32 v20, v242, v20
	v_mul_f32_e32 v21, v243, v21
	v_cvt_f32_ubyte0_e32 v206, v217
	v_cvt_f32_ubyte1_e32 v207, v217
	v_cvt_f32_ubyte2_e32 v220, v217
	v_cvt_f32_ubyte3_e32 v221, v217
	v_cvt_f32_ubyte0_e32 v222, v179
	v_cvt_f32_ubyte1_e32 v223, v179
	v_cvt_f32_ubyte2_e32 v242, v179
	v_cvt_f32_ubyte3_e32 v243, v179
	v_max_f32_e32 v206, s9, v206
	v_max_f32_e32 v207, s9, v207
	v_max_f32_e32 v220, s9, v220
	v_max_f32_e32 v221, s9, v221
	v_max_f32_e32 v222, s9, v222
	v_max_f32_e32 v223, s9, v223
	v_max_f32_e32 v242, s9, v242
	v_max_f32_e32 v243, s9, v243
	v_rcp_f32_e32 v206, v206
	v_rcp_f32_e32 v207, v207
	v_rcp_f32_e32 v220, v220
	v_rcp_f32_e32 v221, v221
	v_mul_f32_e32 v222, v206, v222
	v_mul_f32_e32 v223, v207, v223
	v_mul_f32_e32 v242, v220, v242
	v_mul_f32_e32 v243, v221, v243
	v_mul_f32_e32 v8, v222, v8
	v_mul_f32_e32 v9, v223, v9
	v_mul_f32_e32 v10, v242, v10
	v_mul_f32_e32 v11, v243, v11
	v_cvt_f32_ubyte0_e32 v206, v218
	v_cvt_f32_ubyte1_e32 v207, v218
	v_cvt_f32_ubyte2_e32 v220, v218
	v_cvt_f32_ubyte3_e32 v221, v218
	v_cvt_f32_ubyte0_e32 v222, v180
	v_cvt_f32_ubyte1_e32 v223, v180
	v_cvt_f32_ubyte2_e32 v242, v180
	v_cvt_f32_ubyte3_e32 v243, v180
	v_max_f32_e32 v206, s9, v206
	v_max_f32_e32 v207, s9, v207
	v_max_f32_e32 v220, s9, v220
	v_max_f32_e32 v221, s9, v221
	v_max_f32_e32 v222, s9, v222
	v_max_f32_e32 v223, s9, v223
	v_max_f32_e32 v242, s9, v242
	v_max_f32_e32 v243, s9, v243
	v_rcp_f32_e32 v206, v206
	v_rcp_f32_e32 v207, v207
	v_rcp_f32_e32 v220, v220
	v_rcp_f32_e32 v221, v221
	v_mul_f32_e32 v222, v206, v222
	v_mul_f32_e32 v223, v207, v223
	v_mul_f32_e32 v242, v220, v242
	v_mul_f32_e32 v243, v221, v243
	v_mul_f32_e32 v4, v222, v4
	v_mul_f32_e32 v5, v223, v5
	v_mul_f32_e32 v6, v242, v6
	v_mul_f32_e32 v7, v243, v7
	v_cvt_f32_ubyte0_e32 v206, v219
	v_cvt_f32_ubyte1_e32 v207, v219
	v_cvt_f32_ubyte2_e32 v220, v219
	v_cvt_f32_ubyte3_e32 v221, v219
	v_cvt_f32_ubyte0_e32 v222, v181
	v_cvt_f32_ubyte1_e32 v223, v181
	v_cvt_f32_ubyte2_e32 v242, v181
	v_cvt_f32_ubyte3_e32 v243, v181
	v_max_f32_e32 v206, s9, v206
	v_max_f32_e32 v207, s9, v207
	v_max_f32_e32 v220, s9, v220
	v_max_f32_e32 v221, s9, v221
	v_max_f32_e32 v222, s9, v222
	v_max_f32_e32 v223, s9, v223
	v_max_f32_e32 v242, s9, v242
	v_max_f32_e32 v243, s9, v243
	v_rcp_f32_e32 v206, v206
	v_rcp_f32_e32 v207, v207
	v_rcp_f32_e32 v220, v220
	v_rcp_f32_e32 v221, v221
	v_mul_f32_e32 v222, v206, v222
	v_mul_f32_e32 v223, v207, v223
	v_mul_f32_e32 v242, v220, v242
	v_mul_f32_e32 v243, v221, v243
	v_mul_f32_e32 v0, v222, v0
	v_mul_f32_e32 v1, v223, v1
	v_mul_f32_e32 v2, v242, v2
	v_mul_f32_e32 v3, v243, v3
	s_mov_b32 s68, s66
	s_mov_b32 s41, s64
	s_mov_b32 s67, s44
	s_mov_b32 s40, s46
	s_mov_b64 s[54:55], s[50:51]
	s_mov_b64 s[52:53], s[48:49]
	s_branch .LBB0_233

; #define PG8_STAGE(bufoff, gbase, voff) do { _Pragma("unroll") for (int _i = 0; _i < 2; ++_i) \
;         __builtin_amdgcn_global_load_lds((const unsigned*)((const char*)(gbase) + (voff)[_i]), (LAS unsigned*)(lds + (bufoff) + ldsw + _i * 8192), 16, 0, 0); } while (0)
; #define PG8_LDA(dst, b, h) do { _Pragma("unroll") for (int m = 0; m < 4; ++m) _Pragma("unroll") for (int k = 0; k < 2; ++k) dst[m][k] = *(const LAS bf16x8*)(lds + PG8_SA(b, h) + aoff + m * 2048 + k * 1024); } while (0)
; #define PG8_LDB(dst, b, h) do { _Pragma("unroll") for (int n = 0; n < 2; ++n) _Pragma("unroll") for (int k = 0; k < 2; ++k) dst[n][k] = *(const LAS bf16x8*)(lds + PG8_SB(b, h) + boff + n * 2048 + k * 1024); } while (0)
; #define PG8_MMA(ai, bj, At, Bt) do { __builtin_amdgcn_s_setprio(1); _Pragma("unroll") for (int m = 0; m < 4; ++m) _Pragma("unroll") for (int n = 0; n < 2; ++n) _Pragma("unroll") for (int k = 0; k < 2; ++k) \
;         acc[ai][bj][m][n] = __builtin_amdgcn_mfma_f32_16x16x32_bf16(Bt[n][k], At[m][k], acc[ai][bj][m][n], 0, 0, 0); __builtin_amdgcn_s_setprio(0); } while (0)
; #define PG8_WAIT_V(n) asm volatile("s_waitcnt vmcnt(" #n ")" ::: "memory")
; #define PG8_WAIT_L(n) asm volatile("s_waitcnt lgkmcnt(" #n ")" ::: "memory")
; template <class Epi, class Sched>
; __device__ __forceinline__ void gemm_phase(const int TID, LAS unsigned char* lds, const int lda, const int ldb, const Sched& S, const Epi& E) {
;     ...
;         for (int t = 0; t < nt; t += 2) {
;             const bool last = (t == nt - 2);
;             const char* a1 = cA + (size_t)(t + 1) * kstep;
;             const char* a2 = last ? nA : cA + (size_t)(t + 2) * kstep; const char* b2 = last ? nB : cB + (size_t)(t + 2) * kstep;
;             const char* a3 = a2 + kstep; const char* b3 = b2 + kstep;
;             PG8_LDB(B0, 0, 0); PG8_SCHED; PG8_LDA(At, 0, 0); PG8_STAGE(PG8_SA(1, 1), a1 + hA, voffA);
;             PG8_WAIT_L(8); PG8_BAR; PG8_WAIT_L(0); PG8_MMA(0, 0, At, B0); PG8_BAR; PG8_SCHED;
;             PG8_LDB(B1, 0, 1); PG8_STAGE(PG8_SB(0, 0), b2, voffB);
;             PG8_BAR; PG8_WAIT_L(0); PG8_MMA(0, 1, At, B1); PG8_BAR;
;             PG8_LDA(At, 0, 1); PG8_STAGE(PG8_SA(0, 0), a2, voffA);
;             PG8_BAR; PG8_WAIT_L(0); PG8_MMA(1, 0, At, B0); PG8_BAR; PG8_SCHED;
;             PG8_STAGE(PG8_SB(0, 1), b2 + hB, voffB);
;             PG8_WAIT_V(6); PG8_BAR; PG8_MMA(1, 1, At, B1); PG8_BAR;
.LBB0_295:
	s_add_u32 s8, s28, 0xfffe0080
	s_addc_u32 s9, s29, -1
	s_add_i32 s10, 0, 0x10000
	v_add_u32_e32 v50, s10, v214
	ds_read_b128 v[30:33], v50
	ds_read_b128 v[38:41], v50 offset:1024
	ds_read_b128 v[46:49], v50 offset:2048
	ds_read_b128 v[50:53], v50 offset:3072
	s_cmp_eq_u32 s49, 4
	s_cselect_b32 s57, s51, s9
	s_cselect_b32 s56, s50, s8
	s_cselect_b32 s55, s53, s47
	s_cselect_b32 s54, s52, s23
	v_lshl_add_u64 v[186:187], s[28:29], 0, v[202:203]
	s_add_i32 m0, s3, 0xc000
	ds_read_b128 v[142:145], v216
	ds_read_b128 v[146:149], v216 offset:1024
	ds_read_b128 v[154:157], v216 offset:2048
	ds_read_b128 v[158:161], v216 offset:3072
	ds_read_b128 v[166:169], v216 offset:4096
	ds_read_b128 v[170:173], v216 offset:5120
	ds_read_b128 v[174:177], v216 offset:6144
	ds_read_b128 v[178:181], v216 offset:7168
	global_load_lds_dwordx4 v[186:187], off
	s_add_i32 m0, s3, 0xe000
	v_lshl_add_u64 v[186:187], s[28:29], 0, v[200:201]
	global_load_lds_dwordx4 v[186:187], off
	s_waitcnt lgkmcnt(8)
	s_barrier
	s_waitcnt lgkmcnt(0)
	s_setprio 1
	s_waitcnt lgkmcnt(0)
	v_mfma_f32_16x16x32_bf16 v[162:165], v[30:33], v[142:145], v[162:165]
	v_mfma_f32_16x16x32_bf16 v[150:153], v[46:49], v[142:145], v[150:153]
	v_mfma_f32_16x16x32_bf16 v[130:133], v[30:33], v[154:157], v[130:133]
	v_mfma_f32_16x16x32_bf16 v[126:129], v[46:49], v[154:157], v[126:129]
	v_mfma_f32_16x16x32_bf16 v[114:117], v[30:33], v[166:169], v[114:117]
	v_mfma_f32_16x16x32_bf16 v[110:113], v[46:49], v[166:169], v[110:113]
	v_mfma_f32_16x16x32_bf16 v[98:101], v[30:33], v[174:177], v[98:101]
	v_mfma_f32_16x16x32_bf16 v[94:97], v[46:49], v[174:177], v[94:97]
	v_mfma_f32_16x16x32_bf16 v[162:165], v[38:41], v[146:149], v[162:165]
	v_mfma_f32_16x16x32_bf16 v[150:153], v[50:53], v[146:149], v[150:153]
	v_mfma_f32_16x16x32_bf16 v[130:133], v[38:41], v[158:161], v[130:133]
	v_mfma_f32_16x16x32_bf16 v[126:129], v[50:53], v[158:161], v[126:129]
	v_mfma_f32_16x16x32_bf16 v[114:117], v[38:41], v[170:173], v[114:117]
	v_mfma_f32_16x16x32_bf16 v[110:113], v[50:53], v[170:173], v[110:113]
	v_mfma_f32_16x16x32_bf16 v[98:101], v[38:41], v[178:181], v[98:101]
	v_mfma_f32_16x16x32_bf16 v[94:97], v[50:53], v[178:181], v[94:97]
	s_setprio 0
	s_barrier
	s_add_i32 s11, 0, 0x14000
	v_add_u32_e32 v212, s11, v214
	s_add_i32 s8, s10, s62
	ds_read_b128 v[186:189], v212
	ds_read_b128 v[204:207], v212 offset:1024
	ds_read_b128 v[208:211], v212 offset:2048
	ds_read_b128 v[218:221], v212 offset:3072
	v_lshl_add_u64 v[212:213], s[54:55], 0, v[182:183]
	s_mov_b32 m0, s8
	v_lshl_add_u64 v[222:223], s[54:55], 0, v[198:199]
	global_load_lds_dwordx4 v[212:213], off
	s_add_i32 m0, s8, 0x2000
	s_nop 0
	global_load_lds_dwordx4 v[222:223], off
	s_barrier
	s_waitcnt lgkmcnt(0)
	s_setprio 1
	s_waitcnt lgkmcnt(0)
	v_mfma_f32_16x16x32_bf16 v[138:141], v[186:189], v[142:145], v[138:141]
	v_mfma_f32_16x16x32_bf16 v[134:137], v[208:211], v[142:145], v[134:137]
	v_mfma_f32_16x16x32_bf16 v[122:125], v[186:189], v[154:157], v[122:125]
	v_mfma_f32_16x16x32_bf16 v[118:121], v[208:211], v[154:157], v[118:121]
	v_mfma_f32_16x16x32_bf16 v[106:109], v[186:189], v[166:169], v[106:109]
	v_mfma_f32_16x16x32_bf16 v[102:105], v[208:211], v[166:169], v[102:105]
	v_mfma_f32_16x16x32_bf16 v[90:93], v[186:189], v[174:177], v[90:93]
	v_mfma_f32_16x16x32_bf16 v[86:89], v[208:211], v[174:177], v[86:89]
	v_mfma_f32_16x16x32_bf16 v[138:141], v[204:207], v[146:149], v[138:141]
	v_mfma_f32_16x16x32_bf16 v[134:137], v[218:221], v[146:149], v[134:137]
	v_mfma_f32_16x16x32_bf16 v[122:125], v[204:207], v[158:161], v[122:125]
	v_mfma_f32_16x16x32_bf16 v[118:121], v[218:221], v[158:161], v[118:121]
	v_mfma_f32_16x16x32_bf16 v[106:109], v[204:207], v[170:173], v[106:109]
	v_mfma_f32_16x16x32_bf16 v[102:105], v[218:221], v[170:173], v[102:105]
	v_mfma_f32_16x16x32_bf16 v[90:93], v[204:207], v[178:181], v[90:93]
	v_mfma_f32_16x16x32_bf16 v[86:89], v[218:221], v[178:181], v[86:89]
	s_setprio 0
	s_mov_b32 m0, s3
	v_lshl_add_u64 v[236:237], s[56:57], 0, v[12:13]
	s_barrier
	ds_read_b128 v[142:145], v216 offset:16384
	ds_read_b128 v[146:149], v216 offset:17408
	ds_read_b128 v[154:157], v216 offset:18432
	ds_read_b128 v[158:161], v216 offset:19456
	ds_read_b128 v[166:169], v216 offset:20480
	ds_read_b128 v[170:173], v216 offset:21504
	ds_read_b128 v[174:177], v216 offset:22528
	ds_read_b128 v[178:181], v216 offset:23552
	global_load_lds_dwordx4 v[236:237], off
	s_mov_b32 m0, s63
	v_lshl_add_u64 v[238:239], s[56:57], 0, v[196:197]
	global_load_lds_dwordx4 v[238:239], off
	s_barrier
	s_waitcnt lgkmcnt(0)
	s_setprio 1
	s_waitcnt lgkmcnt(0)
	v_mfma_f32_16x16x32_bf16 v[82:85], v[30:33], v[142:145], v[82:85]
	v_mfma_f32_16x16x32_bf16 v[78:81], v[46:49], v[142:145], v[78:81]
	v_mfma_f32_16x16x32_bf16 v[66:69], v[30:33], v[154:157], v[66:69]
	v_mfma_f32_16x16x32_bf16 v[62:65], v[46:49], v[154:157], v[62:65]
	v_mfma_f32_16x16x32_bf16 v[42:45], v[30:33], v[166:169], v[42:45]
	v_mfma_f32_16x16x32_bf16 v[34:37], v[46:49], v[166:169], v[34:37]
	v_mfma_f32_16x16x32_bf16 v[18:21], v[30:33], v[174:177], v[18:21]
	v_mfma_f32_16x16x32_bf16 v[8:11], v[46:49], v[174:177], v[8:11]
	v_mfma_f32_16x16x32_bf16 v[82:85], v[38:41], v[146:149], v[82:85]
	v_mfma_f32_16x16x32_bf16 v[78:81], v[50:53], v[146:149], v[78:81]
	v_mfma_f32_16x16x32_bf16 v[66:69], v[38:41], v[158:161], v[66:69]
	v_mfma_f32_16x16x32_bf16 v[62:65], v[50:53], v[158:161], v[62:65]
	v_mfma_f32_16x16x32_bf16 v[42:45], v[38:41], v[170:173], v[42:45]
	v_mfma_f32_16x16x32_bf16 v[34:37], v[50:53], v[170:173], v[34:37]
	v_mfma_f32_16x16x32_bf16 v[18:21], v[38:41], v[178:181], v[18:21]
	v_mfma_f32_16x16x32_bf16 v[8:11], v[50:53], v[178:181], v[8:11]
	s_setprio 0
	s_barrier
; #define PG8_STAGE(bufoff, gbase, voff) do { _Pragma("unroll") for (int _i = 0; _i < 2; ++_i) \
;         __builtin_amdgcn_global_load_lds((const unsigned*)((const char*)(gbase) + (voff)[_i]), (LAS unsigned*)(lds + (bufoff) + ldsw + _i * 8192), 16, 0, 0); } while (0)
; #define PG8_LDA(dst, b, h) do { _Pragma("unroll") for (int m = 0; m < 4; ++m) _Pragma("unroll") for (int k = 0; k < 2; ++k) dst[m][k] = *(const LAS bf16x8*)(lds + PG8_SA(b, h) + aoff + m * 2048 + k * 1024); } while (0)
; #define PG8_LDB(dst, b, h) do { _Pragma("unroll") for (int n = 0; n < 2; ++n) _Pragma("unroll") for (int k = 0; k < 2; ++k) dst[n][k] = *(const LAS bf16x8*)(lds + PG8_SB(b, h) + boff + n * 2048 + k * 1024); } while (0)
; #define PG8_WAIT_V(n) asm volatile("s_waitcnt vmcnt(" #n ")" ::: "memory")
; #define PG8_WAIT_L(n) asm volatile("s_waitcnt lgkmcnt(" #n ")" ::: "memory")
; #define PG8_BAR __builtin_amdgcn_s_barrier()
; #define PG8_SCHED __builtin_amdgcn_sched_barrier(0)
; template <class Epi, class Sched>
; __device__ __forceinline__ void gemm_phase(const int TID, LAS unsigned char* lds, const int lda, const int ldb, const Sched& S, const Epi& E) {
;     ...
;             PG8_LDB(B0, 0, 0); PG8_SCHED; PG8_LDA(At, 0, 0); PG8_STAGE(PG8_SA(1, 1), a1 + hA, voffA);
;             PG8_WAIT_L(8); PG8_BAR; PG8_WAIT_L(0); PG8_MMA(0, 0, At, B0); PG8_BAR; PG8_SCHED;
;             PG8_LDB(B1, 0, 1); PG8_STAGE(PG8_SB(0, 0), b2, voffB);
;             PG8_BAR; PG8_WAIT_L(0); PG8_MMA(0, 1, At, B1); PG8_BAR;
;             PG8_LDA(At, 0, 1); PG8_STAGE(PG8_SA(0, 0), a2, voffA);
;             PG8_BAR; PG8_WAIT_L(0); PG8_MMA(1, 0, At, B0); PG8_BAR; PG8_SCHED;
;             PG8_STAGE(PG8_SB(0, 1), b2 + hB, voffB);
;             PG8_WAIT_V(6); PG8_BAR; PG8_MMA(1, 1, At, B1); PG8_BAR;
;             PG8_LDB(B0, 1, 0); PG8_SCHED; PG8_LDA(At, 1, 0); PG8_STAGE(PG8_SA(0, 1), a2 + hA, voffA);
;             PG8_WAIT_L(8); PG8_BAR; PG8_WAIT_L(0); PG8_MMA(0, 0, At, B0); PG8_BAR; PG8_SCHED;
;             PG8_LDB(B1, 1, 1); PG8_STAGE(PG8_SB(1, 0), b3, voffB);
;             PG8_BAR; PG8_WAIT_L(0); PG8_MMA(0, 1, At, B1); PG8_BAR;
;             PG8_LDA(At, 1, 1); PG8_STAGE(PG8_SA(1, 0), a3, voffA);
;             PG8_BAR; PG8_WAIT_L(0); PG8_MMA(1, 0, At, B0); PG8_BAR; PG8_SCHED;
;             PG8_STAGE(PG8_SB(1, 1), b3 + hB, voffB);
;             PG8_WAIT_V(6); PG8_BAR; PG8_MMA(1, 1, At, B1); PG8_BAR;
	s_add_u32 s8, s54, 0x20000
	s_addc_u32 s9, s55, 0
	s_add_i32 s10, s11, s62
	s_mov_b32 m0, s10
	v_lshl_add_u64 v[30:31], s[8:9], 0, v[182:183]
	global_load_lds_dwordx4 v[30:31], off
	s_add_i32 m0, s10, 0x2000
	v_lshl_add_u64 v[30:31], s[8:9], 0, v[198:199]
	global_load_lds_dwordx4 v[30:31], off
	s_waitcnt vmcnt(6)
	s_barrier
	s_setprio 1
	v_mfma_f32_16x16x32_bf16 v[26:29], v[186:189], v[166:169], v[26:29]
	v_mfma_f32_16x16x32_bf16 v[22:25], v[208:211], v[166:169], v[22:25]
	v_mfma_f32_16x16x32_bf16 v[4:7], v[186:189], v[174:177], v[4:7]
	v_mfma_f32_16x16x32_bf16 v[0:3], v[208:211], v[174:177], v[0:3]
	v_mfma_f32_16x16x32_bf16 v[30:33], v[186:189], v[142:145], v[74:77]
	v_mfma_f32_16x16x32_bf16 v[38:41], v[208:211], v[142:145], v[70:73]
	v_mfma_f32_16x16x32_bf16 v[46:49], v[186:189], v[154:157], v[58:61]
	v_mfma_f32_16x16x32_bf16 v[50:53], v[208:211], v[154:157], v[54:57]
	v_mfma_f32_16x16x32_bf16 v[26:29], v[204:207], v[170:173], v[26:29]
	v_mfma_f32_16x16x32_bf16 v[22:25], v[218:221], v[170:173], v[22:25]
	v_mfma_f32_16x16x32_bf16 v[4:7], v[204:207], v[178:181], v[4:7]
	v_mfma_f32_16x16x32_bf16 v[0:3], v[218:221], v[178:181], v[0:3]
	v_mfma_f32_16x16x32_bf16 v[30:33], v[204:207], v[146:149], v[30:33]
	v_mfma_f32_16x16x32_bf16 v[38:41], v[218:221], v[146:149], v[38:41]
	v_mfma_f32_16x16x32_bf16 v[46:49], v[204:207], v[158:161], v[46:49]
	v_mfma_f32_16x16x32_bf16 v[50:53], v[218:221], v[158:161], v[50:53]
	s_setprio 0
	s_add_i32 s10, 0, 0x18000
	v_add_u32_e32 v74, s10, v214
	s_barrier
	ds_read_b128 v[54:57], v74
	ds_read_b128 v[58:61], v74 offset:1024
	ds_read_b128 v[70:73], v74 offset:2048
	ds_read_b128 v[74:77], v74 offset:3072
	s_add_u32 s8, s56, 0x20000
	s_addc_u32 s9, s57, 0
	s_mov_b32 m0, s64
	v_lshl_add_u64 v[186:187], s[8:9], 0, v[12:13]
	ds_read_b128 v[142:145], v216 offset:32768
	ds_read_b128 v[146:149], v216 offset:33792
	ds_read_b128 v[154:157], v216 offset:34816
	ds_read_b128 v[158:161], v216 offset:35840
	ds_read_b128 v[166:169], v216 offset:36864
	ds_read_b128 v[170:173], v216 offset:37888
	ds_read_b128 v[174:177], v216 offset:38912
	ds_read_b128 v[178:181], v216 offset:39936
	global_load_lds_dwordx4 v[186:187], off
	s_mov_b32 m0, s65
	v_lshl_add_u64 v[186:187], s[8:9], 0, v[196:197]
	global_load_lds_dwordx4 v[186:187], off
	s_waitcnt lgkmcnt(8)
	s_barrier
	s_waitcnt lgkmcnt(0)
	s_setprio 1
	s_waitcnt lgkmcnt(0)
	v_mfma_f32_16x16x32_bf16 v[162:165], v[54:57], v[142:145], v[162:165]
	v_mfma_f32_16x16x32_bf16 v[150:153], v[70:73], v[142:145], v[150:153]
	v_mfma_f32_16x16x32_bf16 v[130:133], v[54:57], v[154:157], v[130:133]
	v_mfma_f32_16x16x32_bf16 v[126:129], v[70:73], v[154:157], v[126:129]
	v_mfma_f32_16x16x32_bf16 v[114:117], v[54:57], v[166:169], v[114:117]
	v_mfma_f32_16x16x32_bf16 v[110:113], v[70:73], v[166:169], v[110:113]
	v_mfma_f32_16x16x32_bf16 v[98:101], v[54:57], v[174:177], v[98:101]
	v_mfma_f32_16x16x32_bf16 v[94:97], v[70:73], v[174:177], v[94:97]
	v_mfma_f32_16x16x32_bf16 v[162:165], v[58:61], v[146:149], v[162:165]
	v_mfma_f32_16x16x32_bf16 v[150:153], v[74:77], v[146:149], v[150:153]
	v_mfma_f32_16x16x32_bf16 v[130:133], v[58:61], v[158:161], v[130:133]
	v_mfma_f32_16x16x32_bf16 v[126:129], v[74:77], v[158:161], v[126:129]
	v_mfma_f32_16x16x32_bf16 v[114:117], v[58:61], v[170:173], v[114:117]
	v_mfma_f32_16x16x32_bf16 v[110:113], v[74:77], v[170:173], v[110:113]
	v_mfma_f32_16x16x32_bf16 v[98:101], v[58:61], v[178:181], v[98:101]
	v_mfma_f32_16x16x32_bf16 v[94:97], v[74:77], v[178:181], v[94:97]
	s_setprio 0
	s_barrier
	s_add_i32 s11, 0, 0x1c000
	s_add_i32 s8, s10, s62
	v_add_u32_e32 v217, s11, v214
	v_lshl_add_u64 v[212:213], v[212:213], 0, s[36:37]
	s_mov_b32 m0, s8
	ds_read_b128 v[186:189], v217
	ds_read_b128 v[204:207], v217 offset:1024
	ds_read_b128 v[208:211], v217 offset:2048
	ds_read_b128 v[218:221], v217 offset:3072
	global_load_lds_dwordx4 v[212:213], off
	s_add_i32 m0, s8, 0x2000
	v_lshl_add_u64 v[212:213], v[222:223], 0, s[36:37]
	global_load_lds_dwordx4 v[212:213], off
	s_barrier
	s_waitcnt lgkmcnt(0)
	s_setprio 1
	s_waitcnt lgkmcnt(0)
	v_mfma_f32_16x16x32_bf16 v[138:141], v[186:189], v[142:145], v[138:141]
	v_mfma_f32_16x16x32_bf16 v[134:137], v[208:211], v[142:145], v[134:137]
	v_mfma_f32_16x16x32_bf16 v[122:125], v[186:189], v[154:157], v[122:125]
	v_mfma_f32_16x16x32_bf16 v[118:121], v[208:211], v[154:157], v[118:121]
	v_mfma_f32_16x16x32_bf16 v[106:109], v[186:189], v[166:169], v[106:109]
	v_mfma_f32_16x16x32_bf16 v[102:105], v[208:211], v[166:169], v[102:105]
	v_mfma_f32_16x16x32_bf16 v[90:93], v[186:189], v[174:177], v[90:93]
	v_mfma_f32_16x16x32_bf16 v[86:89], v[208:211], v[174:177], v[86:89]
	v_mfma_f32_16x16x32_bf16 v[138:141], v[204:207], v[146:149], v[138:141]
	v_mfma_f32_16x16x32_bf16 v[134:137], v[218:221], v[146:149], v[134:137]
	v_mfma_f32_16x16x32_bf16 v[122:125], v[204:207], v[158:161], v[122:125]
	v_mfma_f32_16x16x32_bf16 v[118:121], v[218:221], v[158:161], v[118:121]
	v_mfma_f32_16x16x32_bf16 v[106:109], v[204:207], v[170:173], v[106:109]
	v_mfma_f32_16x16x32_bf16 v[102:105], v[218:221], v[170:173], v[102:105]
	v_mfma_f32_16x16x32_bf16 v[90:93], v[204:207], v[178:181], v[90:93]
	v_mfma_f32_16x16x32_bf16 v[86:89], v[218:221], v[178:181], v[86:89]
	s_setprio 0
	s_mov_b32 m0, s66
	v_lshl_add_u64 v[212:213], v[236:237], 0, s[36:37]
	s_barrier
	ds_read_b128 v[142:145], v216 offset:49152
	ds_read_b128 v[146:149], v216 offset:50176
	ds_read_b128 v[154:157], v216 offset:51200
	ds_read_b128 v[158:161], v216 offset:52224
	ds_read_b128 v[166:169], v216 offset:53248
	ds_read_b128 v[170:173], v216 offset:54272
	ds_read_b128 v[174:177], v216 offset:55296
	ds_read_b128 v[178:181], v216 offset:56320
	global_load_lds_dwordx4 v[212:213], off
	s_mov_b32 m0, s67
	v_lshl_add_u64 v[212:213], v[238:239], 0, s[36:37]
	global_load_lds_dwordx4 v[212:213], off
	s_barrier
; #define PG8_STAGE(bufoff, gbase, voff) do { _Pragma("unroll") for (int _i = 0; _i < 2; ++_i) \
;         __builtin_amdgcn_global_load_lds((const unsigned*)((const char*)(gbase) + (voff)[_i]), (LAS unsigned*)(lds + (bufoff) + ldsw + _i * 8192), 16, 0, 0); } while (0)
; #define PG8_LDA(dst, b, h) do { _Pragma("unroll") for (int m = 0; m < 4; ++m) _Pragma("unroll") for (int k = 0; k < 2; ++k) dst[m][k] = *(const LAS bf16x8*)(lds + PG8_SA(b, h) + aoff + m * 2048 + k * 1024); } while (0)
; #define PG8_LDB(dst, b, h) do { _Pragma("unroll") for (int n = 0; n < 2; ++n) _Pragma("unroll") for (int k = 0; k < 2; ++k) dst[n][k] = *(const LAS bf16x8*)(lds + PG8_SB(b, h) + boff + n * 2048 + k * 1024); } while (0)
; #define PG8_MMA(ai, bj, At, Bt) do { __builtin_amdgcn_s_setprio(1); _Pragma("unroll") for (int m = 0; m < 4; ++m) _Pragma("unroll") for (int n = 0; n < 2; ++n) _Pragma("unroll") for (int k = 0; k < 2; ++k) \
;         acc[ai][bj][m][n] = __builtin_amdgcn_mfma_f32_16x16x32_bf16(Bt[n][k], At[m][k], acc[ai][bj][m][n], 0, 0, 0); __builtin_amdgcn_s_setprio(0); } while (0)
; #define PG8_WAIT_V(n) asm volatile("s_waitcnt vmcnt(" #n ")" ::: "memory")
; #define PG8_WAIT_L(n) asm volatile("s_waitcnt lgkmcnt(" #n ")" ::: "memory")
; #define PG8_BAR __builtin_amdgcn_s_barrier()
; #define PG8_SCHED __builtin_amdgcn_sched_barrier(0)
; template <class Epi, class Sched>
; __device__ __forceinline__ void gemm_phase(const int TID, LAS unsigned char* lds, const int lda, const int ldb, const Sched& S, const Epi& E) {
;     ...
;             PG8_WAIT_V(6); PG8_BAR; PG8_MMA(1, 1, At, B1); PG8_BAR;
;             PG8_LDB(B0, 1, 0); PG8_SCHED; PG8_LDA(At, 1, 0); PG8_STAGE(PG8_SA(0, 1), a2 + hA, voffA);
;             PG8_WAIT_L(8); PG8_BAR; PG8_WAIT_L(0); PG8_MMA(0, 0, At, B0); PG8_BAR; PG8_SCHED;
;             PG8_LDB(B1, 1, 1); PG8_STAGE(PG8_SB(1, 0), b3, voffB);
;             PG8_BAR; PG8_WAIT_L(0); PG8_MMA(0, 1, At, B1); PG8_BAR;
;             PG8_LDA(At, 1, 1); PG8_STAGE(PG8_SA(1, 0), a3, voffA);
;             PG8_BAR; PG8_WAIT_L(0); PG8_MMA(1, 0, At, B0); PG8_BAR; PG8_SCHED;
;             PG8_STAGE(PG8_SB(1, 1), b3 + hB, voffB);
;             PG8_WAIT_V(6); PG8_BAR; PG8_MMA(1, 1, At, B1); PG8_BAR;
	s_waitcnt lgkmcnt(0)
	s_setprio 1
	s_waitcnt lgkmcnt(0)
	v_mfma_f32_16x16x32_bf16 v[82:85], v[54:57], v[142:145], v[82:85]
	v_mfma_f32_16x16x32_bf16 v[78:81], v[70:73], v[142:145], v[78:81]
	v_mfma_f32_16x16x32_bf16 v[66:69], v[54:57], v[154:157], v[66:69]
	v_mfma_f32_16x16x32_bf16 v[62:65], v[70:73], v[154:157], v[62:65]
	v_mfma_f32_16x16x32_bf16 v[42:45], v[54:57], v[166:169], v[42:45]
	v_mfma_f32_16x16x32_bf16 v[34:37], v[70:73], v[166:169], v[34:37]
	v_mfma_f32_16x16x32_bf16 v[18:21], v[54:57], v[174:177], v[18:21]
	v_mfma_f32_16x16x32_bf16 v[8:11], v[70:73], v[174:177], v[8:11]
	v_mfma_f32_16x16x32_bf16 v[82:85], v[58:61], v[146:149], v[82:85]
	v_mfma_f32_16x16x32_bf16 v[78:81], v[74:77], v[146:149], v[78:81]
	v_mfma_f32_16x16x32_bf16 v[66:69], v[58:61], v[158:161], v[66:69]
	v_mfma_f32_16x16x32_bf16 v[62:65], v[74:77], v[158:161], v[62:65]
	v_mfma_f32_16x16x32_bf16 v[42:45], v[58:61], v[170:173], v[42:45]
	v_mfma_f32_16x16x32_bf16 v[34:37], v[74:77], v[170:173], v[34:37]
	v_mfma_f32_16x16x32_bf16 v[18:21], v[58:61], v[178:181], v[18:21]
	v_mfma_f32_16x16x32_bf16 v[8:11], v[74:77], v[178:181], v[8:11]
	s_setprio 0
	s_barrier
	s_add_u32 s8, s54, 0x20080
	s_addc_u32 s9, s55, 0
	s_add_i32 s10, s11, s62
	s_mov_b32 m0, s10
	v_lshl_add_u64 v[54:55], s[8:9], 0, v[182:183]
	global_load_lds_dwordx4 v[54:55], off
	s_add_i32 m0, s10, 0x2000
	v_lshl_add_u64 v[54:55], s[8:9], 0, v[198:199]
	global_load_lds_dwordx4 v[54:55], off
	s_waitcnt vmcnt(6)
	s_barrier
	s_setprio 1
	v_mfma_f32_16x16x32_bf16 v[30:33], v[186:189], v[142:145], v[30:33]
	v_mfma_f32_16x16x32_bf16 v[74:77], v[204:207], v[146:149], v[30:33]
	v_mfma_f32_16x16x32_bf16 v[30:33], v[208:211], v[142:145], v[38:41]
	v_mfma_f32_16x16x32_bf16 v[70:73], v[218:221], v[146:149], v[30:33]
	v_mfma_f32_16x16x32_bf16 v[30:33], v[186:189], v[154:157], v[46:49]
	v_mfma_f32_16x16x32_bf16 v[58:61], v[204:207], v[158:161], v[30:33]
	v_mfma_f32_16x16x32_bf16 v[30:33], v[208:211], v[154:157], v[50:53]
	v_mfma_f32_16x16x32_bf16 v[26:29], v[186:189], v[166:169], v[26:29]
	v_mfma_f32_16x16x32_bf16 v[22:25], v[208:211], v[166:169], v[22:25]
	v_mfma_f32_16x16x32_bf16 v[4:7], v[186:189], v[174:177], v[4:7]
	v_mfma_f32_16x16x32_bf16 v[0:3], v[208:211], v[174:177], v[0:3]
	v_mfma_f32_16x16x32_bf16 v[54:57], v[218:221], v[158:161], v[30:33]
	v_mfma_f32_16x16x32_bf16 v[26:29], v[204:207], v[170:173], v[26:29]
	v_mfma_f32_16x16x32_bf16 v[22:25], v[218:221], v[170:173], v[22:25]
	v_mfma_f32_16x16x32_bf16 v[4:7], v[204:207], v[178:181], v[4:7]
	v_mfma_f32_16x16x32_bf16 v[0:3], v[218:221], v[178:181], v[0:3]
	s_setprio 0
	s_add_i32 s49, s49, 2
	s_add_u32 s23, s23, 0x100
	s_addc_u32 s47, s47, 0
	s_add_u32 s28, s28, 0x100
	s_addc_u32 s29, s29, 0
	s_cmp_gt_u32 s49, 5
	s_barrier
	s_cbranch_scc0 .LBB0_295
	v_lshl_add_u32 v206, s2, 8, v195
	v_lshl_or_b32 v142, s21, 8, v215
	v_ashrrev_i32_e32 v207, 31, v206
	v_ashrrev_i32_e32 v143, 31, v142
	v_lshlrev_b64 v[144:145], 10, v[206:207]
	v_lshl_add_u64 v[144:145], s[0:1], 0, v[144:145]
	v_lshlrev_b64 v[204:205], 1, v[142:143]
	v_lshl_add_u64 v[38:39], v[142:143], 2, s[44:45]
	v_mov_b64_e32 v[208:209], s[40:41]
	v_lshl_add_u64 v[142:143], v[144:145], 0, v[204:205]
	global_load_dwordx4 v[46:49], v[38:39], off offset:16
	global_load_dwordx4 v[50:53], v[38:39], off
	global_load_dwordx4 v[30:33], v[38:39], off offset:528
	s_nop 0
	global_load_dwordx4 v[38:41], v[38:39], off offset:512
	v_mad_i64_i32 v[146:147], s[8:9], v206, s4, v[208:209]
	flat_load_dwordx4 v[174:177], v[142:143]
	v_lshl_add_u64 v[144:145], v[146:147], 0, v[204:205]
	flat_load_dwordx4 v[178:181], v[144:145] offset:1024
	flat_load_dwordx4 v[166:169], v[142:143] offset:256
	flat_load_dwordx4 v[170:173], v[144:145] offset:1280
	v_or_b32_e32 v210, 16, v206
	v_ashrrev_i32_e32 v211, 31, v210
	v_lshlrev_b64 v[142:143], 10, v[210:211]
	v_lshl_add_u64 v[142:143], s[0:1], 0, v[142:143]
	v_lshl_add_u64 v[142:143], v[142:143], 0, v[204:205]
	v_mad_i64_i32 v[144:145], s[8:9], v210, s4, v[208:209]
	flat_load_dwordx4 v[154:157], v[142:143]
	v_lshl_add_u64 v[146:147], v[144:145], 0, v[204:205]
	flat_load_dwordx4 v[158:161], v[146:147] offset:1024
	s_nop 0
	flat_load_dwordx4 v[142:145], v[142:143] offset:256
	s_nop 0
	flat_load_dwordx4 v[146:149], v[146:147] offset:1280
	v_lshlrev_b64 v[212:213], 12, v[206:207]
	s_and_b64 vcc, exec, s[38:39]
	s_mov_b32 s21, s46
	s_mov_b32 s2, s48
	s_mov_b64 s[54:55], s[52:53]
	s_mov_b64 s[28:29], s[50:51]
	s_waitcnt vmcnt(0)
	v_add_f32_e32 v150, v150, v46
	v_add_f32_e32 v162, v162, v50
	v_mul_f32_e32 v162, 0xbfb8aa3b, v162
	v_add_f32_e32 v163, v163, v51
	v_mul_f32_e32 v163, 0xbfb8aa3b, v163
	v_add_f32_e32 v164, v164, v52
	s_waitcnt lgkmcnt(0)
; __device__ __forceinline__ float glu2(float z, float a, float g) { return z * g * __builtin_amdgcn_rcpf((1.0f + __expf(-a)) * (1.0f + __expf(-g))); }
	v_lshlrev_b32_e32 v186, 16, v174
	v_lshlrev_b32_e32 v187, 16, v178
	v_mul_f32_e32 v188, v187, v186
	v_exp_f32_e32 v186, v162
	v_mul_f32_e32 v162, 0xbfb8aa3b, v187
	v_exp_f32_e32 v187, v162
	v_and_b32_e32 v178, 0xffff0000, v178
	v_and_b32_e32 v174, 0xffff0000, v174
	v_mul_f32_e32 v174, v178, v174
	v_pk_add_f32 v[186:187], v[186:187], 1.0 op_sel_hi:[1,0]
	v_mul_f32_e32 v164, 0xbfb8aa3b, v164
	v_mul_f32_e32 v162, v186, v187
	v_exp_f32_e32 v186, v163
	v_mul_f32_e32 v163, 0xbfb8aa3b, v178
	v_exp_f32_e32 v187, v163
	v_lshlrev_b32_e32 v178, 16, v179
	v_mul_f32_e32 v150, 0xbfb8aa3b, v150
	v_rcp_f32_e32 v162, v162
	v_pk_add_f32 v[186:187], v[186:187], 1.0 op_sel_hi:[1,0]
	v_add_f32_e32 v138, v138, v38
	v_mul_f32_e32 v163, v186, v187
	v_exp_f32_e32 v186, v164
	v_mul_f32_e32 v164, 0xbfb8aa3b, v178
	v_exp_f32_e32 v187, v164
	v_rcp_f32_e32 v163, v163
	v_mul_f32_e32 v162, v188, v162
	v_mul_f32_e32 v138, 0xbfb8aa3b, v138
	v_pk_add_f32 v[186:187], v[186:187], 1.0 op_sel_hi:[1,0]
	v_mul_f32_e32 v163, v174, v163
	v_mul_f32_e32 v164, v186, v187
	v_rcp_f32_e32 v164, v164
	v_lshlrev_b32_e32 v174, 16, v175
	v_mul_f32_e32 v174, v178, v174
	v_and_b32_e32 v175, 0xffff0000, v175
	v_mul_f32_e32 v174, v174, v164
	v_add_f32_e32 v164, v165, v53
	v_and_b32_e32 v165, 0xffff0000, v179
	v_mul_f32_e32 v175, v165, v175
	v_mul_f32_e32 v164, 0xbfb8aa3b, v164
	v_mul_f32_e32 v165, 0xbfb8aa3b, v165
	v_exp_f32_e32 v164, v164
	v_exp_f32_e32 v165, v165
	v_cvt_pk_bf16_f32 v162, v162, v163
	v_add_f32_e32 v134, v134, v30
	v_mul_f32_e32 v134, 0xbfb8aa3b, v134
	v_pk_add_f32 v[164:165], v[164:165], 1.0 op_sel_hi:[1,0]
	v_add_f32_e32 v130, v130, v50
	v_mul_f32_e32 v164, v164, v165
	v_rcp_f32_e32 v164, v164
	v_lshlrev_b32_e32 v165, 16, v180
	v_mul_f32_e32 v130, 0xbfb8aa3b, v130
	v_add_f32_e32 v126, v126, v46
	v_mul_f32_e32 v175, v175, v164
	v_lshlrev_b32_e32 v164, 16, v176
	v_mul_f32_e32 v178, v165, v164
	v_exp_f32_e32 v164, v150
	v_mul_f32_e32 v150, 0xbfb8aa3b, v165
	v_exp_f32_e32 v165, v150
	v_cvt_pk_bf16_f32 v163, v174, v175
	v_mul_f32_e32 v126, 0xbfb8aa3b, v126
	v_add_f32_e32 v122, v122, v38
	v_pk_add_f32 v[164:165], v[164:165], 1.0 op_sel_hi:[1,0]
	v_mul_f32_e32 v122, 0xbfb8aa3b, v122
	v_mul_f32_e32 v150, v164, v165
	v_rcp_f32_e32 v150, v150
	v_and_b32_e32 v165, 0xffff0000, v176
	v_add_f32_e32 v118, v118, v30
	v_mul_f32_e32 v118, 0xbfb8aa3b, v118
	v_mul_f32_e32 v164, v178, v150
	v_add_f32_e32 v150, v151, v47
	v_and_b32_e32 v151, 0xffff0000, v180
	v_mul_f32_e32 v165, v151, v165
	v_mul_f32_e32 v150, 0xbfb8aa3b, v150
	v_mul_f32_e32 v151, 0xbfb8aa3b, v151
	v_exp_f32_e32 v150, v150
	v_exp_f32_e32 v151, v151
	v_add_f32_e32 v114, v114, v50
	v_mul_f32_e32 v114, 0xbfb8aa3b, v114
	v_add_f32_e32 v110, v110, v46
	v_pk_add_f32 v[150:151], v[150:151], 1.0 op_sel_hi:[1,0]
	v_mul_f32_e32 v110, 0xbfb8aa3b, v110
	v_mul_f32_e32 v150, v150, v151
	v_rcp_f32_e32 v150, v150
	v_lshlrev_b32_e32 v151, 16, v177
	v_add_f32_e32 v106, v106, v38
	v_mul_f32_e32 v106, 0xbfb8aa3b, v106
	v_mul_f32_e32 v165, v165, v150
	v_add_f32_e32 v150, v152, v48
	v_lshlrev_b32_e32 v152, 16, v181
	v_mul_f32_e32 v176, v152, v151
	v_mul_f32_e32 v150, 0xbfb8aa3b, v150
	v_mul_f32_e32 v151, 0xbfb8aa3b, v152
	v_exp_f32_e32 v150, v150
	v_exp_f32_e32 v151, v151
	v_cvt_pk_bf16_f32 v164, v164, v165
	v_add_f32_e32 v102, v102, v30
	v_mul_f32_e32 v102, 0xbfb8aa3b, v102
	v_pk_add_f32 v[150:151], v[150:151], 1.0 op_sel_hi:[1,0]
	v_add_f32_e32 v98, v98, v50
	v_mul_f32_e32 v150, v150, v151
	v_rcp_f32_e32 v150, v150
	v_and_b32_e32 v151, 0xffff0000, v181
	v_mul_f32_e32 v98, 0xbfb8aa3b, v98
	v_add_f32_e32 v94, v94, v46
	v_mul_f32_e32 v152, v176, v150
	v_add_f32_e32 v150, v153, v49
	v_and_b32_e32 v153, 0xffff0000, v177
	v_mul_f32_e32 v153, v151, v153
	v_mul_f32_e32 v150, 0xbfb8aa3b, v150
	v_mul_f32_e32 v151, 0xbfb8aa3b, v151
	v_exp_f32_e32 v150, v150
	v_exp_f32_e32 v151, v151
	v_mul_f32_e32 v94, 0xbfb8aa3b, v94
	v_add_f32_e32 v90, v90, v38
	v_mul_f32_e32 v90, 0xbfb8aa3b, v90
	v_pk_add_f32 v[150:151], v[150:151], 1.0 op_sel_hi:[1,0]
	v_add_f32_e32 v86, v86, v30
	v_mul_f32_e32 v150, v150, v151
	v_rcp_f32_e32 v150, v150
	v_mul_f32_e32 v86, 0xbfb8aa3b, v86
	v_add_f32_e32 v82, v82, v50
	v_mul_f32_e32 v82, 0xbfb8aa3b, v82
	v_mul_f32_e32 v150, v153, v150
	v_cvt_pk_bf16_f32 v165, v152, v150
	v_lshl_add_u64 v[150:151], s[42:43], 0, v[212:213]
	v_lshl_add_u64 v[150:151], v[150:151], 0, v[204:205]
	v_lshlrev_b32_e32 v152, 16, v166
	v_lshlrev_b32_e32 v153, 16, v170
	flat_store_dwordx4 v[150:151], v[162:165]
	v_add_f32_e32 v78, v78, v46
	v_mul_f32_e32 v78, 0xbfb8aa3b, v78
	v_mul_f32_e32 v162, v153, v152
	v_exp_f32_e32 v152, v138
	v_mul_f32_e32 v138, 0xbfb8aa3b, v153
	v_exp_f32_e32 v153, v138
	v_add_f32_e32 v74, v74, v38
	v_mul_f32_e32 v74, 0xbfb8aa3b, v74
	v_add_f32_e32 v70, v70, v30
	v_pk_add_f32 v[152:153], v[152:153], 1.0 op_sel_hi:[1,0]
	v_mul_f32_e32 v70, 0xbfb8aa3b, v70
	v_mul_f32_e32 v138, v152, v153
	v_rcp_f32_e32 v138, v138
	v_and_b32_e32 v153, 0xffff0000, v166
	v_or_b32_e32 v166, 32, v206
	v_add_f32_e32 v66, v66, v50
	v_mul_f32_e32 v152, v162, v138
	v_add_f32_e32 v138, v139, v39
	v_and_b32_e32 v139, 0xffff0000, v170
	v_mul_f32_e32 v153, v139, v153
	v_mul_f32_e32 v138, 0xbfb8aa3b, v138
	v_mul_f32_e32 v139, 0xbfb8aa3b, v139
	v_exp_f32_e32 v138, v138
	v_exp_f32_e32 v139, v139
	v_lshlrev_b32_e32 v170, 16, v154
	v_and_b32_e32 v154, 0xffff0000, v154
	v_mul_f32_e32 v66, 0xbfb8aa3b, v66
	v_pk_add_f32 v[138:139], v[138:139], 1.0 op_sel_hi:[1,0]
	v_add_f32_e32 v62, v62, v46
	v_mul_f32_e32 v138, v138, v139
	v_rcp_f32_e32 v138, v138
	v_lshlrev_b32_e32 v139, 16, v167
	v_mul_f32_e32 v62, 0xbfb8aa3b, v62
	v_add_f32_e32 v58, v58, v38
	v_mul_f32_e32 v153, v153, v138
; __device__ __forceinline__ float glu2(float z, float a, float g) { return z * g * __builtin_amdgcn_rcpf((1.0f + __expf(-a)) * (1.0f + __expf(-g))); }
	v_add_f32_e32 v138, v140, v40
	v_lshlrev_b32_e32 v140, 16, v171
	v_mul_f32_e32 v162, v140, v139
	v_mul_f32_e32 v138, 0xbfb8aa3b, v138
	v_mul_f32_e32 v139, 0xbfb8aa3b, v140
	v_exp_f32_e32 v138, v138
	v_exp_f32_e32 v139, v139
	v_mul_f32_e32 v58, 0xbfb8aa3b, v58
	v_add_f32_e32 v54, v54, v30
	v_mul_f32_e32 v54, 0xbfb8aa3b, v54
	v_pk_add_f32 v[138:139], v[138:139], 1.0 op_sel_hi:[1,0]
	v_add_f32_e32 v42, v42, v50
	v_mul_f32_e32 v138, v138, v139
	v_rcp_f32_e32 v138, v138
	v_and_b32_e32 v139, 0xffff0000, v171
	v_lshlrev_b32_e32 v171, 16, v158
	v_mul_f32_e32 v42, 0xbfb8aa3b, v42
	v_mul_f32_e32 v140, v162, v138
	v_add_f32_e32 v138, v141, v41
	v_and_b32_e32 v141, 0xffff0000, v167
	v_mul_f32_e32 v141, v139, v141
	v_mul_f32_e32 v138, 0xbfb8aa3b, v138
	v_mul_f32_e32 v139, 0xbfb8aa3b, v139
	v_exp_f32_e32 v138, v138
	v_exp_f32_e32 v139, v139
	v_ashrrev_i32_e32 v167, 31, v166
	v_add_f32_e32 v34, v34, v46
	v_mul_f32_e32 v34, 0xbfb8aa3b, v34
	v_pk_add_f32 v[138:139], v[138:139], 1.0 op_sel_hi:[1,0]
	v_add_f32_e32 v26, v26, v38
	v_mul_f32_e32 v138, v138, v139
	v_rcp_f32_e32 v138, v138
	v_lshlrev_b32_e32 v139, 16, v172
	v_mul_f32_e32 v26, 0xbfb8aa3b, v26
	v_add_f32_e32 v22, v22, v30
	v_mul_f32_e32 v141, v141, v138
	v_lshlrev_b32_e32 v138, 16, v168
	v_mul_f32_e32 v162, v139, v138
	v_exp_f32_e32 v138, v134
	v_mul_f32_e32 v134, 0xbfb8aa3b, v139
	v_exp_f32_e32 v139, v134
	v_mul_f32_e32 v22, 0xbfb8aa3b, v22
	v_add_f32_e32 v18, v18, v50
	v_mul_f32_e32 v18, 0xbfb8aa3b, v18
	v_pk_add_f32 v[138:139], v[138:139], 1.0 op_sel_hi:[1,0]
	v_add_f32_e32 v8, v8, v46
	v_mul_f32_e32 v134, v138, v139
	v_rcp_f32_e32 v134, v134
	v_and_b32_e32 v139, 0xffff0000, v168
	v_mul_f32_e32 v8, 0xbfb8aa3b, v8
	v_add_f32_e32 v4, v4, v38
	v_mul_f32_e32 v138, v162, v134
	v_add_f32_e32 v134, v135, v31
	v_and_b32_e32 v135, 0xffff0000, v172
	v_mul_f32_e32 v172, v171, v170
	v_exp_f32_e32 v170, v130
	v_mul_f32_e32 v130, 0xbfb8aa3b, v171
	v_exp_f32_e32 v171, v130
	v_mul_f32_e32 v139, v135, v139
	v_mul_f32_e32 v134, 0xbfb8aa3b, v134
	v_mul_f32_e32 v135, 0xbfb8aa3b, v135
	v_pk_add_f32 v[170:171], v[170:171], 1.0 op_sel_hi:[1,0]
	v_exp_f32_e32 v134, v134
	v_mul_f32_e32 v130, v170, v171
	v_rcp_f32_e32 v130, v130
	v_exp_f32_e32 v135, v135
	v_mul_f32_e32 v4, 0xbfb8aa3b, v4
	v_add_f32_e32 v0, v0, v30
	v_mul_f32_e32 v170, v172, v130
	v_add_f32_e32 v130, v131, v51
	v_and_b32_e32 v131, 0xffff0000, v158
	v_mul_f32_e32 v154, v131, v154
	v_mul_f32_e32 v130, 0xbfb8aa3b, v130
	v_mul_f32_e32 v131, 0xbfb8aa3b, v131
	v_exp_f32_e32 v130, v130
	v_exp_f32_e32 v131, v131
	v_pk_add_f32 v[134:135], v[134:135], 1.0 op_sel_hi:[1,0]
	v_mul_f32_e32 v0, 0xbfb8aa3b, v0
	v_mul_f32_e32 v134, v134, v135
	v_pk_add_f32 v[130:131], v[130:131], 1.0 op_sel_hi:[1,0]
	v_rcp_f32_e32 v134, v134
	v_mul_f32_e32 v130, v130, v131
	v_rcp_f32_e32 v130, v130
	v_lshlrev_b32_e32 v131, 16, v155
	v_mul_f32_e32 v139, v139, v134
	v_add_f32_e32 v134, v136, v32
	v_mul_f32_e32 v154, v154, v130
	v_add_f32_e32 v130, v132, v52
	v_lshlrev_b32_e32 v132, 16, v159
	v_mul_f32_e32 v158, v132, v131
	v_mul_f32_e32 v130, 0xbfb8aa3b, v130
	v_mul_f32_e32 v131, 0xbfb8aa3b, v132
	v_exp_f32_e32 v130, v130
	v_exp_f32_e32 v131, v131
	v_lshlrev_b32_e32 v135, 16, v169
	v_lshlrev_b32_e32 v136, 16, v173
	v_mul_f32_e32 v162, v136, v135
	v_pk_add_f32 v[130:131], v[130:131], 1.0 op_sel_hi:[1,0]
	v_mul_f32_e32 v134, 0xbfb8aa3b, v134
	v_mul_f32_e32 v130, v130, v131
	v_rcp_f32_e32 v130, v130
	v_and_b32_e32 v131, 0xffff0000, v159
	v_mul_f32_e32 v135, 0xbfb8aa3b, v136
	v_exp_f32_e32 v134, v134
	v_mul_f32_e32 v132, v158, v130
	v_add_f32_e32 v130, v133, v53
	v_and_b32_e32 v133, 0xffff0000, v155
	v_mul_f32_e32 v133, v131, v133
	v_mul_f32_e32 v130, 0xbfb8aa3b, v130
	v_mul_f32_e32 v131, 0xbfb8aa3b, v131
	v_exp_f32_e32 v130, v130
	v_exp_f32_e32 v131, v131
	v_exp_f32_e32 v135, v135
	v_and_b32_e32 v136, 0xffff0000, v169
	v_lshlrev_b64 v[168:169], 12, v[210:211]
	v_pk_add_f32 v[130:131], v[130:131], 1.0 op_sel_hi:[1,0]
	v_pk_add_f32 v[134:135], v[134:135], 1.0 op_sel_hi:[1,0]
	v_mul_f32_e32 v130, v130, v131
	v_rcp_f32_e32 v130, v130
	v_lshlrev_b32_e32 v131, 16, v160
	v_mul_f32_e32 v134, v134, v135
	v_rcp_f32_e32 v134, v134
	v_mul_f32_e32 v133, v133, v130
	v_lshlrev_b32_e32 v130, 16, v156
	v_mul_f32_e32 v155, v131, v130
	v_exp_f32_e32 v130, v126
	v_mul_f32_e32 v126, 0xbfb8aa3b, v131
	v_exp_f32_e32 v131, v126
	v_mul_f32_e32 v162, v162, v134
	v_add_f32_e32 v134, v137, v33
	v_and_b32_e32 v135, 0xffff0000, v173
	v_pk_add_f32 v[130:131], v[130:131], 1.0 op_sel_hi:[1,0]
	v_mul_f32_e32 v136, v135, v136
	v_mul_f32_e32 v126, v130, v131
	v_rcp_f32_e32 v126, v126
	v_and_b32_e32 v131, 0xffff0000, v156
	v_mul_f32_e32 v134, 0xbfb8aa3b, v134
	v_mul_f32_e32 v135, 0xbfb8aa3b, v135
	v_mul_f32_e32 v130, v155, v126
	v_add_f32_e32 v126, v127, v47
	v_and_b32_e32 v127, 0xffff0000, v160
	v_mul_f32_e32 v131, v127, v131
	v_mul_f32_e32 v126, 0xbfb8aa3b, v126
	v_mul_f32_e32 v127, 0xbfb8aa3b, v127
	v_exp_f32_e32 v126, v126
	v_exp_f32_e32 v127, v127
	v_exp_f32_e32 v134, v134
	v_exp_f32_e32 v135, v135
	v_pk_add_f32 v[126:127], v[126:127], 1.0 op_sel_hi:[1,0]
	s_nop 0
	v_mul_f32_e32 v126, v126, v127
	v_pk_add_f32 v[134:135], v[134:135], 1.0 op_sel_hi:[1,0]
	v_rcp_f32_e32 v126, v126
	v_mul_f32_e32 v134, v134, v135
	v_rcp_f32_e32 v134, v134
	v_lshlrev_b32_e32 v127, 16, v157
	v_mul_f32_e32 v131, v131, v126
	v_add_f32_e32 v126, v128, v48
	v_lshlrev_b32_e32 v128, 16, v161
	v_mul_f32_e32 v155, v128, v127
	v_mul_f32_e32 v126, 0xbfb8aa3b, v126
	v_mul_f32_e32 v127, 0xbfb8aa3b, v128
	v_mul_f32_e32 v137, v136, v134
	v_cvt_pk_bf16_f32 v134, v152, v153
	v_cvt_pk_bf16_f32 v135, v140, v141
	v_exp_f32_e32 v126, v126
	v_exp_f32_e32 v127, v127
; __device__ __forceinline__ float glu2(float z, float a, float g) { return z * g * __builtin_amdgcn_rcpf((1.0f + __expf(-a)) * (1.0f + __expf(-g))); }
	v_cvt_pk_bf16_f32 v136, v138, v139
	v_cvt_pk_bf16_f32 v137, v162, v137
	flat_store_dwordx4 v[150:151], v[134:137] offset:256
	v_pk_add_f32 v[126:127], v[126:127], 1.0 op_sel_hi:[1,0]
	v_and_b32_e32 v128, 0xffff0000, v157
	v_lshlrev_b64 v[134:135], 10, v[166:167]
	v_lshl_add_u64 v[134:135], s[0:1], 0, v[134:135]
	v_lshl_add_u64 v[134:135], v[134:135], 0, v[204:205]
	v_mad_i64_i32 v[136:137], s[8:9], v166, s4, v[208:209]
	flat_load_dwordx4 v[150:153], v[134:135]
	v_lshl_add_u64 v[138:139], v[136:137], 0, v[204:205]
	v_mul_f32_e32 v126, v126, v127
	flat_load_dwordx4 v[162:165], v[138:139] offset:1024
	s_nop 0
	flat_load_dwordx4 v[134:137], v[134:135] offset:256
	s_nop 0
	flat_load_dwordx4 v[138:141], v[138:139] offset:1280
	v_rcp_f32_e32 v126, v126
	v_and_b32_e32 v127, 0xffff0000, v161
	v_mul_f32_e32 v128, v127, v128
	v_mul_f32_e32 v127, 0xbfb8aa3b, v127
	v_mul_f32_e32 v155, v155, v126
	v_add_f32_e32 v126, v129, v49
	v_mul_f32_e32 v126, 0xbfb8aa3b, v126
	v_exp_f32_e32 v126, v126
	v_exp_f32_e32 v127, v127
	s_nop 0
	v_pk_add_f32 v[126:127], v[126:127], 1.0 op_sel_hi:[1,0]
	s_nop 0
	v_mul_f32_e32 v126, v126, v127
	v_rcp_f32_e32 v126, v126
	s_nop 0
	v_mul_f32_e32 v126, v128, v126
	v_cvt_pk_bf16_f32 v128, v170, v154
	v_cvt_pk_bf16_f32 v129, v132, v133
	v_cvt_pk_bf16_f32 v130, v130, v131
	v_cvt_pk_bf16_f32 v131, v155, v126
	v_lshl_add_u64 v[126:127], s[42:43], 0, v[168:169]
	v_lshl_add_u64 v[126:127], v[126:127], 0, v[204:205]
	flat_store_dwordx4 v[126:127], v[128:131]
	s_nop 1
	v_lshlrev_b32_e32 v128, 16, v142
	v_lshlrev_b32_e32 v129, 16, v146
	v_mul_f32_e32 v130, v129, v128
	v_exp_f32_e32 v128, v122
	v_mul_f32_e32 v122, 0xbfb8aa3b, v129
	v_exp_f32_e32 v129, v122
	s_nop 0
	v_pk_add_f32 v[128:129], v[128:129], 1.0 op_sel_hi:[1,0]
	s_nop 0
	v_mul_f32_e32 v122, v128, v129
	v_rcp_f32_e32 v122, v122
	v_and_b32_e32 v129, 0xffff0000, v142
	v_or_b32_e32 v142, 48, v206
	v_mul_f32_e32 v128, v130, v122
	v_add_f32_e32 v122, v123, v39
	v_and_b32_e32 v123, 0xffff0000, v146
	v_mul_f32_e32 v129, v123, v129
	v_mul_f32_e32 v122, 0xbfb8aa3b, v122
	v_mul_f32_e32 v123, 0xbfb8aa3b, v123
	v_exp_f32_e32 v122, v122
	v_exp_f32_e32 v123, v123
	s_waitcnt vmcnt(0) lgkmcnt(0)
	v_lshlrev_b32_e32 v146, 16, v150
	v_pk_add_f32 v[122:123], v[122:123], 1.0 op_sel_hi:[1,0]
	s_nop 0
	v_mul_f32_e32 v122, v122, v123
	v_rcp_f32_e32 v122, v122
	v_lshlrev_b32_e32 v123, 16, v143
	v_mul_f32_e32 v129, v129, v122
	v_add_f32_e32 v122, v124, v40
	v_lshlrev_b32_e32 v124, 16, v147
	v_mul_f32_e32 v130, v124, v123
	v_mul_f32_e32 v122, 0xbfb8aa3b, v122
	v_mul_f32_e32 v123, 0xbfb8aa3b, v124
	v_exp_f32_e32 v122, v122
	v_exp_f32_e32 v123, v123
	s_nop 0
	v_pk_add_f32 v[122:123], v[122:123], 1.0 op_sel_hi:[1,0]
	s_nop 0
	v_mul_f32_e32 v122, v122, v123
	v_rcp_f32_e32 v122, v122
	v_and_b32_e32 v123, 0xffff0000, v147
	v_lshlrev_b32_e32 v147, 16, v162
	v_mul_f32_e32 v124, v130, v122
	v_add_f32_e32 v122, v125, v41
	v_and_b32_e32 v125, 0xffff0000, v143
	v_mul_f32_e32 v125, v123, v125
	v_mul_f32_e32 v122, 0xbfb8aa3b, v122
	v_mul_f32_e32 v123, 0xbfb8aa3b, v123
	v_exp_f32_e32 v122, v122
	v_exp_f32_e32 v123, v123
	v_ashrrev_i32_e32 v143, 31, v142
	v_pk_add_f32 v[122:123], v[122:123], 1.0 op_sel_hi:[1,0]
	s_nop 0
	v_mul_f32_e32 v122, v122, v123
	v_rcp_f32_e32 v122, v122
	v_lshlrev_b32_e32 v123, 16, v148
	v_mul_f32_e32 v125, v125, v122
	v_lshlrev_b32_e32 v122, 16, v144
	v_mul_f32_e32 v130, v123, v122
	v_exp_f32_e32 v122, v118
	v_mul_f32_e32 v118, 0xbfb8aa3b, v123
	v_exp_f32_e32 v123, v118
	s_nop 0
	v_pk_add_f32 v[122:123], v[122:123], 1.0 op_sel_hi:[1,0]
	s_nop 0
	v_mul_f32_e32 v118, v122, v123
	v_rcp_f32_e32 v118, v118
	v_and_b32_e32 v123, 0xffff0000, v144
	v_mul_f32_e32 v122, v130, v118
	v_add_f32_e32 v118, v119, v31
	v_and_b32_e32 v119, 0xffff0000, v148
	v_mul_f32_e32 v148, v147, v146
	v_exp_f32_e32 v146, v114
	v_mul_f32_e32 v114, 0xbfb8aa3b, v147
	v_exp_f32_e32 v147, v114
	v_mul_f32_e32 v123, v119, v123
	v_mul_f32_e32 v118, 0xbfb8aa3b, v118
	v_mul_f32_e32 v119, 0xbfb8aa3b, v119
	v_pk_add_f32 v[146:147], v[146:147], 1.0 op_sel_hi:[1,0]
	v_exp_f32_e32 v118, v118
	v_mul_f32_e32 v114, v146, v147
	v_rcp_f32_e32 v114, v114
	v_and_b32_e32 v147, 0xffff0000, v150
	v_exp_f32_e32 v119, v119
	v_mul_f32_e32 v146, v148, v114
	v_add_f32_e32 v114, v115, v51
	v_and_b32_e32 v115, 0xffff0000, v162
	v_mul_f32_e32 v147, v115, v147
	v_mul_f32_e32 v114, 0xbfb8aa3b, v114
	v_mul_f32_e32 v115, 0xbfb8aa3b, v115
	v_exp_f32_e32 v114, v114
	v_exp_f32_e32 v115, v115
	v_pk_add_f32 v[118:119], v[118:119], 1.0 op_sel_hi:[1,0]
	v_pk_add_f32 v[114:115], v[114:115], 1.0 op_sel_hi:[1,0]
	s_nop 0
	v_mul_f32_e32 v114, v114, v115
	v_rcp_f32_e32 v114, v114
	v_lshlrev_b32_e32 v115, 16, v151
	v_mul_f32_e32 v118, v118, v119
	v_rcp_f32_e32 v118, v118
	v_mul_f32_e32 v147, v147, v114
	v_add_f32_e32 v114, v116, v52
	v_lshlrev_b32_e32 v116, 16, v163
	v_mul_f32_e32 v148, v116, v115
	v_mul_f32_e32 v114, 0xbfb8aa3b, v114
	v_mul_f32_e32 v115, 0xbfb8aa3b, v116
	v_exp_f32_e32 v114, v114
	v_exp_f32_e32 v115, v115
	v_mul_f32_e32 v123, v123, v118
	v_add_f32_e32 v118, v120, v32
	v_lshlrev_b32_e32 v119, 16, v145
	v_pk_add_f32 v[114:115], v[114:115], 1.0 op_sel_hi:[1,0]
	v_lshlrev_b32_e32 v120, 16, v149
	v_mul_f32_e32 v114, v114, v115
	v_rcp_f32_e32 v114, v114
	v_and_b32_e32 v115, 0xffff0000, v163
	v_mul_f32_e32 v130, v120, v119
	v_mul_f32_e32 v118, 0xbfb8aa3b, v118
	v_mul_f32_e32 v116, v148, v114
	v_add_f32_e32 v114, v117, v53
	v_and_b32_e32 v117, 0xffff0000, v151
	v_mul_f32_e32 v117, v115, v117
	v_mul_f32_e32 v114, 0xbfb8aa3b, v114
	v_mul_f32_e32 v115, 0xbfb8aa3b, v115
	v_exp_f32_e32 v114, v114
	v_exp_f32_e32 v115, v115
	v_mul_f32_e32 v119, 0xbfb8aa3b, v120
; __device__ __forceinline__ float glu2(float z, float a, float g) { return z * g * __builtin_amdgcn_rcpf((1.0f + __expf(-a)) * (1.0f + __expf(-g))); }
	v_exp_f32_e32 v118, v118
	v_exp_f32_e32 v119, v119
	v_pk_add_f32 v[114:115], v[114:115], 1.0 op_sel_hi:[1,0]
	v_and_b32_e32 v120, 0xffff0000, v145
	v_mul_f32_e32 v114, v114, v115
	v_rcp_f32_e32 v114, v114
	v_lshlrev_b32_e32 v115, 16, v164
	v_pk_add_f32 v[118:119], v[118:119], 1.0 op_sel_hi:[1,0]
	v_lshlrev_b64 v[144:145], 12, v[166:167]
	v_mul_f32_e32 v117, v117, v114
	v_lshlrev_b32_e32 v114, 16, v152
	v_mul_f32_e32 v148, v115, v114
	v_exp_f32_e32 v114, v110
	v_mul_f32_e32 v110, 0xbfb8aa3b, v115
	v_exp_f32_e32 v115, v110
	v_mul_f32_e32 v118, v118, v119
	v_rcp_f32_e32 v118, v118
	v_and_b32_e32 v119, 0xffff0000, v149
	v_pk_add_f32 v[114:115], v[114:115], 1.0 op_sel_hi:[1,0]
	v_mul_f32_e32 v120, v119, v120
	v_mul_f32_e32 v110, v114, v115
	v_rcp_f32_e32 v110, v110
	v_and_b32_e32 v115, 0xffff0000, v152
	v_mul_f32_e32 v130, v130, v118
	v_add_f32_e32 v118, v121, v33
	v_mul_f32_e32 v114, v148, v110
	v_add_f32_e32 v110, v111, v47
	v_and_b32_e32 v111, 0xffff0000, v164
	v_mul_f32_e32 v115, v111, v115
	v_mul_f32_e32 v110, 0xbfb8aa3b, v110
	v_mul_f32_e32 v111, 0xbfb8aa3b, v111
	v_exp_f32_e32 v110, v110
	v_exp_f32_e32 v111, v111
	v_mul_f32_e32 v118, 0xbfb8aa3b, v118
	v_mul_f32_e32 v119, 0xbfb8aa3b, v119
	v_exp_f32_e32 v118, v118
	v_exp_f32_e32 v119, v119
	v_pk_add_f32 v[110:111], v[110:111], 1.0 op_sel_hi:[1,0]
	v_pk_add_f32 v[118:119], v[118:119], 1.0 op_sel_hi:[1,0]
	v_mul_f32_e32 v110, v110, v111
	v_rcp_f32_e32 v110, v110
	v_mul_f32_e32 v118, v118, v119
	v_rcp_f32_e32 v118, v118
	v_lshlrev_b32_e32 v111, 16, v153
	v_mul_f32_e32 v115, v115, v110
	v_add_f32_e32 v110, v112, v48
	v_lshlrev_b32_e32 v112, 16, v165
	v_mul_f32_e32 v148, v112, v111
	v_mul_f32_e32 v110, 0xbfb8aa3b, v110
	v_mul_f32_e32 v111, 0xbfb8aa3b, v112
	v_mul_f32_e32 v121, v120, v118
	v_cvt_pk_bf16_f32 v118, v128, v129
	v_cvt_pk_bf16_f32 v119, v124, v125
	v_exp_f32_e32 v110, v110
	v_exp_f32_e32 v111, v111
	v_cvt_pk_bf16_f32 v120, v122, v123
	v_cvt_pk_bf16_f32 v121, v130, v121
	flat_store_dwordx4 v[126:127], v[118:121] offset:256
	v_pk_add_f32 v[110:111], v[110:111], 1.0 op_sel_hi:[1,0]
	v_and_b32_e32 v112, 0xffff0000, v153
	v_lshlrev_b64 v[118:119], 10, v[142:143]
	v_lshl_add_u64 v[118:119], s[0:1], 0, v[118:119]
	v_lshl_add_u64 v[118:119], v[118:119], 0, v[204:205]
	v_mad_i64_i32 v[120:121], s[8:9], v142, s4, v[208:209]
	flat_load_dwordx4 v[126:129], v[118:119]
	v_lshl_add_u64 v[122:123], v[120:121], 0, v[204:205]
	v_mul_f32_e32 v110, v110, v111
	flat_load_dwordx4 v[130:133], v[122:123] offset:1024
	s_nop 0
	flat_load_dwordx4 v[118:121], v[118:119] offset:256
	s_nop 0
	flat_load_dwordx4 v[122:125], v[122:123] offset:1280
	v_rcp_f32_e32 v110, v110
	v_and_b32_e32 v111, 0xffff0000, v165
	v_mul_f32_e32 v112, v111, v112
	v_mul_f32_e32 v111, 0xbfb8aa3b, v111
	v_mul_f32_e32 v148, v148, v110
	v_add_f32_e32 v110, v113, v49
	v_mul_f32_e32 v110, 0xbfb8aa3b, v110
	v_exp_f32_e32 v110, v110
	v_exp_f32_e32 v111, v111
	s_nop 0
	v_pk_add_f32 v[110:111], v[110:111], 1.0 op_sel_hi:[1,0]
	s_nop 0
	v_mul_f32_e32 v110, v110, v111
	v_rcp_f32_e32 v110, v110
	s_nop 0
	v_mul_f32_e32 v110, v112, v110
	v_cvt_pk_bf16_f32 v112, v146, v147
	v_cvt_pk_bf16_f32 v113, v116, v117
	v_cvt_pk_bf16_f32 v114, v114, v115
	v_cvt_pk_bf16_f32 v115, v148, v110
	v_lshl_add_u64 v[110:111], s[42:43], 0, v[144:145]
	v_lshl_add_u64 v[110:111], v[110:111], 0, v[204:205]
	flat_store_dwordx4 v[110:111], v[112:115]
	s_nop 1
	v_lshlrev_b32_e32 v112, 16, v134
	v_lshlrev_b32_e32 v113, 16, v138
	v_mul_f32_e32 v114, v113, v112
	v_exp_f32_e32 v112, v106
	v_mul_f32_e32 v106, 0xbfb8aa3b, v113
	v_exp_f32_e32 v113, v106
	s_nop 0
	v_pk_add_f32 v[112:113], v[112:113], 1.0 op_sel_hi:[1,0]
	s_nop 0
	v_mul_f32_e32 v106, v112, v113
	v_rcp_f32_e32 v106, v106
	v_and_b32_e32 v113, 0xffff0000, v134
	v_add_u32_e32 v134, 0x80, v206
	v_mul_f32_e32 v112, v114, v106
	v_add_f32_e32 v106, v107, v39
	v_and_b32_e32 v107, 0xffff0000, v138
	v_mul_f32_e32 v113, v107, v113
	v_mul_f32_e32 v106, 0xbfb8aa3b, v106
	v_mul_f32_e32 v107, 0xbfb8aa3b, v107
	v_exp_f32_e32 v106, v106
	v_exp_f32_e32 v107, v107
	s_waitcnt vmcnt(0) lgkmcnt(0)
	v_lshlrev_b32_e32 v138, 16, v126
	v_pk_add_f32 v[106:107], v[106:107], 1.0 op_sel_hi:[1,0]
	v_and_b32_e32 v126, 0xffff0000, v126
	v_mul_f32_e32 v106, v106, v107
	v_rcp_f32_e32 v106, v106
	v_lshlrev_b32_e32 v107, 16, v135
	v_mul_f32_e32 v113, v113, v106
	v_add_f32_e32 v106, v108, v40
	v_lshlrev_b32_e32 v108, 16, v139
	v_mul_f32_e32 v114, v108, v107
	v_mul_f32_e32 v106, 0xbfb8aa3b, v106
	v_mul_f32_e32 v107, 0xbfb8aa3b, v108
	v_exp_f32_e32 v106, v106
	v_exp_f32_e32 v107, v107
	s_nop 0
	v_pk_add_f32 v[106:107], v[106:107], 1.0 op_sel_hi:[1,0]
	s_nop 0
	v_mul_f32_e32 v106, v106, v107
	v_rcp_f32_e32 v106, v106
	v_and_b32_e32 v107, 0xffff0000, v139
	v_lshlrev_b32_e32 v139, 16, v130
	v_mul_f32_e32 v108, v114, v106
	v_add_f32_e32 v106, v109, v41
	v_and_b32_e32 v109, 0xffff0000, v135
	v_mul_f32_e32 v109, v107, v109
	v_mul_f32_e32 v106, 0xbfb8aa3b, v106
	v_mul_f32_e32 v107, 0xbfb8aa3b, v107
	v_exp_f32_e32 v106, v106
	v_exp_f32_e32 v107, v107
	v_ashrrev_i32_e32 v135, 31, v134
	v_pk_add_f32 v[106:107], v[106:107], 1.0 op_sel_hi:[1,0]
	s_nop 0
	v_mul_f32_e32 v106, v106, v107
	v_rcp_f32_e32 v106, v106
	v_lshlrev_b32_e32 v107, 16, v140
	v_mul_f32_e32 v109, v109, v106
	v_lshlrev_b32_e32 v106, 16, v136
	v_mul_f32_e32 v114, v107, v106
	v_exp_f32_e32 v106, v102
	v_mul_f32_e32 v102, 0xbfb8aa3b, v107
	v_exp_f32_e32 v107, v102
	s_nop 0
	v_pk_add_f32 v[106:107], v[106:107], 1.0 op_sel_hi:[1,0]
	s_nop 0
	v_mul_f32_e32 v102, v106, v107
	v_rcp_f32_e32 v102, v102
	v_and_b32_e32 v107, 0xffff0000, v136
	v_mul_f32_e32 v106, v114, v102
	v_add_f32_e32 v102, v103, v31
; __device__ __forceinline__ float glu2(float z, float a, float g) { return z * g * __builtin_amdgcn_rcpf((1.0f + __expf(-a)) * (1.0f + __expf(-g))); }
	v_and_b32_e32 v103, 0xffff0000, v140
	v_mul_f32_e32 v140, v139, v138
	v_exp_f32_e32 v138, v98
	v_mul_f32_e32 v98, 0xbfb8aa3b, v139
	v_exp_f32_e32 v139, v98
	v_mul_f32_e32 v107, v103, v107
	v_mul_f32_e32 v102, 0xbfb8aa3b, v102
	v_mul_f32_e32 v103, 0xbfb8aa3b, v103
	v_pk_add_f32 v[138:139], v[138:139], 1.0 op_sel_hi:[1,0]
	v_exp_f32_e32 v102, v102
	v_mul_f32_e32 v98, v138, v139
	v_rcp_f32_e32 v98, v98
	v_exp_f32_e32 v103, v103
	v_mul_f32_e32 v138, v140, v98
	v_add_f32_e32 v98, v99, v51
	v_and_b32_e32 v99, 0xffff0000, v130
	v_mul_f32_e32 v126, v99, v126
	v_mul_f32_e32 v98, 0xbfb8aa3b, v98
	v_mul_f32_e32 v99, 0xbfb8aa3b, v99
	v_exp_f32_e32 v98, v98
	v_exp_f32_e32 v99, v99
	v_pk_add_f32 v[102:103], v[102:103], 1.0 op_sel_hi:[1,0]
	v_pk_add_f32 v[98:99], v[98:99], 1.0 op_sel_hi:[1,0]
	s_nop 0
	v_mul_f32_e32 v98, v98, v99
	v_rcp_f32_e32 v98, v98
	v_lshlrev_b32_e32 v99, 16, v127
	v_mul_f32_e32 v102, v102, v103
	v_rcp_f32_e32 v102, v102
	v_mul_f32_e32 v126, v126, v98
	v_add_f32_e32 v98, v100, v52
	v_lshlrev_b32_e32 v100, 16, v131
	v_mul_f32_e32 v130, v100, v99
	v_mul_f32_e32 v98, 0xbfb8aa3b, v98
	v_mul_f32_e32 v99, 0xbfb8aa3b, v100
	v_exp_f32_e32 v98, v98
	v_exp_f32_e32 v99, v99
	v_mul_f32_e32 v107, v107, v102
	v_add_f32_e32 v102, v104, v32
	v_lshlrev_b32_e32 v103, 16, v137
	v_pk_add_f32 v[98:99], v[98:99], 1.0 op_sel_hi:[1,0]
	v_lshlrev_b32_e32 v104, 16, v141
	v_mul_f32_e32 v98, v98, v99
	v_rcp_f32_e32 v98, v98
	v_and_b32_e32 v99, 0xffff0000, v131
	v_mul_f32_e32 v114, v104, v103
	v_mul_f32_e32 v102, 0xbfb8aa3b, v102
	v_mul_f32_e32 v100, v130, v98
	v_add_f32_e32 v98, v101, v53
	v_and_b32_e32 v101, 0xffff0000, v127
	v_mul_f32_e32 v101, v99, v101
	v_mul_f32_e32 v98, 0xbfb8aa3b, v98
	v_mul_f32_e32 v99, 0xbfb8aa3b, v99
	v_exp_f32_e32 v98, v98
	v_exp_f32_e32 v99, v99
	v_mul_f32_e32 v103, 0xbfb8aa3b, v104
	v_exp_f32_e32 v102, v102
	v_exp_f32_e32 v103, v103
	v_pk_add_f32 v[98:99], v[98:99], 1.0 op_sel_hi:[1,0]
	v_and_b32_e32 v104, 0xffff0000, v137
	v_mul_f32_e32 v98, v98, v99
	v_rcp_f32_e32 v98, v98
	v_lshlrev_b32_e32 v99, 16, v132
	v_pk_add_f32 v[102:103], v[102:103], 1.0 op_sel_hi:[1,0]
	v_lshlrev_b64 v[136:137], 12, v[142:143]
	v_mul_f32_e32 v101, v101, v98
	v_lshlrev_b32_e32 v98, 16, v128
	v_mul_f32_e32 v127, v99, v98
	v_exp_f32_e32 v98, v94
	v_mul_f32_e32 v94, 0xbfb8aa3b, v99
	v_exp_f32_e32 v99, v94
	v_mul_f32_e32 v102, v102, v103
	v_rcp_f32_e32 v102, v102
	v_and_b32_e32 v103, 0xffff0000, v141
	v_pk_add_f32 v[98:99], v[98:99], 1.0 op_sel_hi:[1,0]
	v_mul_f32_e32 v104, v103, v104
	v_mul_f32_e32 v94, v98, v99
	v_rcp_f32_e32 v94, v94
	v_and_b32_e32 v99, 0xffff0000, v128
	v_mul_f32_e32 v114, v114, v102
	v_add_f32_e32 v102, v105, v33
	v_mul_f32_e32 v98, v127, v94
	v_add_f32_e32 v94, v95, v47
	v_and_b32_e32 v95, 0xffff0000, v132
	v_mul_f32_e32 v99, v95, v99
	v_mul_f32_e32 v94, 0xbfb8aa3b, v94
	v_mul_f32_e32 v95, 0xbfb8aa3b, v95
	v_exp_f32_e32 v94, v94
	v_exp_f32_e32 v95, v95
	v_mul_f32_e32 v102, 0xbfb8aa3b, v102
	v_mul_f32_e32 v103, 0xbfb8aa3b, v103
	v_exp_f32_e32 v102, v102
	v_exp_f32_e32 v103, v103
	v_pk_add_f32 v[94:95], v[94:95], 1.0 op_sel_hi:[1,0]
	v_pk_add_f32 v[102:103], v[102:103], 1.0 op_sel_hi:[1,0]
	v_mul_f32_e32 v94, v94, v95
	v_rcp_f32_e32 v94, v94
	v_mul_f32_e32 v102, v102, v103
	v_rcp_f32_e32 v102, v102
	v_lshlrev_b32_e32 v95, 16, v129
	v_mul_f32_e32 v99, v99, v94
	v_add_f32_e32 v94, v96, v48
	v_lshlrev_b32_e32 v96, 16, v133
	v_mul_f32_e32 v127, v96, v95
	v_mul_f32_e32 v94, 0xbfb8aa3b, v94
	v_mul_f32_e32 v95, 0xbfb8aa3b, v96
	v_mul_f32_e32 v105, v104, v102
	v_cvt_pk_bf16_f32 v102, v112, v113
	v_cvt_pk_bf16_f32 v103, v108, v109
	v_exp_f32_e32 v94, v94
	v_exp_f32_e32 v95, v95
	v_cvt_pk_bf16_f32 v104, v106, v107
	v_cvt_pk_bf16_f32 v105, v114, v105
	flat_store_dwordx4 v[110:111], v[102:105] offset:256
	v_pk_add_f32 v[94:95], v[94:95], 1.0 op_sel_hi:[1,0]
	v_and_b32_e32 v96, 0xffff0000, v129
	v_lshlrev_b64 v[102:103], 10, v[134:135]
	v_lshl_add_u64 v[102:103], s[0:1], 0, v[102:103]
	v_lshl_add_u64 v[102:103], v[102:103], 0, v[204:205]
	v_mad_i64_i32 v[104:105], s[8:9], v134, s4, v[208:209]
	flat_load_dwordx4 v[110:113], v[102:103]
	v_lshl_add_u64 v[106:107], v[104:105], 0, v[204:205]
	v_mul_f32_e32 v94, v94, v95
	flat_load_dwordx4 v[114:117], v[106:107] offset:1024
	s_nop 0
	flat_load_dwordx4 v[102:105], v[102:103] offset:256
	s_nop 0
	flat_load_dwordx4 v[106:109], v[106:107] offset:1280
	v_rcp_f32_e32 v94, v94
	v_and_b32_e32 v95, 0xffff0000, v133
	v_mul_f32_e32 v96, v95, v96
	v_mul_f32_e32 v95, 0xbfb8aa3b, v95
	v_mul_f32_e32 v127, v127, v94
	v_add_f32_e32 v94, v97, v49
	v_mul_f32_e32 v94, 0xbfb8aa3b, v94
	v_exp_f32_e32 v94, v94
	v_exp_f32_e32 v95, v95
	s_nop 0
	v_pk_add_f32 v[94:95], v[94:95], 1.0 op_sel_hi:[1,0]
	s_nop 0
	v_mul_f32_e32 v94, v94, v95
	v_rcp_f32_e32 v94, v94
	s_nop 0
	v_mul_f32_e32 v94, v96, v94
	v_cvt_pk_bf16_f32 v96, v138, v126
	v_cvt_pk_bf16_f32 v97, v100, v101
	v_cvt_pk_bf16_f32 v98, v98, v99
	v_cvt_pk_bf16_f32 v99, v127, v94
	v_lshl_add_u64 v[94:95], s[42:43], 0, v[136:137]
	v_lshl_add_u64 v[94:95], v[94:95], 0, v[204:205]
	flat_store_dwordx4 v[94:95], v[96:99]
	s_nop 1
	v_lshlrev_b32_e32 v96, 16, v118
	v_lshlrev_b32_e32 v97, 16, v122
	v_mul_f32_e32 v98, v97, v96
	v_exp_f32_e32 v96, v90
	v_mul_f32_e32 v90, 0xbfb8aa3b, v97
	v_exp_f32_e32 v97, v90
	s_nop 0
	v_pk_add_f32 v[96:97], v[96:97], 1.0 op_sel_hi:[1,0]
	s_nop 0
	v_mul_f32_e32 v90, v96, v97
	v_rcp_f32_e32 v90, v90
	v_and_b32_e32 v97, 0xffff0000, v118
	v_add_u32_e32 v118, 0x90, v206
	v_mul_f32_e32 v96, v98, v90
	v_add_f32_e32 v90, v91, v39
	v_and_b32_e32 v91, 0xffff0000, v122
	v_mul_f32_e32 v97, v91, v97
	v_mul_f32_e32 v90, 0xbfb8aa3b, v90
	v_mul_f32_e32 v91, 0xbfb8aa3b, v91
	v_exp_f32_e32 v90, v90
	v_exp_f32_e32 v91, v91
	s_waitcnt vmcnt(0) lgkmcnt(0)
; __device__ __forceinline__ float glu2(float z, float a, float g) { return z * g * __builtin_amdgcn_rcpf((1.0f + __expf(-a)) * (1.0f + __expf(-g))); }
	v_lshlrev_b32_e32 v122, 16, v110
	v_pk_add_f32 v[90:91], v[90:91], 1.0 op_sel_hi:[1,0]
	v_and_b32_e32 v110, 0xffff0000, v110
	v_mul_f32_e32 v90, v90, v91
	v_rcp_f32_e32 v90, v90
	v_lshlrev_b32_e32 v91, 16, v119
	v_mul_f32_e32 v97, v97, v90
	v_add_f32_e32 v90, v92, v40
	v_lshlrev_b32_e32 v92, 16, v123
	v_mul_f32_e32 v98, v92, v91
	v_mul_f32_e32 v90, 0xbfb8aa3b, v90
	v_mul_f32_e32 v91, 0xbfb8aa3b, v92
	v_exp_f32_e32 v90, v90
	v_exp_f32_e32 v91, v91
	s_nop 0
	v_pk_add_f32 v[90:91], v[90:91], 1.0 op_sel_hi:[1,0]
	s_nop 0
	v_mul_f32_e32 v90, v90, v91
	v_rcp_f32_e32 v90, v90
	v_and_b32_e32 v91, 0xffff0000, v123
	v_lshlrev_b32_e32 v123, 16, v114
	v_mul_f32_e32 v92, v98, v90
	v_add_f32_e32 v90, v93, v41
	v_and_b32_e32 v93, 0xffff0000, v119
	v_mul_f32_e32 v93, v91, v93
	v_mul_f32_e32 v90, 0xbfb8aa3b, v90
	v_mul_f32_e32 v91, 0xbfb8aa3b, v91
	v_exp_f32_e32 v90, v90
	v_exp_f32_e32 v91, v91
	v_ashrrev_i32_e32 v119, 31, v118
	v_pk_add_f32 v[90:91], v[90:91], 1.0 op_sel_hi:[1,0]
	s_nop 0
	v_mul_f32_e32 v90, v90, v91
	v_rcp_f32_e32 v90, v90
	v_lshlrev_b32_e32 v91, 16, v124
	v_mul_f32_e32 v93, v93, v90
	v_lshlrev_b32_e32 v90, 16, v120
	v_mul_f32_e32 v98, v91, v90
	v_exp_f32_e32 v90, v86
	v_mul_f32_e32 v86, 0xbfb8aa3b, v91
	v_exp_f32_e32 v91, v86
	s_nop 0
	v_pk_add_f32 v[90:91], v[90:91], 1.0 op_sel_hi:[1,0]
	s_nop 0
	v_mul_f32_e32 v86, v90, v91
	v_rcp_f32_e32 v86, v86
	v_and_b32_e32 v91, 0xffff0000, v120
	v_mul_f32_e32 v90, v98, v86
	v_add_f32_e32 v86, v87, v31
	v_and_b32_e32 v87, 0xffff0000, v124
	v_mul_f32_e32 v124, v123, v122
	v_exp_f32_e32 v122, v82
	v_mul_f32_e32 v82, 0xbfb8aa3b, v123
	v_exp_f32_e32 v123, v82
	v_mul_f32_e32 v91, v87, v91
	v_mul_f32_e32 v86, 0xbfb8aa3b, v86
	v_mul_f32_e32 v87, 0xbfb8aa3b, v87
	v_pk_add_f32 v[122:123], v[122:123], 1.0 op_sel_hi:[1,0]
	v_exp_f32_e32 v86, v86
	v_mul_f32_e32 v82, v122, v123
	v_rcp_f32_e32 v82, v82
	v_exp_f32_e32 v87, v87
	v_mul_f32_e32 v122, v124, v82
	v_add_f32_e32 v82, v83, v51
	v_and_b32_e32 v83, 0xffff0000, v114
	v_mul_f32_e32 v110, v83, v110
	v_mul_f32_e32 v82, 0xbfb8aa3b, v82
	v_mul_f32_e32 v83, 0xbfb8aa3b, v83
	v_exp_f32_e32 v82, v82
	v_exp_f32_e32 v83, v83
	v_pk_add_f32 v[86:87], v[86:87], 1.0 op_sel_hi:[1,0]
	v_pk_add_f32 v[82:83], v[82:83], 1.0 op_sel_hi:[1,0]
	s_nop 0
	v_mul_f32_e32 v82, v82, v83
	v_rcp_f32_e32 v82, v82
	v_lshlrev_b32_e32 v83, 16, v111
	v_mul_f32_e32 v86, v86, v87
	v_rcp_f32_e32 v86, v86
	v_mul_f32_e32 v110, v110, v82
	v_add_f32_e32 v82, v84, v52
	v_lshlrev_b32_e32 v84, 16, v115
	v_mul_f32_e32 v114, v84, v83
	v_mul_f32_e32 v82, 0xbfb8aa3b, v82
	v_mul_f32_e32 v83, 0xbfb8aa3b, v84
	v_exp_f32_e32 v82, v82
	v_exp_f32_e32 v83, v83
	v_mul_f32_e32 v91, v91, v86
	v_add_f32_e32 v86, v88, v32
	v_lshlrev_b32_e32 v87, 16, v121
	v_pk_add_f32 v[82:83], v[82:83], 1.0 op_sel_hi:[1,0]
	v_lshlrev_b32_e32 v88, 16, v125
	v_mul_f32_e32 v82, v82, v83
	v_rcp_f32_e32 v82, v82
	v_and_b32_e32 v83, 0xffff0000, v115
	v_mul_f32_e32 v98, v88, v87
	v_mul_f32_e32 v86, 0xbfb8aa3b, v86
	v_mul_f32_e32 v84, v114, v82
	v_add_f32_e32 v82, v85, v53
	v_and_b32_e32 v85, 0xffff0000, v111
	v_mul_f32_e32 v85, v83, v85
	v_mul_f32_e32 v82, 0xbfb8aa3b, v82
	v_mul_f32_e32 v83, 0xbfb8aa3b, v83
	v_exp_f32_e32 v82, v82
	v_exp_f32_e32 v83, v83
	v_mul_f32_e32 v87, 0xbfb8aa3b, v88
	v_exp_f32_e32 v86, v86
	v_exp_f32_e32 v87, v87
	v_pk_add_f32 v[82:83], v[82:83], 1.0 op_sel_hi:[1,0]
	v_and_b32_e32 v88, 0xffff0000, v121
	v_mul_f32_e32 v82, v82, v83
	v_rcp_f32_e32 v82, v82
	v_lshlrev_b32_e32 v83, 16, v116
	v_pk_add_f32 v[86:87], v[86:87], 1.0 op_sel_hi:[1,0]
	v_lshlrev_b64 v[120:121], 12, v[134:135]
	v_mul_f32_e32 v85, v85, v82
	v_lshlrev_b32_e32 v82, 16, v112
	v_mul_f32_e32 v111, v83, v82
	v_exp_f32_e32 v82, v78
	v_mul_f32_e32 v78, 0xbfb8aa3b, v83
	v_exp_f32_e32 v83, v78
	v_mul_f32_e32 v86, v86, v87
	v_rcp_f32_e32 v86, v86
	v_and_b32_e32 v87, 0xffff0000, v125
	v_pk_add_f32 v[82:83], v[82:83], 1.0 op_sel_hi:[1,0]
	v_mul_f32_e32 v88, v87, v88
	v_mul_f32_e32 v78, v82, v83
	v_rcp_f32_e32 v78, v78
	v_and_b32_e32 v83, 0xffff0000, v112
	v_mul_f32_e32 v98, v98, v86
	v_add_f32_e32 v86, v89, v33
	v_mul_f32_e32 v82, v111, v78
	v_add_f32_e32 v78, v79, v47
	v_and_b32_e32 v79, 0xffff0000, v116
	v_mul_f32_e32 v83, v79, v83
	v_mul_f32_e32 v78, 0xbfb8aa3b, v78
	v_mul_f32_e32 v79, 0xbfb8aa3b, v79
	v_exp_f32_e32 v78, v78
	v_exp_f32_e32 v79, v79
	v_mul_f32_e32 v86, 0xbfb8aa3b, v86
	v_mul_f32_e32 v87, 0xbfb8aa3b, v87
	v_exp_f32_e32 v86, v86
	v_exp_f32_e32 v87, v87
	v_pk_add_f32 v[78:79], v[78:79], 1.0 op_sel_hi:[1,0]
	v_pk_add_f32 v[86:87], v[86:87], 1.0 op_sel_hi:[1,0]
	v_mul_f32_e32 v78, v78, v79
	v_rcp_f32_e32 v78, v78
	v_mul_f32_e32 v86, v86, v87
	v_rcp_f32_e32 v86, v86
	v_lshlrev_b32_e32 v79, 16, v113
	v_mul_f32_e32 v83, v83, v78
	v_add_f32_e32 v78, v80, v48
	v_lshlrev_b32_e32 v80, 16, v117
	v_mul_f32_e32 v111, v80, v79
	v_mul_f32_e32 v78, 0xbfb8aa3b, v78
	v_mul_f32_e32 v79, 0xbfb8aa3b, v80
	v_mul_f32_e32 v89, v88, v86
	v_cvt_pk_bf16_f32 v86, v96, v97
	v_cvt_pk_bf16_f32 v87, v92, v93
	v_exp_f32_e32 v78, v78
	v_exp_f32_e32 v79, v79
	v_cvt_pk_bf16_f32 v88, v90, v91
	v_cvt_pk_bf16_f32 v89, v98, v89
	flat_store_dwordx4 v[94:95], v[86:89] offset:256
	v_pk_add_f32 v[78:79], v[78:79], 1.0 op_sel_hi:[1,0]
	v_and_b32_e32 v80, 0xffff0000, v113
	v_lshlrev_b64 v[86:87], 10, v[118:119]
	v_lshl_add_u64 v[86:87], s[0:1], 0, v[86:87]
	v_lshl_add_u64 v[86:87], v[86:87], 0, v[204:205]
	v_mad_i64_i32 v[88:89], s[8:9], v118, s4, v[208:209]
	flat_load_dwordx4 v[94:97], v[86:87]
	v_lshl_add_u64 v[90:91], v[88:89], 0, v[204:205]
	v_mul_f32_e32 v78, v78, v79
	flat_load_dwordx4 v[98:101], v[90:91] offset:1024
	s_nop 0
	flat_load_dwordx4 v[86:89], v[86:87] offset:256
; __device__ __forceinline__ float glu2(float z, float a, float g) { return z * g * __builtin_amdgcn_rcpf((1.0f + __expf(-a)) * (1.0f + __expf(-g))); }
	s_nop 0
	flat_load_dwordx4 v[90:93], v[90:91] offset:1280
	v_rcp_f32_e32 v78, v78
	v_and_b32_e32 v79, 0xffff0000, v117
	v_mul_f32_e32 v80, v79, v80
	v_mul_f32_e32 v79, 0xbfb8aa3b, v79
	v_mul_f32_e32 v111, v111, v78
	v_add_f32_e32 v78, v81, v49
	v_mul_f32_e32 v78, 0xbfb8aa3b, v78
	v_exp_f32_e32 v78, v78
	v_exp_f32_e32 v79, v79
	s_nop 0
	v_pk_add_f32 v[78:79], v[78:79], 1.0 op_sel_hi:[1,0]
	s_nop 0
	v_mul_f32_e32 v78, v78, v79
	v_rcp_f32_e32 v78, v78
	s_nop 0
	v_mul_f32_e32 v78, v80, v78
	v_cvt_pk_bf16_f32 v80, v122, v110
	v_cvt_pk_bf16_f32 v81, v84, v85
	v_cvt_pk_bf16_f32 v82, v82, v83
	v_cvt_pk_bf16_f32 v83, v111, v78
	v_lshl_add_u64 v[78:79], s[42:43], 0, v[120:121]
	v_lshl_add_u64 v[78:79], v[78:79], 0, v[204:205]
	flat_store_dwordx4 v[78:79], v[80:83]
	s_nop 1
	v_lshlrev_b32_e32 v80, 16, v102
	v_lshlrev_b32_e32 v81, 16, v106
	v_mul_f32_e32 v82, v81, v80
	v_exp_f32_e32 v80, v74
	v_mul_f32_e32 v74, 0xbfb8aa3b, v81
	v_exp_f32_e32 v81, v74
	s_nop 0
	v_pk_add_f32 v[80:81], v[80:81], 1.0 op_sel_hi:[1,0]
	s_nop 0
	v_mul_f32_e32 v74, v80, v81
	v_rcp_f32_e32 v74, v74
	v_and_b32_e32 v81, 0xffff0000, v102
	v_add_u32_e32 v102, 0xa0, v206
	v_mul_f32_e32 v80, v82, v74
	v_add_f32_e32 v74, v75, v39
	v_and_b32_e32 v75, 0xffff0000, v106
	v_mul_f32_e32 v81, v75, v81
	v_mul_f32_e32 v74, 0xbfb8aa3b, v74
	v_mul_f32_e32 v75, 0xbfb8aa3b, v75
	v_exp_f32_e32 v74, v74
	v_exp_f32_e32 v75, v75
	s_waitcnt vmcnt(0) lgkmcnt(0)
	v_lshlrev_b32_e32 v106, 16, v94
	v_pk_add_f32 v[74:75], v[74:75], 1.0 op_sel_hi:[1,0]
	v_and_b32_e32 v94, 0xffff0000, v94
	v_mul_f32_e32 v74, v74, v75
	v_rcp_f32_e32 v74, v74
	v_lshlrev_b32_e32 v75, 16, v103
	v_mul_f32_e32 v81, v81, v74
	v_add_f32_e32 v74, v76, v40
	v_lshlrev_b32_e32 v76, 16, v107
	v_mul_f32_e32 v82, v76, v75
	v_mul_f32_e32 v74, 0xbfb8aa3b, v74
	v_mul_f32_e32 v75, 0xbfb8aa3b, v76
	v_exp_f32_e32 v74, v74
	v_exp_f32_e32 v75, v75
	s_nop 0
	v_pk_add_f32 v[74:75], v[74:75], 1.0 op_sel_hi:[1,0]
	s_nop 0
	v_mul_f32_e32 v74, v74, v75
	v_rcp_f32_e32 v74, v74
	v_and_b32_e32 v75, 0xffff0000, v107
	v_lshlrev_b32_e32 v107, 16, v98
	v_mul_f32_e32 v76, v82, v74
	v_add_f32_e32 v74, v77, v41
	v_and_b32_e32 v77, 0xffff0000, v103
	v_mul_f32_e32 v77, v75, v77
	v_mul_f32_e32 v74, 0xbfb8aa3b, v74
	v_mul_f32_e32 v75, 0xbfb8aa3b, v75
	v_exp_f32_e32 v74, v74
	v_exp_f32_e32 v75, v75
	v_ashrrev_i32_e32 v103, 31, v102
	v_pk_add_f32 v[74:75], v[74:75], 1.0 op_sel_hi:[1,0]
	s_nop 0
	v_mul_f32_e32 v74, v74, v75
	v_rcp_f32_e32 v74, v74
	v_lshlrev_b32_e32 v75, 16, v108
	v_mul_f32_e32 v77, v77, v74
	v_lshlrev_b32_e32 v74, 16, v104
	v_mul_f32_e32 v82, v75, v74
	v_exp_f32_e32 v74, v70
	v_mul_f32_e32 v70, 0xbfb8aa3b, v75
	v_exp_f32_e32 v75, v70
	s_nop 0
	v_pk_add_f32 v[74:75], v[74:75], 1.0 op_sel_hi:[1,0]
	s_nop 0
	v_mul_f32_e32 v70, v74, v75
	v_rcp_f32_e32 v70, v70
	v_and_b32_e32 v75, 0xffff0000, v104
	v_mul_f32_e32 v74, v82, v70
	v_add_f32_e32 v70, v71, v31
	v_and_b32_e32 v71, 0xffff0000, v108
	v_mul_f32_e32 v108, v107, v106
	v_exp_f32_e32 v106, v66
	v_mul_f32_e32 v66, 0xbfb8aa3b, v107
	v_exp_f32_e32 v107, v66
	v_mul_f32_e32 v75, v71, v75
	v_mul_f32_e32 v70, 0xbfb8aa3b, v70
	v_mul_f32_e32 v71, 0xbfb8aa3b, v71
	v_pk_add_f32 v[106:107], v[106:107], 1.0 op_sel_hi:[1,0]
	v_exp_f32_e32 v70, v70
	v_mul_f32_e32 v66, v106, v107
	v_rcp_f32_e32 v66, v66
	v_exp_f32_e32 v71, v71
	v_mul_f32_e32 v106, v108, v66
	v_add_f32_e32 v66, v67, v51
	v_and_b32_e32 v67, 0xffff0000, v98
	v_mul_f32_e32 v94, v67, v94
	v_mul_f32_e32 v66, 0xbfb8aa3b, v66
	v_mul_f32_e32 v67, 0xbfb8aa3b, v67
	v_exp_f32_e32 v66, v66
	v_exp_f32_e32 v67, v67
	v_pk_add_f32 v[70:71], v[70:71], 1.0 op_sel_hi:[1,0]
	v_pk_add_f32 v[66:67], v[66:67], 1.0 op_sel_hi:[1,0]
	s_nop 0
	v_mul_f32_e32 v66, v66, v67
	v_rcp_f32_e32 v66, v66
	v_lshlrev_b32_e32 v67, 16, v95
	v_mul_f32_e32 v70, v70, v71
	v_rcp_f32_e32 v70, v70
	v_mul_f32_e32 v94, v94, v66
	v_add_f32_e32 v66, v68, v52
	v_lshlrev_b32_e32 v68, 16, v99
	v_mul_f32_e32 v98, v68, v67
	v_mul_f32_e32 v66, 0xbfb8aa3b, v66
	v_mul_f32_e32 v67, 0xbfb8aa3b, v68
	v_exp_f32_e32 v66, v66
	v_exp_f32_e32 v67, v67
	v_mul_f32_e32 v75, v75, v70
	v_add_f32_e32 v70, v72, v32
	v_lshlrev_b32_e32 v71, 16, v105
	v_pk_add_f32 v[66:67], v[66:67], 1.0 op_sel_hi:[1,0]
	v_lshlrev_b32_e32 v72, 16, v109
	v_mul_f32_e32 v66, v66, v67
	v_rcp_f32_e32 v66, v66
	v_and_b32_e32 v67, 0xffff0000, v99
	v_mul_f32_e32 v82, v72, v71
	v_mul_f32_e32 v70, 0xbfb8aa3b, v70
	v_mul_f32_e32 v68, v98, v66
	v_add_f32_e32 v66, v69, v53
	v_and_b32_e32 v69, 0xffff0000, v95
	v_mul_f32_e32 v69, v67, v69
	v_mul_f32_e32 v66, 0xbfb8aa3b, v66
	v_mul_f32_e32 v67, 0xbfb8aa3b, v67
	v_exp_f32_e32 v66, v66
	v_exp_f32_e32 v67, v67
	v_mul_f32_e32 v71, 0xbfb8aa3b, v72
	v_exp_f32_e32 v70, v70
	v_exp_f32_e32 v71, v71
	v_pk_add_f32 v[66:67], v[66:67], 1.0 op_sel_hi:[1,0]
	v_and_b32_e32 v72, 0xffff0000, v105
	v_mul_f32_e32 v66, v66, v67
	v_rcp_f32_e32 v66, v66
	v_lshlrev_b32_e32 v67, 16, v100
	v_pk_add_f32 v[70:71], v[70:71], 1.0 op_sel_hi:[1,0]
	v_lshlrev_b64 v[104:105], 12, v[118:119]
	v_mul_f32_e32 v69, v69, v66
	v_lshlrev_b32_e32 v66, 16, v96
	v_mul_f32_e32 v95, v67, v66
	v_exp_f32_e32 v66, v62
	v_mul_f32_e32 v62, 0xbfb8aa3b, v67
	v_exp_f32_e32 v67, v62
	v_mul_f32_e32 v70, v70, v71
	v_rcp_f32_e32 v70, v70
	v_and_b32_e32 v71, 0xffff0000, v109
	v_pk_add_f32 v[66:67], v[66:67], 1.0 op_sel_hi:[1,0]
	v_mul_f32_e32 v72, v71, v72
	v_mul_f32_e32 v62, v66, v67
	v_rcp_f32_e32 v62, v62
	v_and_b32_e32 v67, 0xffff0000, v96
	v_mul_f32_e32 v82, v82, v70
	v_add_f32_e32 v70, v73, v33
	v_mul_f32_e32 v66, v95, v62
	v_add_f32_e32 v62, v63, v47
	v_and_b32_e32 v63, 0xffff0000, v100
	v_mul_f32_e32 v67, v63, v67
	v_mul_f32_e32 v62, 0xbfb8aa3b, v62
; __device__ __forceinline__ float glu2(float z, float a, float g) { return z * g * __builtin_amdgcn_rcpf((1.0f + __expf(-a)) * (1.0f + __expf(-g))); }
	v_mul_f32_e32 v63, 0xbfb8aa3b, v63
	v_exp_f32_e32 v62, v62
	v_exp_f32_e32 v63, v63
	v_mul_f32_e32 v70, 0xbfb8aa3b, v70
	v_mul_f32_e32 v71, 0xbfb8aa3b, v71
	v_exp_f32_e32 v70, v70
	v_exp_f32_e32 v71, v71
	v_pk_add_f32 v[62:63], v[62:63], 1.0 op_sel_hi:[1,0]
	v_pk_add_f32 v[70:71], v[70:71], 1.0 op_sel_hi:[1,0]
	v_mul_f32_e32 v62, v62, v63
	v_rcp_f32_e32 v62, v62
	v_mul_f32_e32 v70, v70, v71
	v_rcp_f32_e32 v70, v70
	v_lshlrev_b32_e32 v63, 16, v97
	v_mul_f32_e32 v67, v67, v62
	v_add_f32_e32 v62, v64, v48
	v_lshlrev_b32_e32 v64, 16, v101
	v_mul_f32_e32 v95, v64, v63
	v_mul_f32_e32 v62, 0xbfb8aa3b, v62
	v_mul_f32_e32 v63, 0xbfb8aa3b, v64
	v_mul_f32_e32 v73, v72, v70
	v_cvt_pk_bf16_f32 v70, v80, v81
	v_cvt_pk_bf16_f32 v71, v76, v77
	v_exp_f32_e32 v62, v62
	v_exp_f32_e32 v63, v63
	v_cvt_pk_bf16_f32 v72, v74, v75
	v_cvt_pk_bf16_f32 v73, v82, v73
	flat_store_dwordx4 v[78:79], v[70:73] offset:256
	v_pk_add_f32 v[62:63], v[62:63], 1.0 op_sel_hi:[1,0]
	v_and_b32_e32 v64, 0xffff0000, v97
	v_lshlrev_b64 v[70:71], 10, v[102:103]
	v_lshl_add_u64 v[70:71], s[0:1], 0, v[70:71]
	v_lshl_add_u64 v[70:71], v[70:71], 0, v[204:205]
	v_mad_i64_i32 v[72:73], s[8:9], v102, s4, v[208:209]
	flat_load_dwordx4 v[78:81], v[70:71]
	v_lshl_add_u64 v[74:75], v[72:73], 0, v[204:205]
	v_mul_f32_e32 v62, v62, v63
	flat_load_dwordx4 v[82:85], v[74:75] offset:1024
	s_nop 0
	flat_load_dwordx4 v[70:73], v[70:71] offset:256
	s_nop 0
	flat_load_dwordx4 v[74:77], v[74:75] offset:1280
	v_rcp_f32_e32 v62, v62
	v_and_b32_e32 v63, 0xffff0000, v101
	v_mul_f32_e32 v64, v63, v64
	v_mul_f32_e32 v63, 0xbfb8aa3b, v63
	v_mul_f32_e32 v95, v95, v62
	v_add_f32_e32 v62, v65, v49
	v_mul_f32_e32 v62, 0xbfb8aa3b, v62
	v_exp_f32_e32 v62, v62
	v_exp_f32_e32 v63, v63
	s_nop 0
	v_pk_add_f32 v[62:63], v[62:63], 1.0 op_sel_hi:[1,0]
	s_nop 0
	v_mul_f32_e32 v62, v62, v63
	v_rcp_f32_e32 v62, v62
	s_nop 0
	v_mul_f32_e32 v62, v64, v62
	v_cvt_pk_bf16_f32 v64, v106, v94
	v_cvt_pk_bf16_f32 v65, v68, v69
	v_cvt_pk_bf16_f32 v66, v66, v67
	v_cvt_pk_bf16_f32 v67, v95, v62
	v_lshl_add_u64 v[62:63], s[42:43], 0, v[104:105]
	v_lshl_add_u64 v[62:63], v[62:63], 0, v[204:205]
	flat_store_dwordx4 v[62:63], v[64:67]
	s_nop 1
	v_lshlrev_b32_e32 v64, 16, v86
	v_lshlrev_b32_e32 v65, 16, v90
	v_mul_f32_e32 v66, v65, v64
	v_exp_f32_e32 v64, v58
	v_mul_f32_e32 v58, 0xbfb8aa3b, v65
	v_exp_f32_e32 v65, v58
	s_nop 0
	v_pk_add_f32 v[64:65], v[64:65], 1.0 op_sel_hi:[1,0]
	s_nop 0
	v_mul_f32_e32 v58, v64, v65
	v_rcp_f32_e32 v58, v58
	v_and_b32_e32 v65, 0xffff0000, v86
	v_add_u32_e32 v86, 0xb0, v206
	v_mul_f32_e32 v64, v66, v58
	v_add_f32_e32 v58, v59, v39
	v_and_b32_e32 v59, 0xffff0000, v90
	v_mul_f32_e32 v65, v59, v65
	v_mul_f32_e32 v58, 0xbfb8aa3b, v58
	v_mul_f32_e32 v59, 0xbfb8aa3b, v59
	v_exp_f32_e32 v58, v58
	v_exp_f32_e32 v59, v59
	s_waitcnt vmcnt(0) lgkmcnt(0)
	v_lshlrev_b32_e32 v90, 16, v78
	v_pk_add_f32 v[58:59], v[58:59], 1.0 op_sel_hi:[1,0]
	v_and_b32_e32 v78, 0xffff0000, v78
	v_mul_f32_e32 v58, v58, v59
	v_rcp_f32_e32 v58, v58
	v_lshlrev_b32_e32 v59, 16, v87
	v_mul_f32_e32 v65, v65, v58
	v_add_f32_e32 v58, v60, v40
	v_lshlrev_b32_e32 v60, 16, v91
	v_mul_f32_e32 v66, v60, v59
	v_mul_f32_e32 v58, 0xbfb8aa3b, v58
	v_mul_f32_e32 v59, 0xbfb8aa3b, v60
	v_exp_f32_e32 v58, v58
	v_exp_f32_e32 v59, v59
	s_nop 0
	v_pk_add_f32 v[58:59], v[58:59], 1.0 op_sel_hi:[1,0]
	s_nop 0
	v_mul_f32_e32 v58, v58, v59
	v_rcp_f32_e32 v58, v58
	v_and_b32_e32 v59, 0xffff0000, v91
	v_lshlrev_b32_e32 v91, 16, v82
	v_mul_f32_e32 v60, v66, v58
	v_add_f32_e32 v58, v61, v41
	v_and_b32_e32 v61, 0xffff0000, v87
	v_mul_f32_e32 v61, v59, v61
	v_mul_f32_e32 v58, 0xbfb8aa3b, v58
	v_mul_f32_e32 v59, 0xbfb8aa3b, v59
	v_exp_f32_e32 v58, v58
	v_exp_f32_e32 v59, v59
	v_ashrrev_i32_e32 v87, 31, v86
	v_pk_add_f32 v[58:59], v[58:59], 1.0 op_sel_hi:[1,0]
	s_nop 0
	v_mul_f32_e32 v58, v58, v59
	v_rcp_f32_e32 v58, v58
	v_lshlrev_b32_e32 v59, 16, v92
	v_mul_f32_e32 v61, v61, v58
	v_lshlrev_b32_e32 v58, 16, v88
	v_mul_f32_e32 v66, v59, v58
	v_exp_f32_e32 v58, v54
	v_mul_f32_e32 v54, 0xbfb8aa3b, v59
	v_exp_f32_e32 v59, v54
	s_nop 0
	v_pk_add_f32 v[58:59], v[58:59], 1.0 op_sel_hi:[1,0]
	s_nop 0
	v_mul_f32_e32 v54, v58, v59
	v_rcp_f32_e32 v54, v54
	v_and_b32_e32 v59, 0xffff0000, v88
	v_mul_f32_e32 v58, v66, v54
	v_add_f32_e32 v54, v55, v31
	v_and_b32_e32 v55, 0xffff0000, v92
	v_mul_f32_e32 v92, v91, v90
	v_exp_f32_e32 v90, v42
	v_mul_f32_e32 v42, 0xbfb8aa3b, v91
	v_exp_f32_e32 v91, v42
	v_mul_f32_e32 v59, v55, v59
	v_mul_f32_e32 v54, 0xbfb8aa3b, v54
	v_mul_f32_e32 v55, 0xbfb8aa3b, v55
	v_pk_add_f32 v[90:91], v[90:91], 1.0 op_sel_hi:[1,0]
	v_exp_f32_e32 v54, v54
	v_mul_f32_e32 v42, v90, v91
	v_rcp_f32_e32 v42, v42
	v_exp_f32_e32 v55, v55
	v_mul_f32_e32 v90, v92, v42
	v_add_f32_e32 v42, v43, v51
	v_and_b32_e32 v43, 0xffff0000, v82
	v_mul_f32_e32 v78, v43, v78
	v_mul_f32_e32 v42, 0xbfb8aa3b, v42
	v_mul_f32_e32 v43, 0xbfb8aa3b, v43
	v_exp_f32_e32 v42, v42
	v_exp_f32_e32 v43, v43
	v_pk_add_f32 v[54:55], v[54:55], 1.0 op_sel_hi:[1,0]
	v_pk_add_f32 v[42:43], v[42:43], 1.0 op_sel_hi:[1,0]
	s_nop 0
	v_mul_f32_e32 v42, v42, v43
	v_rcp_f32_e32 v42, v42
	v_lshlrev_b32_e32 v43, 16, v79
	v_mul_f32_e32 v54, v54, v55
	v_rcp_f32_e32 v54, v54
	v_mul_f32_e32 v78, v78, v42
	v_add_f32_e32 v42, v44, v52
	v_lshlrev_b32_e32 v44, 16, v83
	v_mul_f32_e32 v82, v44, v43
	v_mul_f32_e32 v42, 0xbfb8aa3b, v42
	v_mul_f32_e32 v43, 0xbfb8aa3b, v44
	v_exp_f32_e32 v42, v42
	v_exp_f32_e32 v43, v43
	v_mul_f32_e32 v59, v59, v54
	v_add_f32_e32 v54, v56, v32
	v_lshlrev_b32_e32 v55, 16, v89
	v_pk_add_f32 v[42:43], v[42:43], 1.0 op_sel_hi:[1,0]
	v_lshlrev_b32_e32 v56, 16, v93
	v_mul_f32_e32 v42, v42, v43
	v_rcp_f32_e32 v42, v42
; __device__ __forceinline__ float glu2(float z, float a, float g) { return z * g * __builtin_amdgcn_rcpf((1.0f + __expf(-a)) * (1.0f + __expf(-g))); }
	v_and_b32_e32 v43, 0xffff0000, v83
	v_mul_f32_e32 v66, v56, v55
	v_mul_f32_e32 v54, 0xbfb8aa3b, v54
	v_mul_f32_e32 v44, v82, v42
	v_add_f32_e32 v42, v45, v53
	v_and_b32_e32 v45, 0xffff0000, v79
	v_mul_f32_e32 v45, v43, v45
	v_mul_f32_e32 v42, 0xbfb8aa3b, v42
	v_mul_f32_e32 v43, 0xbfb8aa3b, v43
	v_exp_f32_e32 v42, v42
	v_exp_f32_e32 v43, v43
	v_mul_f32_e32 v55, 0xbfb8aa3b, v56
	v_exp_f32_e32 v54, v54
	v_exp_f32_e32 v55, v55
	v_pk_add_f32 v[42:43], v[42:43], 1.0 op_sel_hi:[1,0]
	v_and_b32_e32 v56, 0xffff0000, v89
	v_mul_f32_e32 v42, v42, v43
	v_rcp_f32_e32 v42, v42
	v_lshlrev_b32_e32 v43, 16, v84
	v_pk_add_f32 v[54:55], v[54:55], 1.0 op_sel_hi:[1,0]
	v_lshlrev_b64 v[88:89], 12, v[102:103]
	v_mul_f32_e32 v45, v45, v42
	v_lshlrev_b32_e32 v42, 16, v80
	v_mul_f32_e32 v79, v43, v42
	v_exp_f32_e32 v42, v34
	v_mul_f32_e32 v34, 0xbfb8aa3b, v43
	v_exp_f32_e32 v43, v34
	v_mul_f32_e32 v54, v54, v55
	v_rcp_f32_e32 v54, v54
	v_and_b32_e32 v55, 0xffff0000, v93
	v_pk_add_f32 v[42:43], v[42:43], 1.0 op_sel_hi:[1,0]
	v_mul_f32_e32 v56, v55, v56
	v_mul_f32_e32 v34, v42, v43
	v_rcp_f32_e32 v34, v34
	v_and_b32_e32 v42, 0xffff0000, v80
	v_mul_f32_e32 v66, v66, v54
	v_add_f32_e32 v54, v57, v33
	v_mul_f32_e32 v79, v79, v34
	v_add_f32_e32 v34, v35, v47
	v_and_b32_e32 v35, 0xffff0000, v84
	v_mul_f32_e32 v42, v35, v42
	v_mul_f32_e32 v34, 0xbfb8aa3b, v34
	v_mul_f32_e32 v35, 0xbfb8aa3b, v35
	v_exp_f32_e32 v34, v34
	v_exp_f32_e32 v35, v35
	v_mul_f32_e32 v54, 0xbfb8aa3b, v54
	v_mul_f32_e32 v55, 0xbfb8aa3b, v55
	v_exp_f32_e32 v54, v54
	v_pk_add_f32 v[34:35], v[34:35], 1.0 op_sel_hi:[1,0]
	v_exp_f32_e32 v55, v55
	v_mul_f32_e32 v34, v34, v35
	v_rcp_f32_e32 v34, v34
	v_lshlrev_b32_e32 v35, 16, v81
	v_pk_add_f32 v[54:55], v[54:55], 1.0 op_sel_hi:[1,0]
	v_mul_f32_e32 v80, v42, v34
	v_add_f32_e32 v34, v36, v48
	v_lshlrev_b32_e32 v36, 16, v85
	v_mul_f32_e32 v42, v36, v35
	v_mul_f32_e32 v34, 0xbfb8aa3b, v34
	v_mul_f32_e32 v35, 0xbfb8aa3b, v36
	v_exp_f32_e32 v34, v34
	v_exp_f32_e32 v35, v35
	v_mul_f32_e32 v54, v54, v55
	v_rcp_f32_e32 v54, v54
	v_pk_add_f32 v[34:35], v[34:35], 1.0 op_sel_hi:[1,0]
	s_nop 0
	v_mul_f32_e32 v34, v34, v35
	v_rcp_f32_e32 v34, v34
	v_and_b32_e32 v35, 0xffff0000, v85
	v_mul_f32_e32 v57, v56, v54
	v_cvt_pk_bf16_f32 v54, v64, v65
	v_mul_f32_e32 v36, v42, v34
	v_add_f32_e32 v34, v37, v49
	v_and_b32_e32 v37, 0xffff0000, v81
	v_mul_f32_e32 v37, v35, v37
	v_mul_f32_e32 v34, 0xbfb8aa3b, v34
	v_mul_f32_e32 v35, 0xbfb8aa3b, v35
	v_exp_f32_e32 v34, v34
	v_exp_f32_e32 v35, v35
	v_cvt_pk_bf16_f32 v55, v60, v61
	v_cvt_pk_bf16_f32 v56, v58, v59
	v_cvt_pk_bf16_f32 v57, v66, v57
	flat_store_dwordx4 v[62:63], v[54:57] offset:256
	v_pk_add_f32 v[34:35], v[34:35], 1.0 op_sel_hi:[1,0]
	s_nop 0
	v_mul_f32_e32 v34, v34, v35
	v_rcp_f32_e32 v34, v34
	v_lshlrev_b64 v[54:55], 10, v[86:87]
	v_lshl_add_u64 v[54:55], s[0:1], 0, v[54:55]
	v_mad_i64_i32 v[56:57], s[8:9], v86, s4, v[208:209]
	v_lshl_add_u64 v[54:55], v[54:55], 0, v[204:205]
	v_lshl_add_u64 v[58:59], v[56:57], 0, v[204:205]
	v_mul_f32_e32 v34, v37, v34
	flat_load_dwordx4 v[62:65], v[54:55]
	flat_load_dwordx4 v[66:69], v[58:59] offset:1024
	s_nop 0
	flat_load_dwordx4 v[54:57], v[54:55] offset:256
	s_nop 0
	flat_load_dwordx4 v[58:61], v[58:59] offset:1280
	v_cvt_pk_bf16_f32 v42, v90, v78
	v_cvt_pk_bf16_f32 v43, v44, v45
	v_cvt_pk_bf16_f32 v44, v79, v80
	v_cvt_pk_bf16_f32 v45, v36, v34
	v_lshl_add_u64 v[34:35], s[42:43], 0, v[88:89]
	v_lshl_add_u64 v[34:35], v[34:35], 0, v[204:205]
	v_lshlrev_b32_e32 v36, 16, v70
	v_lshlrev_b32_e32 v37, 16, v74
	flat_store_dwordx4 v[34:35], v[42:45]
	s_nop 1
	v_mul_f32_e32 v42, v37, v36
	v_exp_f32_e32 v36, v26
	v_mul_f32_e32 v26, 0xbfb8aa3b, v37
	v_exp_f32_e32 v37, v26
	s_nop 0
	v_pk_add_f32 v[36:37], v[36:37], 1.0 op_sel_hi:[1,0]
	s_nop 0
	v_mul_f32_e32 v26, v36, v37
	v_rcp_f32_e32 v26, v26
	v_and_b32_e32 v37, 0xffff0000, v70
	v_mul_f32_e32 v36, v42, v26
	v_add_f32_e32 v26, v27, v39
	v_and_b32_e32 v27, 0xffff0000, v74
	v_mul_f32_e32 v37, v27, v37
	v_mul_f32_e32 v26, 0xbfb8aa3b, v26
	v_mul_f32_e32 v27, 0xbfb8aa3b, v27
	v_exp_f32_e32 v26, v26
	v_exp_f32_e32 v27, v27
	s_nop 0
	v_pk_add_f32 v[26:27], v[26:27], 1.0 op_sel_hi:[1,0]
	s_nop 0
	v_mul_f32_e32 v26, v26, v27
	v_rcp_f32_e32 v26, v26
	v_lshlrev_b32_e32 v27, 16, v71
	v_mul_f32_e32 v37, v37, v26
	v_add_f32_e32 v26, v28, v40
	v_lshlrev_b32_e32 v28, 16, v75
	v_mul_f32_e32 v42, v28, v27
	v_mul_f32_e32 v26, 0xbfb8aa3b, v26
	v_mul_f32_e32 v27, 0xbfb8aa3b, v28
	v_exp_f32_e32 v26, v26
	v_exp_f32_e32 v27, v27
	s_nop 0
	v_pk_add_f32 v[26:27], v[26:27], 1.0 op_sel_hi:[1,0]
	s_nop 0
	v_mul_f32_e32 v26, v26, v27
	v_rcp_f32_e32 v26, v26
	v_and_b32_e32 v27, 0xffff0000, v75
	v_mul_f32_e32 v28, v42, v26
	v_add_f32_e32 v26, v29, v41
	v_and_b32_e32 v29, 0xffff0000, v71
	v_mul_f32_e32 v29, v27, v29
	v_mul_f32_e32 v26, 0xbfb8aa3b, v26
	v_mul_f32_e32 v27, 0xbfb8aa3b, v27
	v_exp_f32_e32 v26, v26
	v_exp_f32_e32 v27, v27
	s_nop 0
	v_pk_add_f32 v[26:27], v[26:27], 1.0 op_sel_hi:[1,0]
	s_nop 0
	v_mul_f32_e32 v26, v26, v27
	v_rcp_f32_e32 v26, v26
	v_lshlrev_b32_e32 v27, 16, v76
	v_mul_f32_e32 v29, v29, v26
	v_lshlrev_b32_e32 v26, 16, v72
	v_mul_f32_e32 v42, v27, v26
	v_exp_f32_e32 v26, v22
	v_mul_f32_e32 v22, 0xbfb8aa3b, v27
	v_exp_f32_e32 v27, v22
	s_nop 0
	v_pk_add_f32 v[26:27], v[26:27], 1.0 op_sel_hi:[1,0]
	s_nop 0
	v_mul_f32_e32 v22, v26, v27
	v_rcp_f32_e32 v22, v22
	v_and_b32_e32 v27, 0xffff0000, v72
	v_mul_f32_e32 v26, v42, v22
	v_add_f32_e32 v22, v23, v31
	v_and_b32_e32 v23, 0xffff0000, v76
	v_mul_f32_e32 v27, v23, v27
	v_mul_f32_e32 v22, 0xbfb8aa3b, v22
	v_mul_f32_e32 v23, 0xbfb8aa3b, v23
	v_exp_f32_e32 v22, v22
	v_exp_f32_e32 v23, v23
	s_nop 0
	v_pk_add_f32 v[22:23], v[22:23], 1.0 op_sel_hi:[1,0]
	s_nop 0
	v_mul_f32_e32 v22, v22, v23
	v_rcp_f32_e32 v22, v22
	v_lshlrev_b32_e32 v23, 16, v73
	v_mul_f32_e32 v27, v27, v22
	v_add_f32_e32 v22, v24, v32
	v_lshlrev_b32_e32 v24, 16, v77
	v_mul_f32_e32 v42, v24, v23
	v_mul_f32_e32 v22, 0xbfb8aa3b, v22
	v_mul_f32_e32 v23, 0xbfb8aa3b, v24
	v_exp_f32_e32 v22, v22
	v_exp_f32_e32 v23, v23
	v_and_b32_e32 v24, 0xffff0000, v73
	v_pk_add_f32 v[22:23], v[22:23], 1.0 op_sel_hi:[1,0]
	s_nop 0
	v_mul_f32_e32 v22, v22, v23
	v_rcp_f32_e32 v22, v22
	v_and_b32_e32 v23, 0xffff0000, v77
	v_mul_f32_e32 v24, v23, v24
	v_mul_f32_e32 v23, 0xbfb8aa3b, v23
	v_mul_f32_e32 v42, v42, v22
	v_add_f32_e32 v22, v25, v33
	v_mul_f32_e32 v22, 0xbfb8aa3b, v22
	v_exp_f32_e32 v22, v22
	v_exp_f32_e32 v23, v23
	s_nop 0
	v_pk_add_f32 v[22:23], v[22:23], 1.0 op_sel_hi:[1,0]
	s_nop 0
	v_mul_f32_e32 v22, v22, v23
	v_rcp_f32_e32 v22, v22
	s_nop 0
	v_mul_f32_e32 v25, v24, v22
	v_cvt_pk_bf16_f32 v22, v36, v37
	v_cvt_pk_bf16_f32 v23, v28, v29
	v_cvt_pk_bf16_f32 v24, v26, v27
	v_cvt_pk_bf16_f32 v25, v42, v25
	flat_store_dwordx4 v[34:35], v[22:25] offset:256
	s_waitcnt vmcnt(0) lgkmcnt(0)
; __device__ __forceinline__ float glu2(float z, float a, float g) { return z * g * __builtin_amdgcn_rcpf((1.0f + __expf(-a)) * (1.0f + __expf(-g))); }
	s_nop 0
	v_lshlrev_b32_e32 v24, 16, v62
	v_lshlrev_b32_e32 v25, 16, v66
	v_mul_f32_e32 v26, v25, v24
	v_exp_f32_e32 v24, v18
	v_mul_f32_e32 v18, 0xbfb8aa3b, v25
	v_exp_f32_e32 v25, v18
	v_lshlrev_b64 v[22:23], 12, v[86:87]
	v_pk_add_f32 v[24:25], v[24:25], 1.0 op_sel_hi:[1,0]
	s_nop 0
	v_mul_f32_e32 v18, v24, v25
	v_rcp_f32_e32 v18, v18
	v_and_b32_e32 v25, 0xffff0000, v62
	v_mul_f32_e32 v24, v26, v18
	v_add_f32_e32 v18, v19, v51
	v_and_b32_e32 v19, 0xffff0000, v66
	v_mul_f32_e32 v25, v19, v25
	v_mul_f32_e32 v18, 0xbfb8aa3b, v18
	v_mul_f32_e32 v19, 0xbfb8aa3b, v19
	v_exp_f32_e32 v18, v18
	v_exp_f32_e32 v19, v19
	s_nop 0
	v_pk_add_f32 v[18:19], v[18:19], 1.0 op_sel_hi:[1,0]
	s_nop 0
	v_mul_f32_e32 v18, v18, v19
	v_rcp_f32_e32 v18, v18
	v_lshlrev_b32_e32 v19, 16, v63
	v_mul_f32_e32 v25, v25, v18
	v_add_f32_e32 v18, v20, v52
	v_lshlrev_b32_e32 v20, 16, v67
	v_mul_f32_e32 v26, v20, v19
	v_mul_f32_e32 v18, 0xbfb8aa3b, v18
	v_mul_f32_e32 v19, 0xbfb8aa3b, v20
	v_exp_f32_e32 v18, v18
	v_exp_f32_e32 v19, v19
	s_nop 0
	v_pk_add_f32 v[18:19], v[18:19], 1.0 op_sel_hi:[1,0]
	s_nop 0
	v_mul_f32_e32 v18, v18, v19
	v_rcp_f32_e32 v18, v18
	v_and_b32_e32 v19, 0xffff0000, v67
	v_mul_f32_e32 v20, v26, v18
	v_add_f32_e32 v18, v21, v53
	v_and_b32_e32 v21, 0xffff0000, v63
	v_mul_f32_e32 v21, v19, v21
	v_mul_f32_e32 v18, 0xbfb8aa3b, v18
	v_mul_f32_e32 v19, 0xbfb8aa3b, v19
	v_exp_f32_e32 v18, v18
	v_exp_f32_e32 v19, v19
	s_nop 0
	v_pk_add_f32 v[18:19], v[18:19], 1.0 op_sel_hi:[1,0]
	s_nop 0
	v_mul_f32_e32 v18, v18, v19
	v_rcp_f32_e32 v18, v18
	v_lshlrev_b32_e32 v19, 16, v68
	v_mul_f32_e32 v21, v21, v18
	v_lshlrev_b32_e32 v18, 16, v64
	v_mul_f32_e32 v26, v19, v18
	v_exp_f32_e32 v18, v8
	v_mul_f32_e32 v8, 0xbfb8aa3b, v19
	v_exp_f32_e32 v19, v8
	s_nop 0
	v_pk_add_f32 v[18:19], v[18:19], 1.0 op_sel_hi:[1,0]
	s_nop 0
	v_mul_f32_e32 v8, v18, v19
	v_rcp_f32_e32 v8, v8
	v_and_b32_e32 v18, 0xffff0000, v64
	v_mul_f32_e32 v26, v26, v8
	v_add_f32_e32 v8, v9, v47
	v_and_b32_e32 v9, 0xffff0000, v68
	v_mul_f32_e32 v18, v9, v18
	v_mul_f32_e32 v8, 0xbfb8aa3b, v8
	v_mul_f32_e32 v9, 0xbfb8aa3b, v9
	v_exp_f32_e32 v8, v8
	v_exp_f32_e32 v9, v9
	s_nop 0
	v_pk_add_f32 v[8:9], v[8:9], 1.0 op_sel_hi:[1,0]
	s_nop 0
	v_mul_f32_e32 v8, v8, v9
	v_rcp_f32_e32 v8, v8
	v_lshlrev_b32_e32 v9, 16, v65
	v_mul_f32_e32 v27, v18, v8
	v_add_f32_e32 v8, v10, v48
	v_lshlrev_b32_e32 v10, 16, v69
	v_mul_f32_e32 v18, v10, v9
	v_mul_f32_e32 v8, 0xbfb8aa3b, v8
	v_mul_f32_e32 v9, 0xbfb8aa3b, v10
	v_exp_f32_e32 v8, v8
	v_exp_f32_e32 v9, v9
	s_nop 0
	v_pk_add_f32 v[8:9], v[8:9], 1.0 op_sel_hi:[1,0]
	s_nop 0
	v_mul_f32_e32 v8, v8, v9
	v_rcp_f32_e32 v8, v8
	v_and_b32_e32 v9, 0xffff0000, v69
	v_mul_f32_e32 v10, v18, v8
	v_add_f32_e32 v8, v11, v49
	v_and_b32_e32 v11, 0xffff0000, v65
	v_mul_f32_e32 v11, v9, v11
	v_mul_f32_e32 v8, 0xbfb8aa3b, v8
	v_mul_f32_e32 v9, 0xbfb8aa3b, v9
	v_exp_f32_e32 v8, v8
	v_exp_f32_e32 v9, v9
	v_cvt_pk_bf16_f32 v18, v24, v25
	v_cvt_pk_bf16_f32 v19, v20, v21
	v_cvt_pk_bf16_f32 v20, v26, v27
	s_nop 0
	v_pk_add_f32 v[8:9], v[8:9], 1.0 op_sel_hi:[1,0]
	s_nop 0
	v_mul_f32_e32 v8, v8, v9
	v_rcp_f32_e32 v8, v8
	s_nop 0
	v_mul_f32_e32 v8, v11, v8
	v_cvt_pk_bf16_f32 v21, v10, v8
	v_lshl_add_u64 v[8:9], s[42:43], 0, v[22:23]
	v_lshl_add_u64 v[8:9], v[8:9], 0, v[204:205]
	v_lshlrev_b32_e32 v10, 16, v54
	v_lshlrev_b32_e32 v11, 16, v58
	flat_store_dwordx4 v[8:9], v[18:21]
	s_nop 1
	v_mul_f32_e32 v18, v11, v10
	v_exp_f32_e32 v10, v4
	v_mul_f32_e32 v4, 0xbfb8aa3b, v11
	v_exp_f32_e32 v11, v4
	s_nop 0
	v_pk_add_f32 v[10:11], v[10:11], 1.0 op_sel_hi:[1,0]
	s_nop 0
	v_mul_f32_e32 v4, v10, v11
	v_rcp_f32_e32 v4, v4
	v_and_b32_e32 v11, 0xffff0000, v54
	v_mul_f32_e32 v10, v18, v4
	v_add_f32_e32 v4, v5, v39
	v_and_b32_e32 v5, 0xffff0000, v58
	v_mul_f32_e32 v11, v5, v11
	v_mul_f32_e32 v4, 0xbfb8aa3b, v4
	v_mul_f32_e32 v5, 0xbfb8aa3b, v5
	v_exp_f32_e32 v4, v4
	v_exp_f32_e32 v5, v5
	s_nop 0
	v_pk_add_f32 v[4:5], v[4:5], 1.0 op_sel_hi:[1,0]
	s_nop 0
	v_mul_f32_e32 v4, v4, v5
	v_rcp_f32_e32 v4, v4
	v_lshlrev_b32_e32 v5, 16, v55
	v_mul_f32_e32 v11, v11, v4
	v_add_f32_e32 v4, v6, v40
	v_lshlrev_b32_e32 v6, 16, v59
	v_mul_f32_e32 v18, v6, v5
	v_mul_f32_e32 v4, 0xbfb8aa3b, v4
	v_mul_f32_e32 v5, 0xbfb8aa3b, v6
	v_exp_f32_e32 v4, v4
	v_exp_f32_e32 v5, v5
	s_nop 0
	v_pk_add_f32 v[4:5], v[4:5], 1.0 op_sel_hi:[1,0]
	s_nop 0
	v_mul_f32_e32 v4, v4, v5
	v_rcp_f32_e32 v4, v4
	v_and_b32_e32 v5, 0xffff0000, v59
	v_mul_f32_e32 v6, v18, v4
	v_add_f32_e32 v4, v7, v41
	v_and_b32_e32 v7, 0xffff0000, v55
	v_mul_f32_e32 v7, v5, v7
	v_mul_f32_e32 v4, 0xbfb8aa3b, v4
	v_mul_f32_e32 v5, 0xbfb8aa3b, v5
	v_exp_f32_e32 v4, v4
	v_exp_f32_e32 v5, v5
	s_nop 0
	v_pk_add_f32 v[4:5], v[4:5], 1.0 op_sel_hi:[1,0]
	s_nop 0
	v_mul_f32_e32 v4, v4, v5
	v_rcp_f32_e32 v4, v4
	v_lshlrev_b32_e32 v5, 16, v60
	v_mul_f32_e32 v7, v7, v4
	v_lshlrev_b32_e32 v4, 16, v56
	v_mul_f32_e32 v18, v5, v4
	v_exp_f32_e32 v4, v0
	v_mul_f32_e32 v0, 0xbfb8aa3b, v5
	v_exp_f32_e32 v5, v0
	s_nop 0
	v_pk_add_f32 v[4:5], v[4:5], 1.0 op_sel_hi:[1,0]
	s_nop 0
	v_mul_f32_e32 v0, v4, v5
	v_rcp_f32_e32 v0, v0
	v_and_b32_e32 v5, 0xffff0000, v56
	v_mul_f32_e32 v4, v18, v0
	v_add_f32_e32 v0, v1, v31
	v_and_b32_e32 v1, 0xffff0000, v60
	v_mul_f32_e32 v5, v1, v5
	v_mul_f32_e32 v0, 0xbfb8aa3b, v0
	v_mul_f32_e32 v1, 0xbfb8aa3b, v1
	v_exp_f32_e32 v0, v0
	v_exp_f32_e32 v1, v1
	s_nop 0
	v_pk_add_f32 v[0:1], v[0:1], 1.0 op_sel_hi:[1,0]
	s_nop 0
	v_mul_f32_e32 v0, v0, v1
	v_rcp_f32_e32 v0, v0
	v_lshlrev_b32_e32 v1, 16, v57
	v_mul_f32_e32 v5, v5, v0
	v_add_f32_e32 v0, v2, v32
	v_lshlrev_b32_e32 v2, 16, v61
	v_mul_f32_e32 v18, v2, v1
	v_mul_f32_e32 v0, 0xbfb8aa3b, v0
	v_mul_f32_e32 v1, 0xbfb8aa3b, v2
	v_exp_f32_e32 v0, v0
	v_exp_f32_e32 v1, v1
	v_and_b32_e32 v2, 0xffff0000, v57
	v_pk_add_f32 v[0:1], v[0:1], 1.0 op_sel_hi:[1,0]
	s_nop 0
	v_mul_f32_e32 v0, v0, v1
	v_rcp_f32_e32 v0, v0
	v_and_b32_e32 v1, 0xffff0000, v61
	v_mul_f32_e32 v2, v1, v2
	v_mul_f32_e32 v1, 0xbfb8aa3b, v1
	v_mul_f32_e32 v18, v18, v0
	v_add_f32_e32 v0, v3, v33
	v_mul_f32_e32 v0, 0xbfb8aa3b, v0
	v_exp_f32_e32 v0, v0
	v_exp_f32_e32 v1, v1
	s_nop 0
	v_pk_add_f32 v[0:1], v[0:1], 1.0 op_sel_hi:[1,0]
	s_nop 0
	v_mul_f32_e32 v0, v0, v1
	v_rcp_f32_e32 v0, v0
	s_nop 0
	v_mul_f32_e32 v3, v2, v0
	v_cvt_pk_bf16_f32 v0, v10, v11
	v_cvt_pk_bf16_f32 v1, v6, v7
	v_cvt_pk_bf16_f32 v2, v4, v5
	v_cvt_pk_bf16_f32 v3, v18, v3
	flat_store_dwordx4 v[8:9], v[0:3] offset:256
	s_cbranch_vccz .LBB0_288
	s_waitcnt vmcnt(0)
	s_cmpk_gt_u32 s58, 0xff
	s_cbranch_scc1 .LBB0_299
	s_barrier

; #define PG8_STAGE(bufoff, gbase, voff) do { _Pragma("unroll") for (int _i = 0; _i < 2; ++_i) \
;         __builtin_amdgcn_global_load_lds((const unsigned*)((const char*)(gbase) + (voff)[_i]), (LAS unsigned*)(lds + (bufoff) + ldsw + _i * 8192), 16, 0, 0); } while (0)
; #define PG8_LDA(dst, b, h) do { _Pragma("unroll") for (int m = 0; m < 4; ++m) _Pragma("unroll") for (int k = 0; k < 2; ++k) dst[m][k] = *(const LAS bf16x8*)(lds + PG8_SA(b, h) + aoff + m * 2048 + k * 1024); } while (0)
; #define PG8_LDB(dst, b, h) do { _Pragma("unroll") for (int n = 0; n < 2; ++n) _Pragma("unroll") for (int k = 0; k < 2; ++k) dst[n][k] = *(const LAS bf16x8*)(lds + PG8_SB(b, h) + boff + n * 2048 + k * 1024); } while (0)
; #define PG8_MMA(ai, bj, At, Bt) do { __builtin_amdgcn_s_setprio(1); _Pragma("unroll") for (int m = 0; m < 4; ++m) _Pragma("unroll") for (int n = 0; n < 2; ++n) _Pragma("unroll") for (int k = 0; k < 2; ++k) \
;         acc[ai][bj][m][n] = __builtin_amdgcn_mfma_f32_16x16x32_bf16(Bt[n][k], At[m][k], acc[ai][bj][m][n], 0, 0, 0); __builtin_amdgcn_s_setprio(0); } while (0)
; #define PG8_WAIT_L(n) asm volatile("s_waitcnt lgkmcnt(" #n ")" ::: "memory")
; #define PG8_BAR __builtin_amdgcn_s_barrier()
; #define PG8_SCHED __builtin_amdgcn_sched_barrier(0)
; template <class Epi, class Sched>
; __device__ __forceinline__ void gemm_phase(const int TID, LAS unsigned char* lds, const int lda, const int ldb, const Sched& S, const Epi& E) {
;     ...
;             const bool last = (t == nt - 2);
;             const char* a1 = cA + (size_t)(t + 1) * kstep;
;             const char* a2 = last ? nA : cA + (size_t)(t + 2) * kstep; const char* b2 = last ? nB : cB + (size_t)(t + 2) * kstep;
;             const char* a3 = a2 + kstep; const char* b3 = b2 + kstep;
;             PG8_LDB(B0, 0, 0); PG8_SCHED; PG8_LDA(At, 0, 0); PG8_STAGE(PG8_SA(1, 1), a1 + hA, voffA);
;             PG8_WAIT_L(8); PG8_BAR; PG8_WAIT_L(0); PG8_MMA(0, 0, At, B0); PG8_BAR; PG8_SCHED;
;             PG8_LDB(B1, 0, 1); PG8_STAGE(PG8_SB(0, 0), b2, voffB);
;             PG8_BAR; PG8_WAIT_L(0); PG8_MMA(0, 1, At, B1); PG8_BAR;
;             PG8_LDA(At, 0, 1); PG8_STAGE(PG8_SA(0, 0), a2, voffA);
;             PG8_BAR; PG8_WAIT_L(0); PG8_MMA(1, 0, At, B0); PG8_BAR; PG8_SCHED;
.LBB0_310:
	s_add_u32 s8, s48, 0xfffe0080
	s_addc_u32 s9, s49, -1
	s_add_i32 s10, 0, 0x10000
	v_add_u32_e32 v153, s10, v149
	ds_read_b128 v[154:157], v153
	ds_read_b128 v[158:161], v153 offset:1024
	ds_read_b128 v[162:165], v153 offset:2048
	ds_read_b128 v[166:169], v153 offset:3072
	s_cmp_eq_u32 s23, 4
	s_cselect_b32 s53, s41, s9
	s_cselect_b32 s52, s40, s8
	s_cselect_b32 s51, s43, s21
	s_cselect_b32 s50, s42, s3
	v_lshl_add_u64 v[186:187], s[48:49], 0, v[144:145]
	s_add_i32 m0, s59, 0xc000
	ds_read_b128 v[170:173], v152
	ds_read_b128 v[174:177], v152 offset:1024
	ds_read_b128 v[178:181], v152 offset:2048
	ds_read_b128 v[196:199], v152 offset:3072
	ds_read_b128 v[200:203], v152 offset:4096
	ds_read_b128 v[204:207], v152 offset:5120
	ds_read_b128 v[208:211], v152 offset:6144
	ds_read_b128 v[212:215], v152 offset:7168
	global_load_lds_dwordx4 v[186:187], off
	s_add_i32 m0, s59, 0xe000
	v_lshl_add_u64 v[186:187], s[48:49], 0, v[142:143]
	global_load_lds_dwordx4 v[186:187], off
	s_waitcnt lgkmcnt(8)
	s_barrier
	s_waitcnt lgkmcnt(0)
	s_setprio 1
	s_waitcnt lgkmcnt(0)
	v_mfma_f32_16x16x32_bf16 v[130:133], v[154:157], v[170:173], v[130:133]
	v_mfma_f32_16x16x32_bf16 v[126:129], v[162:165], v[170:173], v[126:129]
	v_mfma_f32_16x16x32_bf16 v[114:117], v[154:157], v[178:181], v[114:117]
	v_mfma_f32_16x16x32_bf16 v[110:113], v[162:165], v[178:181], v[110:113]
	v_mfma_f32_16x16x32_bf16 v[98:101], v[154:157], v[200:203], v[98:101]
	v_mfma_f32_16x16x32_bf16 v[94:97], v[162:165], v[200:203], v[94:97]
	v_mfma_f32_16x16x32_bf16 v[82:85], v[154:157], v[208:211], v[82:85]
	v_mfma_f32_16x16x32_bf16 v[78:81], v[162:165], v[208:211], v[78:81]
	v_mfma_f32_16x16x32_bf16 v[130:133], v[158:161], v[174:177], v[130:133]
	v_mfma_f32_16x16x32_bf16 v[126:129], v[166:169], v[174:177], v[126:129]
	v_mfma_f32_16x16x32_bf16 v[114:117], v[158:161], v[196:199], v[114:117]
	v_mfma_f32_16x16x32_bf16 v[110:113], v[166:169], v[196:199], v[110:113]
	v_mfma_f32_16x16x32_bf16 v[98:101], v[158:161], v[204:207], v[98:101]
	v_mfma_f32_16x16x32_bf16 v[94:97], v[166:169], v[204:207], v[94:97]
	v_mfma_f32_16x16x32_bf16 v[82:85], v[158:161], v[212:215], v[82:85]
	v_mfma_f32_16x16x32_bf16 v[78:81], v[166:169], v[212:215], v[78:81]
	s_setprio 0
	s_barrier
	s_add_i32 s11, 0, 0x14000
	s_add_i32 s8, s10, s58
	v_add_u32_e32 v153, s11, v149
	v_lshl_add_u64 v[186:187], s[50:51], 0, v[136:137]
	s_mov_b32 m0, s8
	ds_read_b128 v[216:219], v153
	ds_read_b128 v[220:223], v153 offset:1024
	ds_read_b128 v[236:239], v153 offset:2048
	ds_read_b128 v[240:243], v153 offset:3072
	global_load_lds_dwordx4 v[186:187], off
	s_add_i32 m0, s8, 0x2000
	v_lshl_add_u64 v[188:189], s[50:51], 0, v[12:13]
	global_load_lds_dwordx4 v[188:189], off
	s_barrier
	s_waitcnt lgkmcnt(0)
	s_setprio 1
	s_waitcnt lgkmcnt(0)
	v_mfma_f32_16x16x32_bf16 v[122:125], v[216:219], v[170:173], v[122:125]
	v_mfma_f32_16x16x32_bf16 v[118:121], v[236:239], v[170:173], v[118:121]
	v_mfma_f32_16x16x32_bf16 v[106:109], v[216:219], v[178:181], v[106:109]
	v_mfma_f32_16x16x32_bf16 v[102:105], v[236:239], v[178:181], v[102:105]
	v_mfma_f32_16x16x32_bf16 v[90:93], v[216:219], v[200:203], v[90:93]
	v_mfma_f32_16x16x32_bf16 v[86:89], v[236:239], v[200:203], v[86:89]
	v_mfma_f32_16x16x32_bf16 v[74:77], v[216:219], v[208:211], v[74:77]
	v_mfma_f32_16x16x32_bf16 v[70:73], v[236:239], v[208:211], v[70:73]
	v_mfma_f32_16x16x32_bf16 v[122:125], v[220:223], v[174:177], v[122:125]
	v_mfma_f32_16x16x32_bf16 v[118:121], v[240:243], v[174:177], v[118:121]
	v_mfma_f32_16x16x32_bf16 v[106:109], v[220:223], v[196:199], v[106:109]
	v_mfma_f32_16x16x32_bf16 v[102:105], v[240:243], v[196:199], v[102:105]
	v_mfma_f32_16x16x32_bf16 v[90:93], v[220:223], v[204:207], v[90:93]
	v_mfma_f32_16x16x32_bf16 v[86:89], v[240:243], v[204:207], v[86:89]
	v_mfma_f32_16x16x32_bf16 v[74:77], v[220:223], v[212:215], v[74:77]
	v_mfma_f32_16x16x32_bf16 v[70:73], v[240:243], v[212:215], v[70:73]
	s_setprio 0
	s_mov_b32 m0, s59
	v_lshl_add_u64 v[244:245], s[52:53], 0, v[138:139]
	s_barrier
	ds_read_b128 v[170:173], v152 offset:16384
	ds_read_b128 v[174:177], v152 offset:17408
	ds_read_b128 v[178:181], v152 offset:18432
	ds_read_b128 v[196:199], v152 offset:19456
	ds_read_b128 v[200:203], v152 offset:20480
	ds_read_b128 v[204:207], v152 offset:21504
	ds_read_b128 v[208:211], v152 offset:22528
	ds_read_b128 v[212:215], v152 offset:23552
	global_load_lds_dwordx4 v[244:245], off
	s_mov_b32 m0, s60
	v_lshl_add_u64 v[246:247], s[52:53], 0, v[134:135]
	global_load_lds_dwordx4 v[246:247], off
	s_barrier
	s_waitcnt lgkmcnt(0)
	s_setprio 1
	s_waitcnt lgkmcnt(0)
	v_mfma_f32_16x16x32_bf16 v[66:69], v[154:157], v[170:173], v[66:69]
	v_mfma_f32_16x16x32_bf16 v[62:65], v[162:165], v[170:173], v[62:65]
	v_mfma_f32_16x16x32_bf16 v[50:53], v[154:157], v[178:181], v[50:53]
	v_mfma_f32_16x16x32_bf16 v[46:49], v[162:165], v[178:181], v[46:49]
	v_mfma_f32_16x16x32_bf16 v[34:37], v[154:157], v[200:203], v[34:37]
	v_mfma_f32_16x16x32_bf16 v[30:33], v[162:165], v[200:203], v[30:33]
	v_mfma_f32_16x16x32_bf16 v[18:21], v[154:157], v[208:211], v[18:21]
	v_mfma_f32_16x16x32_bf16 v[8:11], v[162:165], v[208:211], v[8:11]
	v_mfma_f32_16x16x32_bf16 v[66:69], v[158:161], v[174:177], v[66:69]
	v_mfma_f32_16x16x32_bf16 v[62:65], v[166:169], v[174:177], v[62:65]
	v_mfma_f32_16x16x32_bf16 v[50:53], v[158:161], v[196:199], v[50:53]
	v_mfma_f32_16x16x32_bf16 v[46:49], v[166:169], v[196:199], v[46:49]
	v_mfma_f32_16x16x32_bf16 v[34:37], v[158:161], v[204:207], v[34:37]
	v_mfma_f32_16x16x32_bf16 v[30:33], v[166:169], v[204:207], v[30:33]
	v_mfma_f32_16x16x32_bf16 v[18:21], v[158:161], v[212:215], v[18:21]
	v_mfma_f32_16x16x32_bf16 v[8:11], v[166:169], v[212:215], v[8:11]
	s_setprio 0
	s_barrier
; #define PG8_STAGE(bufoff, gbase, voff) do { _Pragma("unroll") for (int _i = 0; _i < 2; ++_i) \
;         __builtin_amdgcn_global_load_lds((const unsigned*)((const char*)(gbase) + (voff)[_i]), (LAS unsigned*)(lds + (bufoff) + ldsw + _i * 8192), 16, 0, 0); } while (0)
; #define PG8_LDA(dst, b, h) do { _Pragma("unroll") for (int m = 0; m < 4; ++m) _Pragma("unroll") for (int k = 0; k < 2; ++k) dst[m][k] = *(const LAS bf16x8*)(lds + PG8_SA(b, h) + aoff + m * 2048 + k * 1024); } while (0)
; #define PG8_LDB(dst, b, h) do { _Pragma("unroll") for (int n = 0; n < 2; ++n) _Pragma("unroll") for (int k = 0; k < 2; ++k) dst[n][k] = *(const LAS bf16x8*)(lds + PG8_SB(b, h) + boff + n * 2048 + k * 1024); } while (0)
; #define PG8_MMA(ai, bj, At, Bt) do { __builtin_amdgcn_s_setprio(1); _Pragma("unroll") for (int m = 0; m < 4; ++m) _Pragma("unroll") for (int n = 0; n < 2; ++n) _Pragma("unroll") for (int k = 0; k < 2; ++k) \
;         acc[ai][bj][m][n] = __builtin_amdgcn_mfma_f32_16x16x32_bf16(Bt[n][k], At[m][k], acc[ai][bj][m][n], 0, 0, 0); __builtin_amdgcn_s_setprio(0); } while (0)
; #define PG8_WAIT_V(n) asm volatile("s_waitcnt vmcnt(" #n ")" ::: "memory")
; #define PG8_WAIT_L(n) asm volatile("s_waitcnt lgkmcnt(" #n ")" ::: "memory")
; #define PG8_BAR __builtin_amdgcn_s_barrier()
; #define PG8_SCHED __builtin_amdgcn_sched_barrier(0)
; template <class Epi, class Sched>
; __device__ __forceinline__ void gemm_phase(const int TID, LAS unsigned char* lds, const int lda, const int ldb, const Sched& S, const Epi& E) {
;     ...
;             PG8_STAGE(PG8_SB(0, 1), b2 + hB, voffB);
;             PG8_WAIT_V(6); PG8_BAR; PG8_MMA(1, 1, At, B1); PG8_BAR;
;             PG8_LDB(B0, 1, 0); PG8_SCHED; PG8_LDA(At, 1, 0); PG8_STAGE(PG8_SA(0, 1), a2 + hA, voffA);
;             PG8_WAIT_L(8); PG8_BAR; PG8_WAIT_L(0); PG8_MMA(0, 0, At, B0); PG8_BAR; PG8_SCHED;
;             PG8_LDB(B1, 1, 1); PG8_STAGE(PG8_SB(1, 0), b3, voffB);
;             PG8_BAR; PG8_WAIT_L(0); PG8_MMA(0, 1, At, B1); PG8_BAR;
;             PG8_LDA(At, 1, 1); PG8_STAGE(PG8_SA(1, 0), a3, voffA);
;             PG8_BAR; PG8_WAIT_L(0); PG8_MMA(1, 0, At, B0); PG8_BAR; PG8_SCHED;
	s_add_u32 s8, s50, 0x20000
	s_addc_u32 s9, s51, 0
	s_add_i32 s10, s11, s58
	s_mov_b32 m0, s10
	v_lshl_add_u64 v[154:155], s[8:9], 0, v[136:137]
	global_load_lds_dwordx4 v[154:155], off
	s_add_i32 m0, s10, 0x2000
	v_lshl_add_u64 v[154:155], s[8:9], 0, v[12:13]
	global_load_lds_dwordx4 v[154:155], off
	s_waitcnt vmcnt(6)
	s_barrier
	s_setprio 1
	v_mfma_f32_16x16x32_bf16 v[58:61], v[216:219], v[170:173], v[58:61]
	v_mfma_f32_16x16x32_bf16 v[54:57], v[236:239], v[170:173], v[54:57]
	v_mfma_f32_16x16x32_bf16 v[42:45], v[216:219], v[178:181], v[42:45]
	v_mfma_f32_16x16x32_bf16 v[38:41], v[236:239], v[178:181], v[38:41]
	v_mfma_f32_16x16x32_bf16 v[26:29], v[216:219], v[200:203], v[26:29]
	v_mfma_f32_16x16x32_bf16 v[22:25], v[236:239], v[200:203], v[22:25]
	v_mfma_f32_16x16x32_bf16 v[4:7], v[216:219], v[208:211], v[4:7]
	v_mfma_f32_16x16x32_bf16 v[0:3], v[236:239], v[208:211], v[0:3]
	v_mfma_f32_16x16x32_bf16 v[58:61], v[220:223], v[174:177], v[58:61]
	v_mfma_f32_16x16x32_bf16 v[54:57], v[240:243], v[174:177], v[54:57]
	v_mfma_f32_16x16x32_bf16 v[42:45], v[220:223], v[196:199], v[42:45]
	v_mfma_f32_16x16x32_bf16 v[38:41], v[240:243], v[196:199], v[38:41]
	v_mfma_f32_16x16x32_bf16 v[26:29], v[220:223], v[204:207], v[26:29]
	v_mfma_f32_16x16x32_bf16 v[22:25], v[240:243], v[204:207], v[22:25]
	v_mfma_f32_16x16x32_bf16 v[4:7], v[220:223], v[212:215], v[4:7]
	v_mfma_f32_16x16x32_bf16 v[0:3], v[240:243], v[212:215], v[0:3]
	s_setprio 0
	s_add_i32 s10, 0, 0x18000
	v_add_u32_e32 v153, s10, v149
	s_barrier
	ds_read_b128 v[154:157], v153
	ds_read_b128 v[158:161], v153 offset:1024
	ds_read_b128 v[162:165], v153 offset:2048
	ds_read_b128 v[166:169], v153 offset:3072
	s_add_u32 s8, s52, 0x20000
	s_addc_u32 s9, s53, 0
	s_mov_b32 m0, s61
	v_lshl_add_u64 v[216:217], s[8:9], 0, v[138:139]
	ds_read_b128 v[170:173], v152 offset:32768
	ds_read_b128 v[174:177], v152 offset:33792
	ds_read_b128 v[178:181], v152 offset:34816
	ds_read_b128 v[196:199], v152 offset:35840
	ds_read_b128 v[200:203], v152 offset:36864
	ds_read_b128 v[204:207], v152 offset:37888
	ds_read_b128 v[208:211], v152 offset:38912
	ds_read_b128 v[212:215], v152 offset:39936
	global_load_lds_dwordx4 v[216:217], off
	s_mov_b32 m0, s62
	v_lshl_add_u64 v[216:217], s[8:9], 0, v[134:135]
	global_load_lds_dwordx4 v[216:217], off
	s_waitcnt lgkmcnt(8)
	s_barrier
	s_waitcnt lgkmcnt(0)
	s_setprio 1
	s_waitcnt lgkmcnt(0)
	v_mfma_f32_16x16x32_bf16 v[130:133], v[154:157], v[170:173], v[130:133]
	v_mfma_f32_16x16x32_bf16 v[126:129], v[162:165], v[170:173], v[126:129]
	v_mfma_f32_16x16x32_bf16 v[114:117], v[154:157], v[178:181], v[114:117]
	v_mfma_f32_16x16x32_bf16 v[110:113], v[162:165], v[178:181], v[110:113]
	v_mfma_f32_16x16x32_bf16 v[98:101], v[154:157], v[200:203], v[98:101]
	v_mfma_f32_16x16x32_bf16 v[94:97], v[162:165], v[200:203], v[94:97]
	v_mfma_f32_16x16x32_bf16 v[82:85], v[154:157], v[208:211], v[82:85]
	v_mfma_f32_16x16x32_bf16 v[78:81], v[162:165], v[208:211], v[78:81]
	v_mfma_f32_16x16x32_bf16 v[130:133], v[158:161], v[174:177], v[130:133]
	v_mfma_f32_16x16x32_bf16 v[126:129], v[166:169], v[174:177], v[126:129]
	v_mfma_f32_16x16x32_bf16 v[114:117], v[158:161], v[196:199], v[114:117]
	v_mfma_f32_16x16x32_bf16 v[110:113], v[166:169], v[196:199], v[110:113]
	v_mfma_f32_16x16x32_bf16 v[98:101], v[158:161], v[204:207], v[98:101]
	v_mfma_f32_16x16x32_bf16 v[94:97], v[166:169], v[204:207], v[94:97]
	v_mfma_f32_16x16x32_bf16 v[82:85], v[158:161], v[212:215], v[82:85]
	v_mfma_f32_16x16x32_bf16 v[78:81], v[166:169], v[212:215], v[78:81]
	s_setprio 0
	s_barrier
	s_add_i32 s11, 0, 0x1c000
	s_add_i32 s8, s10, s58
	v_add_u32_e32 v153, s11, v149
	v_lshl_add_u64 v[186:187], v[186:187], 0, s[36:37]
	s_mov_b32 m0, s8
	ds_read_b128 v[216:219], v153
	ds_read_b128 v[220:223], v153 offset:1024
	ds_read_b128 v[236:239], v153 offset:2048
	ds_read_b128 v[240:243], v153 offset:3072
	global_load_lds_dwordx4 v[186:187], off
	s_add_i32 m0, s8, 0x2000
	v_lshl_add_u64 v[186:187], v[188:189], 0, s[36:37]
	global_load_lds_dwordx4 v[186:187], off
	s_barrier
	s_waitcnt lgkmcnt(0)
	s_setprio 1
	s_waitcnt lgkmcnt(0)
	v_mfma_f32_16x16x32_bf16 v[122:125], v[216:219], v[170:173], v[122:125]
	v_mfma_f32_16x16x32_bf16 v[118:121], v[236:239], v[170:173], v[118:121]
	v_mfma_f32_16x16x32_bf16 v[106:109], v[216:219], v[178:181], v[106:109]
	v_mfma_f32_16x16x32_bf16 v[102:105], v[236:239], v[178:181], v[102:105]
	v_mfma_f32_16x16x32_bf16 v[90:93], v[216:219], v[200:203], v[90:93]
	v_mfma_f32_16x16x32_bf16 v[86:89], v[236:239], v[200:203], v[86:89]
	v_mfma_f32_16x16x32_bf16 v[74:77], v[216:219], v[208:211], v[74:77]
	v_mfma_f32_16x16x32_bf16 v[70:73], v[236:239], v[208:211], v[70:73]
	v_mfma_f32_16x16x32_bf16 v[122:125], v[220:223], v[174:177], v[122:125]
	v_mfma_f32_16x16x32_bf16 v[118:121], v[240:243], v[174:177], v[118:121]
	v_mfma_f32_16x16x32_bf16 v[106:109], v[220:223], v[196:199], v[106:109]
	v_mfma_f32_16x16x32_bf16 v[102:105], v[240:243], v[196:199], v[102:105]
	v_mfma_f32_16x16x32_bf16 v[90:93], v[220:223], v[204:207], v[90:93]
	v_mfma_f32_16x16x32_bf16 v[86:89], v[240:243], v[204:207], v[86:89]
	v_mfma_f32_16x16x32_bf16 v[74:77], v[220:223], v[212:215], v[74:77]
	v_mfma_f32_16x16x32_bf16 v[70:73], v[240:243], v[212:215], v[70:73]
	s_setprio 0
	s_mov_b32 m0, s63
	v_lshl_add_u64 v[186:187], v[244:245], 0, s[36:37]
	s_barrier
	ds_read_b128 v[170:173], v152 offset:49152
	ds_read_b128 v[174:177], v152 offset:50176
	ds_read_b128 v[178:181], v152 offset:51200
	ds_read_b128 v[196:199], v152 offset:52224
	ds_read_b128 v[200:203], v152 offset:53248
	ds_read_b128 v[204:207], v152 offset:54272
	ds_read_b128 v[208:211], v152 offset:55296
	ds_read_b128 v[212:215], v152 offset:56320
	global_load_lds_dwordx4 v[186:187], off
	s_mov_b32 m0, s64
	v_lshl_add_u64 v[186:187], v[246:247], 0, s[36:37]
	global_load_lds_dwordx4 v[186:187], off
	s_barrier
; #define PG8_STAGE(bufoff, gbase, voff) do { _Pragma("unroll") for (int _i = 0; _i < 2; ++_i) \
;         __builtin_amdgcn_global_load_lds((const unsigned*)((const char*)(gbase) + (voff)[_i]), (LAS unsigned*)(lds + (bufoff) + ldsw + _i * 8192), 16, 0, 0); } while (0)
; #define PG8_MMA(ai, bj, At, Bt) do { __builtin_amdgcn_s_setprio(1); _Pragma("unroll") for (int m = 0; m < 4; ++m) _Pragma("unroll") for (int n = 0; n < 2; ++n) _Pragma("unroll") for (int k = 0; k < 2; ++k) \
;         acc[ai][bj][m][n] = __builtin_amdgcn_mfma_f32_16x16x32_bf16(Bt[n][k], At[m][k], acc[ai][bj][m][n], 0, 0, 0); __builtin_amdgcn_s_setprio(0); } while (0)
; #define PG8_WAIT_V(n) asm volatile("s_waitcnt vmcnt(" #n ")" ::: "memory")
; #define PG8_WAIT_L(n) asm volatile("s_waitcnt lgkmcnt(" #n ")" ::: "memory")
; #define PG8_BAR __builtin_amdgcn_s_barrier()
; #define PG8_SCHED __builtin_amdgcn_sched_barrier(0)
; template <class Epi, class Sched>
; __device__ __forceinline__ void gemm_phase(const int TID, LAS unsigned char* lds, const int lda, const int ldb, const Sched& S, const Epi& E) {
;     ...
;             PG8_BAR; PG8_WAIT_L(0); PG8_MMA(1, 0, At, B0); PG8_BAR; PG8_SCHED;
;             PG8_STAGE(PG8_SB(1, 1), b3 + hB, voffB);
;             PG8_WAIT_V(6); PG8_BAR; PG8_MMA(1, 1, At, B1); PG8_BAR;
;         }
;         E(acc, cur, wr, wc, fr, fq);
	s_waitcnt lgkmcnt(0)
	s_setprio 1
	s_waitcnt lgkmcnt(0)
	v_mfma_f32_16x16x32_bf16 v[66:69], v[154:157], v[170:173], v[66:69]
	v_mfma_f32_16x16x32_bf16 v[62:65], v[162:165], v[170:173], v[62:65]
	v_mfma_f32_16x16x32_bf16 v[50:53], v[154:157], v[178:181], v[50:53]
	v_mfma_f32_16x16x32_bf16 v[46:49], v[162:165], v[178:181], v[46:49]
	v_mfma_f32_16x16x32_bf16 v[34:37], v[154:157], v[200:203], v[34:37]
	v_mfma_f32_16x16x32_bf16 v[30:33], v[162:165], v[200:203], v[30:33]
	v_mfma_f32_16x16x32_bf16 v[18:21], v[154:157], v[208:211], v[18:21]
	v_mfma_f32_16x16x32_bf16 v[8:11], v[162:165], v[208:211], v[8:11]
	v_mfma_f32_16x16x32_bf16 v[66:69], v[158:161], v[174:177], v[66:69]
	v_mfma_f32_16x16x32_bf16 v[62:65], v[166:169], v[174:177], v[62:65]
	v_mfma_f32_16x16x32_bf16 v[50:53], v[158:161], v[196:199], v[50:53]
	v_mfma_f32_16x16x32_bf16 v[46:49], v[166:169], v[196:199], v[46:49]
	v_mfma_f32_16x16x32_bf16 v[34:37], v[158:161], v[204:207], v[34:37]
	v_mfma_f32_16x16x32_bf16 v[30:33], v[166:169], v[204:207], v[30:33]
	v_mfma_f32_16x16x32_bf16 v[18:21], v[158:161], v[212:215], v[18:21]
	v_mfma_f32_16x16x32_bf16 v[8:11], v[166:169], v[212:215], v[8:11]
	s_setprio 0
	s_barrier
	s_add_u32 s8, s50, 0x20080
	s_addc_u32 s9, s51, 0
	s_add_i32 s10, s11, s58
	s_mov_b32 m0, s10
	v_lshl_add_u64 v[154:155], s[8:9], 0, v[136:137]
	global_load_lds_dwordx4 v[154:155], off
	s_add_i32 m0, s10, 0x2000
	v_lshl_add_u64 v[154:155], s[8:9], 0, v[12:13]
	global_load_lds_dwordx4 v[154:155], off
	s_waitcnt vmcnt(6)
	s_barrier
	s_setprio 1
	v_mfma_f32_16x16x32_bf16 v[58:61], v[216:219], v[170:173], v[58:61]
	v_mfma_f32_16x16x32_bf16 v[54:57], v[236:239], v[170:173], v[54:57]
	v_mfma_f32_16x16x32_bf16 v[42:45], v[216:219], v[178:181], v[42:45]
	v_mfma_f32_16x16x32_bf16 v[38:41], v[236:239], v[178:181], v[38:41]
	v_mfma_f32_16x16x32_bf16 v[26:29], v[216:219], v[200:203], v[26:29]
	v_mfma_f32_16x16x32_bf16 v[22:25], v[236:239], v[200:203], v[22:25]
	v_mfma_f32_16x16x32_bf16 v[4:7], v[216:219], v[208:211], v[4:7]
	v_mfma_f32_16x16x32_bf16 v[0:3], v[236:239], v[208:211], v[0:3]
	v_mfma_f32_16x16x32_bf16 v[58:61], v[220:223], v[174:177], v[58:61]
	v_mfma_f32_16x16x32_bf16 v[54:57], v[240:243], v[174:177], v[54:57]
	v_mfma_f32_16x16x32_bf16 v[42:45], v[220:223], v[196:199], v[42:45]
	v_mfma_f32_16x16x32_bf16 v[38:41], v[240:243], v[196:199], v[38:41]
	v_mfma_f32_16x16x32_bf16 v[26:29], v[220:223], v[204:207], v[26:29]
	v_mfma_f32_16x16x32_bf16 v[22:25], v[240:243], v[204:207], v[22:25]
	v_mfma_f32_16x16x32_bf16 v[4:7], v[220:223], v[212:215], v[4:7]
	v_mfma_f32_16x16x32_bf16 v[0:3], v[240:243], v[212:215], v[0:3]
	s_setprio 0
	s_add_i32 s23, s23, 2
	s_add_u32 s3, s3, 0x100
	s_addc_u32 s21, s21, 0
	s_add_u32 s48, s48, 0x100
	s_addc_u32 s49, s49, 0
	s_cmp_gt_u32 s23, 5
	s_barrier
	s_cbranch_scc0 .LBB0_310
	v_lshl_add_u32 v153, s2, 8, v148
	v_cmp_gt_i32_e32 vcc, s47, v153
	v_lshlrev_b32_e32 v182, 1, v140
	s_and_saveexec_b64 s[2:3], vcc
	s_cbranch_execz .LBB0_313
; __device__ __forceinline__ float sigm(float x) { return __builtin_amdgcn_rcpf(1.0f + __expf(-x)); }
; __device__ __forceinline__ float silu(float x) { return x * sigm(x); }
; __device__ __forceinline__ float glu2(float z, float a, float g) { return z * g * __builtin_amdgcn_rcpf((1.0f + __expf(-a)) * (1.0f + __expf(-g))); }
	v_mul_f32_e32 v155, 0x3d372713, v130
	v_mul_f32_e32 v155, v130, v155
	v_fma_f32 v155, v130, v155, v130
	v_mul_f32_e32 v155, 0x3f4c422a, v155
	v_add_f32_e32 v155, v155, v155
	v_mul_f32_e32 v155, 0xbfb8aa3b, v155
	v_exp_f32_e32 v155, v155
	v_lshlrev_b32_e32 v154, 4, v153
	s_lshl_b32 s8, s46, 4
	s_ashr_i32 s9, s8, 31
	v_add_f32_e32 v155, 1.0, v155
	v_rcp_f32_e32 v155, v155
	s_lshl_b64 s[48:49], s[8:9], 1
	v_mul_f32_e32 v130, v130, v155
	v_mul_f32_e32 v155, 0x3d372713, v126
	v_mul_f32_e32 v155, v126, v155
	v_fma_f32 v155, v126, v155, v126
	v_mul_f32_e32 v155, 0x3f4c422a, v155
	v_add_f32_e32 v155, v155, v155
	v_mul_f32_e32 v155, 0xbfb8aa3b, v155
	v_exp_f32_e32 v155, v155
	s_nop 0
	v_add_f32_e32 v155, 1.0, v155
	v_rcp_f32_e32 v155, v155
	s_nop 0
	v_mul_f32_e32 v155, v126, v155
	v_mul_f32_e32 v126, 0x3d372713, v131
	v_mul_f32_e32 v126, v131, v126
	v_fma_f32 v126, v131, v126, v131
	v_mul_f32_e32 v126, 0x3f4c422a, v126
	v_add_f32_e32 v126, v126, v126
	v_mul_f32_e32 v126, 0xbfb8aa3b, v126
	v_exp_f32_e32 v126, v126
	s_nop 0
	v_add_f32_e32 v126, 1.0, v126
	v_rcp_f32_e32 v126, v126
	s_nop 0
	v_mul_f32_e32 v126, v131, v126
	v_mul_f32_e32 v131, 0x3d372713, v127
	v_mul_f32_e32 v131, v127, v131
	v_fma_f32 v131, v127, v131, v127
	v_mul_f32_e32 v131, 0x3f4c422a, v131
	v_add_f32_e32 v131, v131, v131
	v_mul_f32_e32 v131, 0xbfb8aa3b, v131
	v_exp_f32_e32 v131, v131
	v_cvt_pk_bf16_f32 v126, v130, v126
	v_or_b32_e32 v130, v154, v150
	v_add_f32_e32 v131, 1.0, v131
	v_rcp_f32_e32 v131, v131
	s_nop 0
	v_mul_f32_e32 v131, v127, v131
	v_mul_f32_e32 v127, 0x3d372713, v132
	v_mul_f32_e32 v127, v132, v127
	v_fma_f32 v127, v132, v127, v132
	v_mul_f32_e32 v127, 0x3f4c422a, v127
	v_add_f32_e32 v127, v127, v127
	v_mul_f32_e32 v127, 0xbfb8aa3b, v127
	v_exp_f32_e32 v127, v127
	s_nop 0
	v_add_f32_e32 v127, 1.0, v127
	v_rcp_f32_e32 v127, v127
	s_nop 0
	v_mul_f32_e32 v127, v132, v127
	v_mul_f32_e32 v132, 0x3d372713, v128
	v_mul_f32_e32 v132, v128, v132
	v_fma_f32 v132, v128, v132, v128
	v_mul_f32_e32 v132, 0x3f4c422a, v132
	v_add_f32_e32 v132, v132, v132
	v_mul_f32_e32 v132, 0xbfb8aa3b, v132
	v_exp_f32_e32 v132, v132
	s_nop 0
	v_add_f32_e32 v132, 1.0, v132
	v_rcp_f32_e32 v132, v132
	s_nop 0
	v_mul_f32_e32 v132, v128, v132
	v_mul_f32_e32 v128, 0x3d372713, v133
	v_mul_f32_e32 v128, v133, v128
	v_fma_f32 v128, v133, v128, v133
	v_mul_f32_e32 v128, 0x3f4c422a, v128
	v_add_f32_e32 v128, v128, v128
	v_mul_f32_e32 v128, 0xbfb8aa3b, v128
	v_exp_f32_e32 v128, v128
	s_nop 0
	v_add_f32_e32 v128, 1.0, v128
	v_rcp_f32_e32 v128, v128
	s_nop 0
	v_mul_f32_e32 v128, v133, v128
	v_mul_f32_e32 v133, 0x3d372713, v129
	v_mul_f32_e32 v133, v129, v133
	v_fma_f32 v133, v129, v133, v129
	v_mul_f32_e32 v133, 0x3f4c422a, v133
	v_add_f32_e32 v133, v133, v133
	v_mul_f32_e32 v133, 0xbfb8aa3b, v133
	v_exp_f32_e32 v133, v133
	v_cvt_pk_bf16_f32 v127, v127, v128
	v_cvt_pk_bf16_f32 v128, v155, v131
	v_ashrrev_i32_e32 v131, 31, v130
	v_add_f32_e32 v133, 1.0, v133
	v_rcp_f32_e32 v133, v133
	v_lshlrev_b64 v[130:131], 10, v[130:131]
	v_lshl_add_u64 v[130:131], s[0:1], 0, v[130:131]
	v_lshl_add_u64 v[130:131], v[130:131], 0, s[48:49]
	v_mul_f32_e32 v129, v129, v133
	v_lshl_add_u64 v[130:131], v[130:131], 0, v[182:183]
	v_cvt_pk_bf16_f32 v129, v132, v129
	flat_store_dwordx4 v[130:131], v[126:129]
	s_nop 1
	v_mul_f32_e32 v126, 0x3d372713, v122
	v_mul_f32_e32 v126, v122, v126
	v_fma_f32 v126, v122, v126, v122
	v_mul_f32_e32 v126, 0x3f4c422a, v126
	v_add_f32_e32 v126, v126, v126
	v_mul_f32_e32 v126, 0xbfb8aa3b, v126
	v_exp_f32_e32 v126, v126
	s_nop 0
	v_add_f32_e32 v126, 1.0, v126
	v_rcp_f32_e32 v126, v126
	s_nop 0
	v_mul_f32_e32 v122, v122, v126
	v_mul_f32_e32 v126, 0x3d372713, v118
	v_mul_f32_e32 v126, v118, v126
	v_fma_f32 v126, v118, v126, v118
	v_mul_f32_e32 v126, 0x3f4c422a, v126
	v_add_f32_e32 v126, v126, v126
	v_mul_f32_e32 v126, 0xbfb8aa3b, v126
	v_exp_f32_e32 v126, v126
	s_nop 0
	v_add_f32_e32 v126, 1.0, v126
	v_rcp_f32_e32 v126, v126
	s_nop 0
	v_mul_f32_e32 v126, v118, v126
	v_mul_f32_e32 v118, 0x3d372713, v123
	v_mul_f32_e32 v118, v123, v118
	v_fma_f32 v118, v123, v118, v123
	v_mul_f32_e32 v118, 0x3f4c422a, v118
	v_add_f32_e32 v118, v118, v118
	v_mul_f32_e32 v118, 0xbfb8aa3b, v118
	v_exp_f32_e32 v118, v118
	s_nop 0
	v_add_f32_e32 v118, 1.0, v118
	v_rcp_f32_e32 v118, v118
	s_nop 0
	v_mul_f32_e32 v118, v123, v118
	v_mul_f32_e32 v123, 0x3d372713, v119
	v_mul_f32_e32 v123, v119, v123
	v_fma_f32 v123, v119, v123, v119
	v_mul_f32_e32 v123, 0x3f4c422a, v123
	v_add_f32_e32 v123, v123, v123
	v_mul_f32_e32 v123, 0xbfb8aa3b, v123
	v_exp_f32_e32 v123, v123
	v_cvt_pk_bf16_f32 v118, v122, v118
	v_or_b32_e32 v122, v154, v151
	v_add_f32_e32 v123, 1.0, v123
	v_rcp_f32_e32 v123, v123
	s_nop 0
	v_mul_f32_e32 v123, v119, v123
	v_mul_f32_e32 v119, 0x3d372713, v124
	v_mul_f32_e32 v119, v124, v119
	v_fma_f32 v119, v124, v119, v124
	v_mul_f32_e32 v119, 0x3f4c422a, v119
	v_add_f32_e32 v119, v119, v119
	v_mul_f32_e32 v119, 0xbfb8aa3b, v119
	v_exp_f32_e32 v119, v119
	s_nop 0
	v_add_f32_e32 v119, 1.0, v119
	v_rcp_f32_e32 v119, v119
	s_nop 0
	v_mul_f32_e32 v119, v124, v119
	v_mul_f32_e32 v124, 0x3d372713, v120
	v_mul_f32_e32 v124, v120, v124
	v_fma_f32 v124, v120, v124, v120
	v_mul_f32_e32 v124, 0x3f4c422a, v124
	v_add_f32_e32 v124, v124, v124
	v_mul_f32_e32 v124, 0xbfb8aa3b, v124
	v_exp_f32_e32 v124, v124
	s_nop 0
	v_add_f32_e32 v124, 1.0, v124
	v_rcp_f32_e32 v124, v124
	s_nop 0
	v_mul_f32_e32 v124, v120, v124
	v_mul_f32_e32 v120, 0x3d372713, v125
	v_mul_f32_e32 v120, v125, v120
	v_fma_f32 v120, v125, v120, v125
	v_mul_f32_e32 v120, 0x3f4c422a, v120
	v_add_f32_e32 v120, v120, v120
	v_mul_f32_e32 v120, 0xbfb8aa3b, v120
	v_exp_f32_e32 v120, v120
	s_nop 0
	v_add_f32_e32 v120, 1.0, v120
	v_rcp_f32_e32 v120, v120
	s_nop 0
	v_mul_f32_e32 v120, v125, v120
	v_mul_f32_e32 v125, 0x3d372713, v121
	v_mul_f32_e32 v125, v121, v125
	v_fma_f32 v125, v121, v125, v121
	v_mul_f32_e32 v125, 0x3f4c422a, v125
	v_add_f32_e32 v125, v125, v125
	v_mul_f32_e32 v125, 0xbfb8aa3b, v125
	v_exp_f32_e32 v125, v125
	v_cvt_pk_bf16_f32 v119, v119, v120
	v_cvt_pk_bf16_f32 v120, v126, v123
	v_ashrrev_i32_e32 v123, 31, v122
	v_add_f32_e32 v125, 1.0, v125
	v_rcp_f32_e32 v125, v125
	v_lshlrev_b64 v[122:123], 10, v[122:123]
	v_lshl_add_u64 v[122:123], s[0:1], 0, v[122:123]
	v_lshl_add_u64 v[122:123], v[122:123], 0, s[48:49]
	v_mul_f32_e32 v121, v121, v125
	v_lshl_add_u64 v[122:123], v[122:123], 0, v[182:183]
	v_cvt_pk_bf16_f32 v121, v124, v121
	flat_store_dwordx4 v[122:123], v[118:121]

; #define PG8_STAGE(bufoff, gbase, voff) do { _Pragma("unroll") for (int _i = 0; _i < 2; ++_i) \
;         __builtin_amdgcn_global_load_lds((const unsigned*)((const char*)(gbase) + (voff)[_i]), (LAS unsigned*)(lds + (bufoff) + ldsw + _i * 8192), 16, 0, 0); } while (0)
; #define PG8_LDA(dst, b, h) do { _Pragma("unroll") for (int m = 0; m < 4; ++m) _Pragma("unroll") for (int k = 0; k < 2; ++k) dst[m][k] = *(const LAS bf16x8*)(lds + PG8_SA(b, h) + aoff + m * 2048 + k * 1024); } while (0)
; #define PG8_LDB(dst, b, h) do { _Pragma("unroll") for (int n = 0; n < 2; ++n) _Pragma("unroll") for (int k = 0; k < 2; ++k) dst[n][k] = *(const LAS bf16x8*)(lds + PG8_SB(b, h) + boff + n * 2048 + k * 1024); } while (0)
; #define PG8_WAIT_V(n) asm volatile("s_waitcnt vmcnt(" #n ")" ::: "memory")
; #define PG8_WAIT_L(n) asm volatile("s_waitcnt lgkmcnt(" #n ")" ::: "memory")
; #define PG8_BAR __builtin_amdgcn_s_barrier()
; #define PG8_SCHED __builtin_amdgcn_sched_barrier(0)
; template <class Epi, class Sched>
; __device__ __forceinline__ void gemm_phase(const int TID, LAS unsigned char* lds, const int lda, const int ldb, const Sched& S, const Epi& E) {
;     ...
;         const bool has_next = S.next(ui + 1, nxt);
;         const char* nA = has_next ? nxt.a : cA; const char* nB = has_next ? nxt.b : cB;
;         const int nt = cur.nt;
;         for (int t = 0; t < nt; t += 2) {
;             const bool last = (t == nt - 2);
;             const char* a1 = cA + (size_t)(t + 1) * kstep;
;             const char* a2 = last ? nA : cA + (size_t)(t + 2) * kstep; const char* b2 = last ? nB : cB + (size_t)(t + 2) * kstep;
;             const char* a3 = a2 + kstep; const char* b3 = b2 + kstep;
;             PG8_LDB(B0, 0, 0); PG8_SCHED; PG8_LDA(At, 0, 0); PG8_STAGE(PG8_SA(1, 1), a1 + hA, voffA);
;             PG8_WAIT_L(8); PG8_BAR; PG8_WAIT_L(0); PG8_MMA(0, 0, At, B0); PG8_BAR; PG8_SCHED;
;             PG8_LDB(B1, 0, 1); PG8_STAGE(PG8_SB(0, 0), b2, voffB);
;             PG8_BAR; PG8_WAIT_L(0); PG8_MMA(0, 1, At, B1); PG8_BAR;
;             PG8_LDA(At, 0, 1); PG8_STAGE(PG8_SA(0, 0), a2, voffA);
;             PG8_BAR; PG8_WAIT_L(0); PG8_MMA(1, 0, At, B0); PG8_BAR; PG8_SCHED;
;             PG8_STAGE(PG8_SB(0, 1), b2 + hB, voffB);
;             PG8_WAIT_V(6); PG8_BAR; PG8_MMA(1, 1, At, B1); PG8_BAR;
.LBB0_732:
	s_add_u32 s3, s46, s1
	s_addc_u32 s8, s47, 0
	s_add_u32 s9, s3, 0x100
	s_addc_u32 s10, s8, 0
	s_and_b64 s[54:55], s[52:53], exec
	s_cselect_b32 s59, s29, s10
	s_cselect_b32 s58, s28, s9
	s_add_u32 s1, s48, s1
	s_addc_u32 s9, s49, 0
	s_add_u32 s1, s1, 0x100
	s_addc_u32 s9, s9, 0
	s_add_i32 s10, 0, 0x10000
	s_and_b64 s[52:53], s[52:53], exec
	s_cselect_b32 s61, s39, s9
	s_cselect_b32 s60, s38, s1
	s_add_u32 s62, s3, 0x20080
	s_addc_u32 s63, s8, 0
	s_add_i32 s80, s10, s66
	s_add_i32 m0, s43, 0xc000
	s_add_i32 s8, s43, 0xe000
	s_add_i32 s79, 0, 0x14000
	s_add_i32 s78, s80, 0x2000
	s_add_u32 s56, s60, 0x10000
	v_add_u32_e32 v158, s10, v144
	s_addc_u32 s57, s61, 0
	s_add_i32 s75, s79, s66
	ds_read_b128 v[146:149], v158
	ds_read_b128 v[150:153], v158 offset:1024
	ds_read_b128 v[154:157], v158 offset:2048
	ds_read_b128 v[158:161], v158 offset:3072
	s_add_i32 s74, s75, 0x2000
	s_add_i32 s73, 0, 0x18000
	s_add_u32 s54, s58, 0x20000
	s_addc_u32 s55, s59, 0
	s_add_i32 s72, s73, s66
	s_add_i32 s3, 0, 0x1c000
	s_add_i32 s1, s72, 0x2000
	s_add_u32 s52, s60, 0x10080
	s_addc_u32 s53, s61, 0
	s_add_i32 s77, s3, s66
	s_add_i32 s76, s77, 0x2000
	v_lshl_add_u64 v[186:187], s[62:63], 0, v[138:139]
	ds_read_b128 v[162:165], v145
	ds_read_b128 v[166:169], v145 offset:1024
	ds_read_b128 v[170:173], v145 offset:2048
	ds_read_b128 v[174:177], v145 offset:3072
	ds_read_b128 v[178:181], v145 offset:4096
	ds_read_b128 v[196:199], v145 offset:5120
	ds_read_b128 v[200:203], v145 offset:6144
	ds_read_b128 v[204:207], v145 offset:7168
	global_load_lds_dwordx4 v[186:187], off
	s_mov_b32 m0, s8
	v_lshl_add_u64 v[186:187], s[62:63], 0, v[136:137]
	global_load_lds_dwordx4 v[186:187], off
	s_waitcnt lgkmcnt(8)
	s_barrier
	s_waitcnt lgkmcnt(0)
	s_setprio 1
	s_waitcnt lgkmcnt(0)
	v_mfma_f32_16x16x32_bf16 v[130:133], v[146:149], v[162:165], v[130:133]
	v_mfma_f32_16x16x32_bf16 v[126:129], v[154:157], v[162:165], v[126:129]
	v_mfma_f32_16x16x32_bf16 v[122:125], v[146:149], v[170:173], v[122:125]
	v_mfma_f32_16x16x32_bf16 v[114:117], v[154:157], v[170:173], v[114:117]
	v_mfma_f32_16x16x32_bf16 v[106:109], v[146:149], v[178:181], v[106:109]
	v_mfma_f32_16x16x32_bf16 v[98:101], v[154:157], v[178:181], v[98:101]
	v_mfma_f32_16x16x32_bf16 v[90:93], v[146:149], v[200:203], v[90:93]
	v_mfma_f32_16x16x32_bf16 v[82:85], v[154:157], v[200:203], v[82:85]
	v_mfma_f32_16x16x32_bf16 v[130:133], v[150:153], v[166:169], v[130:133]
	v_mfma_f32_16x16x32_bf16 v[126:129], v[158:161], v[166:169], v[126:129]
	v_mfma_f32_16x16x32_bf16 v[122:125], v[150:153], v[174:177], v[122:125]
	v_mfma_f32_16x16x32_bf16 v[114:117], v[158:161], v[174:177], v[114:117]
	v_mfma_f32_16x16x32_bf16 v[106:109], v[150:153], v[196:199], v[106:109]
	v_mfma_f32_16x16x32_bf16 v[98:101], v[158:161], v[196:199], v[98:101]
	v_mfma_f32_16x16x32_bf16 v[90:93], v[150:153], v[204:207], v[90:93]
	v_mfma_f32_16x16x32_bf16 v[82:85], v[158:161], v[204:207], v[82:85]
	s_setprio 0
	s_barrier
	v_add_u32_e32 v186, s79, v144
	s_mov_b32 m0, s80
	ds_read_b128 v[208:211], v186
	ds_read_b128 v[212:215], v186 offset:1024
	ds_read_b128 v[216:219], v186 offset:2048
	ds_read_b128 v[220:223], v186 offset:3072
	v_lshl_add_u64 v[186:187], s[60:61], 0, v[182:183]
	global_load_lds_dwordx4 v[186:187], off
	s_mov_b32 m0, s78
	v_lshl_add_u64 v[188:189], s[60:61], 0, v[12:13]
	global_load_lds_dwordx4 v[188:189], off
	s_barrier
	s_waitcnt lgkmcnt(0)
	s_setprio 1
	s_waitcnt lgkmcnt(0)
	v_mfma_f32_16x16x32_bf16 v[118:121], v[208:211], v[162:165], v[118:121]
	v_mfma_f32_16x16x32_bf16 v[110:113], v[216:219], v[162:165], v[110:113]
	v_mfma_f32_16x16x32_bf16 v[102:105], v[208:211], v[170:173], v[102:105]
	v_mfma_f32_16x16x32_bf16 v[94:97], v[216:219], v[170:173], v[94:97]
	v_mfma_f32_16x16x32_bf16 v[86:89], v[208:211], v[178:181], v[86:89]
	v_mfma_f32_16x16x32_bf16 v[78:81], v[216:219], v[178:181], v[78:81]
	v_mfma_f32_16x16x32_bf16 v[74:77], v[208:211], v[200:203], v[74:77]
	v_mfma_f32_16x16x32_bf16 v[70:73], v[216:219], v[200:203], v[70:73]
	v_mfma_f32_16x16x32_bf16 v[118:121], v[212:215], v[166:169], v[118:121]
	v_mfma_f32_16x16x32_bf16 v[110:113], v[220:223], v[166:169], v[110:113]
	v_mfma_f32_16x16x32_bf16 v[102:105], v[212:215], v[174:177], v[102:105]
	v_mfma_f32_16x16x32_bf16 v[94:97], v[220:223], v[174:177], v[94:97]
	v_mfma_f32_16x16x32_bf16 v[86:89], v[212:215], v[196:199], v[86:89]
	v_mfma_f32_16x16x32_bf16 v[78:81], v[220:223], v[196:199], v[78:81]
	v_mfma_f32_16x16x32_bf16 v[74:77], v[212:215], v[204:207], v[74:77]
	v_mfma_f32_16x16x32_bf16 v[70:73], v[220:223], v[204:207], v[70:73]
	s_setprio 0
	s_mov_b32 m0, s43
	v_lshl_add_u64 v[236:237], s[58:59], 0, v[138:139]
	s_barrier
	ds_read_b128 v[162:165], v145 offset:16384
	ds_read_b128 v[166:169], v145 offset:17408
	ds_read_b128 v[170:173], v145 offset:18432
	ds_read_b128 v[174:177], v145 offset:19456
	ds_read_b128 v[178:181], v145 offset:20480
	ds_read_b128 v[196:199], v145 offset:21504
	ds_read_b128 v[200:203], v145 offset:22528
	ds_read_b128 v[204:207], v145 offset:23552
	global_load_lds_dwordx4 v[236:237], off
	s_mov_b32 m0, s45
	v_lshl_add_u64 v[238:239], s[58:59], 0, v[136:137]
	global_load_lds_dwordx4 v[238:239], off
	s_barrier
; #define PG8_STAGE(bufoff, gbase, voff) do { _Pragma("unroll") for (int _i = 0; _i < 2; ++_i) \
;         __builtin_amdgcn_global_load_lds((const unsigned*)((const char*)(gbase) + (voff)[_i]), (LAS unsigned*)(lds + (bufoff) + ldsw + _i * 8192), 16, 0, 0); } while (0)
; #define PG8_LDA(dst, b, h) do { _Pragma("unroll") for (int m = 0; m < 4; ++m) _Pragma("unroll") for (int k = 0; k < 2; ++k) dst[m][k] = *(const LAS bf16x8*)(lds + PG8_SA(b, h) + aoff + m * 2048 + k * 1024); } while (0)
; #define PG8_LDB(dst, b, h) do { _Pragma("unroll") for (int n = 0; n < 2; ++n) _Pragma("unroll") for (int k = 0; k < 2; ++k) dst[n][k] = *(const LAS bf16x8*)(lds + PG8_SB(b, h) + boff + n * 2048 + k * 1024); } while (0)
; #define PG8_MMA(ai, bj, At, Bt) do { __builtin_amdgcn_s_setprio(1); _Pragma("unroll") for (int m = 0; m < 4; ++m) _Pragma("unroll") for (int n = 0; n < 2; ++n) _Pragma("unroll") for (int k = 0; k < 2; ++k) \
;         acc[ai][bj][m][n] = __builtin_amdgcn_mfma_f32_16x16x32_bf16(Bt[n][k], At[m][k], acc[ai][bj][m][n], 0, 0, 0); __builtin_amdgcn_s_setprio(0); } while (0)
; #define PG8_WAIT_V(n) asm volatile("s_waitcnt vmcnt(" #n ")" ::: "memory")
; #define PG8_WAIT_L(n) asm volatile("s_waitcnt lgkmcnt(" #n ")" ::: "memory")
; #define PG8_BAR __builtin_amdgcn_s_barrier()
; #define PG8_SCHED __builtin_amdgcn_sched_barrier(0)
; template <class Epi, class Sched>
; __device__ __forceinline__ void gemm_phase(const int TID, LAS unsigned char* lds, const int lda, const int ldb, const Sched& S, const Epi& E) {
;     ...
;             PG8_WAIT_V(6); PG8_BAR; PG8_MMA(1, 1, At, B1); PG8_BAR;
;             PG8_LDB(B0, 1, 0); PG8_SCHED; PG8_LDA(At, 1, 0); PG8_STAGE(PG8_SA(0, 1), a2 + hA, voffA);
;             PG8_WAIT_L(8); PG8_BAR; PG8_WAIT_L(0); PG8_MMA(0, 0, At, B0); PG8_BAR; PG8_SCHED;
;             PG8_LDB(B1, 1, 1); PG8_STAGE(PG8_SB(1, 0), b3, voffB);
;             PG8_BAR; PG8_WAIT_L(0); PG8_MMA(0, 1, At, B1); PG8_BAR;
;             PG8_LDA(At, 1, 1); PG8_STAGE(PG8_SA(1, 0), a3, voffA);
;             PG8_BAR; PG8_WAIT_L(0); PG8_MMA(1, 0, At, B0); PG8_BAR; PG8_SCHED;
	s_waitcnt lgkmcnt(0)
	s_setprio 1
	s_waitcnt lgkmcnt(0)
	v_mfma_f32_16x16x32_bf16 v[66:69], v[146:149], v[162:165], v[66:69]
	v_mfma_f32_16x16x32_bf16 v[62:65], v[154:157], v[162:165], v[62:65]
	v_mfma_f32_16x16x32_bf16 v[58:61], v[146:149], v[170:173], v[58:61]
	v_mfma_f32_16x16x32_bf16 v[50:53], v[154:157], v[170:173], v[50:53]
	v_mfma_f32_16x16x32_bf16 v[42:45], v[146:149], v[178:181], v[42:45]
	v_mfma_f32_16x16x32_bf16 v[34:37], v[154:157], v[178:181], v[34:37]
	v_mfma_f32_16x16x32_bf16 v[26:29], v[146:149], v[200:203], v[26:29]
	v_mfma_f32_16x16x32_bf16 v[18:21], v[154:157], v[200:203], v[18:21]
	v_mfma_f32_16x16x32_bf16 v[66:69], v[150:153], v[166:169], v[66:69]
	v_mfma_f32_16x16x32_bf16 v[62:65], v[158:161], v[166:169], v[62:65]
	v_mfma_f32_16x16x32_bf16 v[58:61], v[150:153], v[174:177], v[58:61]
	v_mfma_f32_16x16x32_bf16 v[50:53], v[158:161], v[174:177], v[50:53]
	v_mfma_f32_16x16x32_bf16 v[42:45], v[150:153], v[196:199], v[42:45]
	v_mfma_f32_16x16x32_bf16 v[34:37], v[158:161], v[196:199], v[34:37]
	v_mfma_f32_16x16x32_bf16 v[26:29], v[150:153], v[204:207], v[26:29]
	v_mfma_f32_16x16x32_bf16 v[18:21], v[158:161], v[204:207], v[18:21]
	s_setprio 0
	s_barrier
	s_mov_b32 m0, s75
	v_lshl_add_u64 v[146:147], s[56:57], 0, v[182:183]
	global_load_lds_dwordx4 v[146:147], off
	s_mov_b32 m0, s74
	v_lshl_add_u64 v[146:147], s[56:57], 0, v[12:13]
	global_load_lds_dwordx4 v[146:147], off
	s_waitcnt vmcnt(6)
	s_barrier
	s_setprio 1
	v_mfma_f32_16x16x32_bf16 v[54:57], v[208:211], v[162:165], v[54:57]
	v_mfma_f32_16x16x32_bf16 v[46:49], v[216:219], v[162:165], v[46:49]
	v_mfma_f32_16x16x32_bf16 v[38:41], v[208:211], v[170:173], v[38:41]
	v_mfma_f32_16x16x32_bf16 v[30:33], v[216:219], v[170:173], v[30:33]
	v_mfma_f32_16x16x32_bf16 v[22:25], v[208:211], v[178:181], v[22:25]
	v_mfma_f32_16x16x32_bf16 v[8:11], v[216:219], v[178:181], v[8:11]
	v_mfma_f32_16x16x32_bf16 v[4:7], v[208:211], v[200:203], v[4:7]
	v_mfma_f32_16x16x32_bf16 v[0:3], v[216:219], v[200:203], v[0:3]
	v_mfma_f32_16x16x32_bf16 v[54:57], v[212:215], v[166:169], v[54:57]
	v_mfma_f32_16x16x32_bf16 v[46:49], v[220:223], v[166:169], v[46:49]
	v_mfma_f32_16x16x32_bf16 v[38:41], v[212:215], v[174:177], v[38:41]
	v_mfma_f32_16x16x32_bf16 v[30:33], v[220:223], v[174:177], v[30:33]
	v_mfma_f32_16x16x32_bf16 v[22:25], v[212:215], v[196:199], v[22:25]
	v_mfma_f32_16x16x32_bf16 v[8:11], v[220:223], v[196:199], v[8:11]
	v_mfma_f32_16x16x32_bf16 v[4:7], v[212:215], v[204:207], v[4:7]
	v_mfma_f32_16x16x32_bf16 v[0:3], v[220:223], v[204:207], v[0:3]
	s_setprio 0
	v_add_u32_e32 v158, s73, v144
	s_barrier
	ds_read_b128 v[146:149], v158
	ds_read_b128 v[150:153], v158 offset:1024
	ds_read_b128 v[154:157], v158 offset:2048
	ds_read_b128 v[158:161], v158 offset:3072
	s_mov_b32 m0, s67
	v_lshl_add_u64 v[208:209], s[54:55], 0, v[138:139]
	ds_read_b128 v[162:165], v145 offset:32768
	ds_read_b128 v[166:169], v145 offset:33792
	ds_read_b128 v[170:173], v145 offset:34816
	ds_read_b128 v[174:177], v145 offset:35840
	ds_read_b128 v[178:181], v145 offset:36864
	ds_read_b128 v[196:199], v145 offset:37888
	ds_read_b128 v[200:203], v145 offset:38912
	ds_read_b128 v[204:207], v145 offset:39936
	global_load_lds_dwordx4 v[208:209], off
	s_mov_b32 m0, s68
	v_lshl_add_u64 v[208:209], s[54:55], 0, v[136:137]
	global_load_lds_dwordx4 v[208:209], off
	s_waitcnt lgkmcnt(8)
	s_barrier
	s_waitcnt lgkmcnt(0)
	s_setprio 1
	s_waitcnt lgkmcnt(0)
	v_mfma_f32_16x16x32_bf16 v[130:133], v[146:149], v[162:165], v[130:133]
	v_mfma_f32_16x16x32_bf16 v[126:129], v[154:157], v[162:165], v[126:129]
	v_mfma_f32_16x16x32_bf16 v[122:125], v[146:149], v[170:173], v[122:125]
	v_mfma_f32_16x16x32_bf16 v[114:117], v[154:157], v[170:173], v[114:117]
	v_mfma_f32_16x16x32_bf16 v[106:109], v[146:149], v[178:181], v[106:109]
	v_mfma_f32_16x16x32_bf16 v[98:101], v[154:157], v[178:181], v[98:101]
	v_mfma_f32_16x16x32_bf16 v[90:93], v[146:149], v[200:203], v[90:93]
	v_mfma_f32_16x16x32_bf16 v[82:85], v[154:157], v[200:203], v[82:85]
	v_mfma_f32_16x16x32_bf16 v[130:133], v[150:153], v[166:169], v[130:133]
	v_mfma_f32_16x16x32_bf16 v[126:129], v[158:161], v[166:169], v[126:129]
	v_mfma_f32_16x16x32_bf16 v[122:125], v[150:153], v[174:177], v[122:125]
	v_mfma_f32_16x16x32_bf16 v[114:117], v[158:161], v[174:177], v[114:117]
	v_mfma_f32_16x16x32_bf16 v[106:109], v[150:153], v[196:199], v[106:109]
	v_mfma_f32_16x16x32_bf16 v[98:101], v[158:161], v[196:199], v[98:101]
	v_mfma_f32_16x16x32_bf16 v[90:93], v[150:153], v[204:207], v[90:93]
	v_mfma_f32_16x16x32_bf16 v[82:85], v[158:161], v[204:207], v[82:85]
	s_setprio 0
	s_barrier
	s_mov_b32 m0, s72
	v_add_u32_e32 v195, s3, v144
	v_lshl_add_u64 v[186:187], v[186:187], 0, s[36:37]
	ds_read_b128 v[208:211], v195
	ds_read_b128 v[212:215], v195 offset:1024
	ds_read_b128 v[216:219], v195 offset:2048
	ds_read_b128 v[220:223], v195 offset:3072
	global_load_lds_dwordx4 v[186:187], off
	s_mov_b32 m0, s1
	v_lshl_add_u64 v[186:187], v[188:189], 0, s[36:37]
	global_load_lds_dwordx4 v[186:187], off
	s_barrier
; #define PG8_STAGE(bufoff, gbase, voff) do { _Pragma("unroll") for (int _i = 0; _i < 2; ++_i) \
;         __builtin_amdgcn_global_load_lds((const unsigned*)((const char*)(gbase) + (voff)[_i]), (LAS unsigned*)(lds + (bufoff) + ldsw + _i * 8192), 16, 0, 0); } while (0)
; #define PG8_MMA(ai, bj, At, Bt) do { __builtin_amdgcn_s_setprio(1); _Pragma("unroll") for (int m = 0; m < 4; ++m) _Pragma("unroll") for (int n = 0; n < 2; ++n) _Pragma("unroll") for (int k = 0; k < 2; ++k) \
;         acc[ai][bj][m][n] = __builtin_amdgcn_mfma_f32_16x16x32_bf16(Bt[n][k], At[m][k], acc[ai][bj][m][n], 0, 0, 0); __builtin_amdgcn_s_setprio(0); } while (0)
; #define PG8_WAIT_V(n) asm volatile("s_waitcnt vmcnt(" #n ")" ::: "memory")
; #define PG8_WAIT_L(n) asm volatile("s_waitcnt lgkmcnt(" #n ")" ::: "memory")
; #define PG8_BAR __builtin_amdgcn_s_barrier()
; #define PG8_SCHED __builtin_amdgcn_sched_barrier(0)
; template <class Epi, class Sched>
; __device__ __forceinline__ void gemm_phase(const int TID, LAS unsigned char* lds, const int lda, const int ldb, const Sched& S, const Epi& E) {
;     ...
;             PG8_BAR; PG8_WAIT_L(0); PG8_MMA(1, 0, At, B0); PG8_BAR; PG8_SCHED;
;             PG8_STAGE(PG8_SB(1, 1), b3 + hB, voffB);
;             PG8_WAIT_V(6); PG8_BAR; PG8_MMA(1, 1, At, B1); PG8_BAR;
	s_waitcnt lgkmcnt(0)
	s_setprio 1
	s_waitcnt lgkmcnt(0)
	v_mfma_f32_16x16x32_bf16 v[118:121], v[208:211], v[162:165], v[118:121]
	v_mfma_f32_16x16x32_bf16 v[110:113], v[216:219], v[162:165], v[110:113]
	v_mfma_f32_16x16x32_bf16 v[102:105], v[208:211], v[170:173], v[102:105]
	v_mfma_f32_16x16x32_bf16 v[94:97], v[216:219], v[170:173], v[94:97]
	v_mfma_f32_16x16x32_bf16 v[86:89], v[208:211], v[178:181], v[86:89]
	v_mfma_f32_16x16x32_bf16 v[78:81], v[216:219], v[178:181], v[78:81]
	v_mfma_f32_16x16x32_bf16 v[74:77], v[208:211], v[200:203], v[74:77]
	v_mfma_f32_16x16x32_bf16 v[70:73], v[216:219], v[200:203], v[70:73]
	v_mfma_f32_16x16x32_bf16 v[118:121], v[212:215], v[166:169], v[118:121]
	v_mfma_f32_16x16x32_bf16 v[110:113], v[220:223], v[166:169], v[110:113]
	v_mfma_f32_16x16x32_bf16 v[102:105], v[212:215], v[174:177], v[102:105]
	v_mfma_f32_16x16x32_bf16 v[94:97], v[220:223], v[174:177], v[94:97]
	v_mfma_f32_16x16x32_bf16 v[86:89], v[212:215], v[196:199], v[86:89]
	v_mfma_f32_16x16x32_bf16 v[78:81], v[220:223], v[196:199], v[78:81]
	v_mfma_f32_16x16x32_bf16 v[74:77], v[212:215], v[204:207], v[74:77]
	v_mfma_f32_16x16x32_bf16 v[70:73], v[220:223], v[204:207], v[70:73]
	s_setprio 0
	s_mov_b32 m0, s69
	v_lshl_add_u64 v[186:187], v[236:237], 0, s[36:37]
	s_barrier
	ds_read_b128 v[162:165], v145 offset:49152
	ds_read_b128 v[166:169], v145 offset:50176
	ds_read_b128 v[170:173], v145 offset:51200
	ds_read_b128 v[174:177], v145 offset:52224
	ds_read_b128 v[178:181], v145 offset:53248
	ds_read_b128 v[196:199], v145 offset:54272
	ds_read_b128 v[200:203], v145 offset:55296
	ds_read_b128 v[204:207], v145 offset:56320
	global_load_lds_dwordx4 v[186:187], off
	s_mov_b32 m0, s70
	v_lshl_add_u64 v[186:187], v[238:239], 0, s[36:37]
	global_load_lds_dwordx4 v[186:187], off
	s_barrier
	s_waitcnt lgkmcnt(0)
	s_setprio 1
	s_waitcnt lgkmcnt(0)
	v_mfma_f32_16x16x32_bf16 v[66:69], v[146:149], v[162:165], v[66:69]
	v_mfma_f32_16x16x32_bf16 v[62:65], v[154:157], v[162:165], v[62:65]
	v_mfma_f32_16x16x32_bf16 v[58:61], v[146:149], v[170:173], v[58:61]
	v_mfma_f32_16x16x32_bf16 v[50:53], v[154:157], v[170:173], v[50:53]
	v_mfma_f32_16x16x32_bf16 v[42:45], v[146:149], v[178:181], v[42:45]
	v_mfma_f32_16x16x32_bf16 v[34:37], v[154:157], v[178:181], v[34:37]
	v_mfma_f32_16x16x32_bf16 v[26:29], v[146:149], v[200:203], v[26:29]
	v_mfma_f32_16x16x32_bf16 v[18:21], v[154:157], v[200:203], v[18:21]
	v_mfma_f32_16x16x32_bf16 v[66:69], v[150:153], v[166:169], v[66:69]
	v_mfma_f32_16x16x32_bf16 v[62:65], v[158:161], v[166:169], v[62:65]
	v_mfma_f32_16x16x32_bf16 v[58:61], v[150:153], v[174:177], v[58:61]
	v_mfma_f32_16x16x32_bf16 v[50:53], v[158:161], v[174:177], v[50:53]
	v_mfma_f32_16x16x32_bf16 v[42:45], v[150:153], v[196:199], v[42:45]
	v_mfma_f32_16x16x32_bf16 v[34:37], v[158:161], v[196:199], v[34:37]
	v_mfma_f32_16x16x32_bf16 v[26:29], v[150:153], v[204:207], v[26:29]
	v_mfma_f32_16x16x32_bf16 v[18:21], v[158:161], v[204:207], v[18:21]
	s_setprio 0
	s_barrier
	s_mov_b32 m0, s77
	v_lshl_add_u64 v[146:147], s[52:53], 0, v[182:183]
	global_load_lds_dwordx4 v[146:147], off
	s_mov_b32 m0, s76
	v_lshl_add_u64 v[146:147], s[52:53], 0, v[12:13]
	global_load_lds_dwordx4 v[146:147], off
	s_waitcnt vmcnt(6)
	s_barrier
	s_setprio 1
	v_mfma_f32_16x16x32_bf16 v[54:57], v[208:211], v[162:165], v[54:57]
	v_mfma_f32_16x16x32_bf16 v[46:49], v[216:219], v[162:165], v[46:49]
	v_mfma_f32_16x16x32_bf16 v[38:41], v[208:211], v[170:173], v[38:41]
	v_mfma_f32_16x16x32_bf16 v[30:33], v[216:219], v[170:173], v[30:33]
	v_mfma_f32_16x16x32_bf16 v[22:25], v[208:211], v[178:181], v[22:25]
	v_mfma_f32_16x16x32_bf16 v[8:11], v[216:219], v[178:181], v[8:11]
	v_mfma_f32_16x16x32_bf16 v[4:7], v[208:211], v[200:203], v[4:7]
	v_mfma_f32_16x16x32_bf16 v[0:3], v[216:219], v[200:203], v[0:3]
	v_mfma_f32_16x16x32_bf16 v[54:57], v[212:215], v[166:169], v[54:57]
	v_mfma_f32_16x16x32_bf16 v[46:49], v[220:223], v[166:169], v[46:49]
	v_mfma_f32_16x16x32_bf16 v[38:41], v[212:215], v[174:177], v[38:41]
	v_mfma_f32_16x16x32_bf16 v[30:33], v[220:223], v[174:177], v[30:33]
	v_mfma_f32_16x16x32_bf16 v[22:25], v[212:215], v[196:199], v[22:25]
	v_mfma_f32_16x16x32_bf16 v[8:11], v[220:223], v[196:199], v[8:11]
	v_mfma_f32_16x16x32_bf16 v[4:7], v[212:215], v[204:207], v[4:7]
	v_mfma_f32_16x16x32_bf16 v[0:3], v[220:223], v[204:207], v[0:3]
	s_setprio 0
	s_movk_i32 s1, 0x100
	s_andn2_b64 vcc, exec, s[50:51]
	s_mov_b64 s[52:53], -1
	s_mov_b64 s[50:51], 0
	s_barrier
	s_cbranch_vccz .LBB0_732
; #define PG8_WAIT_V(n) asm volatile("s_waitcnt vmcnt(" #n ")" ::: "memory")
; #define PG8_BAR __builtin_amdgcn_s_barrier()
; template <class Epi, class Sched>
; __device__ __forceinline__ void gemm_phase(const int TID, LAS unsigned char* lds, const int lda, const int ldb, const Sched& S, const Epi& E) {
;     ...
;         E(acc, cur, wr, wc, fr, fq);
;         if (!has_next) break;
; #pragma unroll
;         for (int a = 0; a < 2; ++a)
; #pragma unroll
;             for (int b = 0; b < 2; ++b)
; #pragma unroll
;                 for (int m = 0; m < 4; ++m)
; #pragma unroll
;                     for (int n = 0; n < 2; ++n) acc[a][b][m][n] = (f32x4){0.f, 0.f, 0.f, 0.f};
;         cur = nxt; cA = nA; cB = nB; ++ui;
;     }
;     PG8_WAIT_V(0);
;     if (wr == 0) PG8_BAR;
;     PG8_BAR;
	s_lshl_b32 s1, s44, 8
	s_mul_i32 s3, s42, 0x700
	s_add_i32 s1, s1, s3
	v_cvt_pk_bf16_f32 v146, v130, v131
	v_add_u32_e32 v130, s1, v135
	v_ashrrev_i32_e32 v131, 31, v130
	v_cvt_pk_bf16_f32 v147, v132, v133
	v_lshlrev_b64 v[132:133], 9, v[130:131]
	v_lshl_add_u64 v[132:133], v[140:141], 0, v[132:133]
	flat_store_dwordx2 v[132:133], v[146:147]
	v_cvt_pk_bf16_f32 v126, v126, v127
	v_cvt_pk_bf16_f32 v127, v128, v129
	flat_store_dwordx2 v[132:133], v[126:127] offset:32
	v_cvt_pk_bf16_f32 v118, v118, v119
	v_cvt_pk_bf16_f32 v119, v120, v121
	flat_store_dwordx2 v[132:133], v[118:119] offset:256
	v_cvt_pk_bf16_f32 v110, v110, v111
	v_cvt_pk_bf16_f32 v111, v112, v113
	v_or_b32_e32 v112, 16, v130
	v_ashrrev_i32_e32 v113, 31, v112
	v_lshlrev_b64 v[112:113], 9, v[112:113]
	flat_store_dwordx2 v[132:133], v[110:111] offset:288
	v_cvt_pk_bf16_f32 v110, v122, v123
	v_cvt_pk_bf16_f32 v111, v124, v125
	v_lshl_add_u64 v[112:113], v[140:141], 0, v[112:113]
	flat_store_dwordx2 v[112:113], v[110:111]
	v_cvt_pk_bf16_f32 v110, v114, v115
	v_cvt_pk_bf16_f32 v111, v116, v117
	flat_store_dwordx2 v[112:113], v[110:111] offset:32
	v_cvt_pk_bf16_f32 v102, v102, v103
	v_cvt_pk_bf16_f32 v103, v104, v105
	flat_store_dwordx2 v[112:113], v[102:103] offset:256
	v_cvt_pk_bf16_f32 v94, v94, v95
	v_cvt_pk_bf16_f32 v95, v96, v97
	v_or_b32_e32 v96, 32, v130
	v_ashrrev_i32_e32 v97, 31, v96
	v_lshlrev_b64 v[96:97], 9, v[96:97]
	flat_store_dwordx2 v[112:113], v[94:95] offset:288
	v_cvt_pk_bf16_f32 v94, v106, v107
	v_cvt_pk_bf16_f32 v95, v108, v109
	v_lshl_add_u64 v[96:97], v[140:141], 0, v[96:97]
	flat_store_dwordx2 v[96:97], v[94:95]
	v_cvt_pk_bf16_f32 v94, v98, v99
	v_cvt_pk_bf16_f32 v95, v100, v101
	flat_store_dwordx2 v[96:97], v[94:95] offset:32
	v_cvt_pk_bf16_f32 v86, v86, v87
	v_cvt_pk_bf16_f32 v87, v88, v89
	flat_store_dwordx2 v[96:97], v[86:87] offset:256
	v_cvt_pk_bf16_f32 v78, v78, v79
	v_cvt_pk_bf16_f32 v79, v80, v81
	v_or_b32_e32 v80, 48, v130
	v_ashrrev_i32_e32 v81, 31, v80
	v_lshlrev_b64 v[80:81], 9, v[80:81]
	flat_store_dwordx2 v[96:97], v[78:79] offset:288
	v_cvt_pk_bf16_f32 v78, v90, v91
	v_cvt_pk_bf16_f32 v79, v92, v93
	v_lshl_add_u64 v[80:81], v[140:141], 0, v[80:81]
	flat_store_dwordx2 v[80:81], v[78:79]
	v_cvt_pk_bf16_f32 v78, v82, v83
	v_cvt_pk_bf16_f32 v79, v84, v85
	flat_store_dwordx2 v[80:81], v[78:79] offset:32
	v_cvt_pk_bf16_f32 v74, v74, v75
	v_cvt_pk_bf16_f32 v75, v76, v77
	flat_store_dwordx2 v[80:81], v[74:75] offset:256
	v_cvt_pk_bf16_f32 v70, v70, v71
	v_cvt_pk_bf16_f32 v71, v72, v73
	flat_store_dwordx2 v[80:81], v[70:71] offset:288
	v_cvt_pk_bf16_f32 v66, v66, v67
	v_cvt_pk_bf16_f32 v67, v68, v69
	v_add_u32_e32 v68, 0x80, v130
	v_ashrrev_i32_e32 v69, 31, v68
	v_lshlrev_b64 v[68:69], 9, v[68:69]
	v_lshl_add_u64 v[68:69], v[140:141], 0, v[68:69]
	flat_store_dwordx2 v[68:69], v[66:67]
	v_cvt_pk_bf16_f32 v62, v62, v63
	v_cvt_pk_bf16_f32 v63, v64, v65
	flat_store_dwordx2 v[68:69], v[62:63] offset:32
	v_cvt_pk_bf16_f32 v54, v54, v55
	v_cvt_pk_bf16_f32 v55, v56, v57
	flat_store_dwordx2 v[68:69], v[54:55] offset:256
	v_cvt_pk_bf16_f32 v46, v46, v47
	v_cvt_pk_bf16_f32 v47, v48, v49
	v_add_u32_e32 v48, 0x90, v130
	v_ashrrev_i32_e32 v49, 31, v48
	v_lshlrev_b64 v[48:49], 9, v[48:49]
	flat_store_dwordx2 v[68:69], v[46:47] offset:288
	v_cvt_pk_bf16_f32 v46, v58, v59
	v_cvt_pk_bf16_f32 v47, v60, v61
	v_lshl_add_u64 v[48:49], v[140:141], 0, v[48:49]
	flat_store_dwordx2 v[48:49], v[46:47]
	v_cvt_pk_bf16_f32 v46, v50, v51
	v_cvt_pk_bf16_f32 v47, v52, v53
	flat_store_dwordx2 v[48:49], v[46:47] offset:32
	v_cvt_pk_bf16_f32 v38, v38, v39
	v_cvt_pk_bf16_f32 v39, v40, v41
	flat_store_dwordx2 v[48:49], v[38:39] offset:256
	v_cvt_pk_bf16_f32 v30, v30, v31
	v_cvt_pk_bf16_f32 v31, v32, v33
	v_add_u32_e32 v32, 0xa0, v130
	v_ashrrev_i32_e32 v33, 31, v32
	v_lshlrev_b64 v[32:33], 9, v[32:33]
	flat_store_dwordx2 v[48:49], v[30:31] offset:288
	v_cvt_pk_bf16_f32 v30, v42, v43
	v_cvt_pk_bf16_f32 v31, v44, v45
	v_lshl_add_u64 v[32:33], v[140:141], 0, v[32:33]
	flat_store_dwordx2 v[32:33], v[30:31]
	v_cvt_pk_bf16_f32 v30, v34, v35
	v_cvt_pk_bf16_f32 v31, v36, v37
	flat_store_dwordx2 v[32:33], v[30:31] offset:32
	v_cvt_pk_bf16_f32 v22, v22, v23
	v_cvt_pk_bf16_f32 v23, v24, v25
	flat_store_dwordx2 v[32:33], v[22:23] offset:256
	v_cvt_pk_bf16_f32 v8, v8, v9
	v_cvt_pk_bf16_f32 v9, v10, v11
	v_add_u32_e32 v10, 0xb0, v130
	v_ashrrev_i32_e32 v11, 31, v10
	v_lshlrev_b64 v[10:11], 9, v[10:11]
	flat_store_dwordx2 v[32:33], v[8:9] offset:288
	v_cvt_pk_bf16_f32 v8, v26, v27
	v_cvt_pk_bf16_f32 v9, v28, v29
	v_lshl_add_u64 v[10:11], v[140:141], 0, v[10:11]
	s_and_b64 vcc, exec, s[40:41]
	s_mov_b32 s42, s0
	s_mov_b32 s44, s2
	s_mov_b64 s[48:49], s[38:39]
	s_mov_b64 s[46:47], s[28:29]
	flat_store_dwordx2 v[10:11], v[8:9]
	v_cvt_pk_bf16_f32 v8, v18, v19
	v_cvt_pk_bf16_f32 v9, v20, v21
	flat_store_dwordx2 v[10:11], v[8:9] offset:32
	v_cvt_pk_bf16_f32 v4, v4, v5
	v_cvt_pk_bf16_f32 v5, v6, v7
	flat_store_dwordx2 v[10:11], v[4:5] offset:256
	v_cvt_pk_bf16_f32 v0, v0, v1
	v_cvt_pk_bf16_f32 v1, v2, v3
	flat_store_dwordx2 v[10:11], v[0:1] offset:288
	s_cbranch_vccz .LBB0_729
	s_waitcnt vmcnt(0)
	s_cmpk_gt_u32 s21, 0xff
	s_cbranch_scc1 .LBB0_736
	s_barrier

; #define PG8_STAGE(bufoff, gbase, voff) do { _Pragma("unroll") for (int _i = 0; _i < 2; ++_i) \
;         __builtin_amdgcn_global_load_lds((const unsigned*)((const char*)(gbase) + (voff)[_i]), (LAS unsigned*)(lds + (bufoff) + ldsw + _i * 8192), 16, 0, 0); } while (0)
; #define PG8_LDA(dst, b, h) do { _Pragma("unroll") for (int m = 0; m < 4; ++m) _Pragma("unroll") for (int k = 0; k < 2; ++k) dst[m][k] = *(const LAS bf16x8*)(lds + PG8_SA(b, h) + aoff + m * 2048 + k * 1024); } while (0)
; #define PG8_LDB(dst, b, h) do { _Pragma("unroll") for (int n = 0; n < 2; ++n) _Pragma("unroll") for (int k = 0; k < 2; ++k) dst[n][k] = *(const LAS bf16x8*)(lds + PG8_SB(b, h) + boff + n * 2048 + k * 1024); } while (0)
; #define PG8_WAIT_V(n) asm volatile("s_waitcnt vmcnt(" #n ")" ::: "memory")
; #define PG8_WAIT_L(n) asm volatile("s_waitcnt lgkmcnt(" #n ")" ::: "memory")
; #define PG8_BAR __builtin_amdgcn_s_barrier()
; #define PG8_SCHED __builtin_amdgcn_sched_barrier(0)
; template <class Epi, class Sched>
; __device__ __forceinline__ void gemm_phase(const int TID, LAS unsigned char* lds, const int lda, const int ldb, const Sched& S, const Epi& E) {
;     ...
;         const bool has_next = S.next(ui + 1, nxt);
;         const char* nA = has_next ? nxt.a : cA; const char* nB = has_next ? nxt.b : cB;
;         const int nt = cur.nt;
;         for (int t = 0; t < nt; t += 2) {
;             const bool last = (t == nt - 2);
;             const char* a1 = cA + (size_t)(t + 1) * kstep;
;             const char* a2 = last ? nA : cA + (size_t)(t + 2) * kstep; const char* b2 = last ? nB : cB + (size_t)(t + 2) * kstep;
;             const char* a3 = a2 + kstep; const char* b3 = b2 + kstep;
;             PG8_LDB(B0, 0, 0); PG8_SCHED; PG8_LDA(At, 0, 0); PG8_STAGE(PG8_SA(1, 1), a1 + hA, voffA);
;             PG8_WAIT_L(8); PG8_BAR; PG8_WAIT_L(0); PG8_MMA(0, 0, At, B0); PG8_BAR; PG8_SCHED;
;             PG8_LDB(B1, 0, 1); PG8_STAGE(PG8_SB(0, 0), b2, voffB);
;             PG8_BAR; PG8_WAIT_L(0); PG8_MMA(0, 1, At, B1); PG8_BAR;
;             PG8_LDA(At, 0, 1); PG8_STAGE(PG8_SA(0, 0), a2, voffA);
;             PG8_BAR; PG8_WAIT_L(0); PG8_MMA(1, 0, At, B0); PG8_BAR; PG8_SCHED;
;             PG8_STAGE(PG8_SB(0, 1), b2 + hB, voffB);
;             PG8_WAIT_V(6); PG8_BAR; PG8_MMA(1, 1, At, B1); PG8_BAR;
.Lk1_body:
	s_add_u32 s8, s46, 0xfff80080
	s_addc_u32 s9, s47, -1
	s_add_i32 s10, 0, 0x10000
	s_cmp_eq_u32 s29, 28
	s_cselect_b32 s51, s43, s9
	s_cselect_b32 s50, s42, s8
	s_cselect_b32 s49, s45, s24
	s_cselect_b32 s48, s44, s3
	v_lshl_add_u64 v[154:155], s[46:47], 0, v[148:149]
	s_add_i32 m0, s57, 0xc000
	ds_read_b128 v[170:173], v157
	ds_read_b128 v[174:177], v157 offset:1024
	ds_read_b128 v[178:181], v157 offset:2048
	ds_read_b128 v[196:199], v157 offset:3072
	ds_read_b128 v[200:203], v157 offset:4096
	ds_read_b128 v[204:207], v157 offset:5120
	ds_read_b128 v[208:211], v157 offset:6144
	ds_read_b128 v[212:215], v157 offset:7168
	global_load_lds_dwordx4 v[154:155], off
	s_add_i32 m0, s57, 0xe000
	v_lshl_add_u64 v[154:155], s[46:47], 0, v[146:147]
	global_load_lds_dwordx4 v[154:155], off
	s_waitcnt lgkmcnt(8)
	s_barrier
	s_waitcnt lgkmcnt(0)
	s_waitcnt lgkmcnt(0)
	v_mfma_f32_16x16x32_bf16 v[130:133], v[150:153], v[170:173], v[130:133]
	v_mfma_f32_16x16x32_bf16 v[126:129], v[162:165], v[170:173], v[126:129]
	v_mfma_f32_16x16x32_bf16 v[114:117], v[150:153], v[178:181], v[114:117]
	v_mfma_f32_16x16x32_bf16 v[110:113], v[162:165], v[178:181], v[110:113]
	v_mfma_f32_16x16x32_bf16 v[98:101], v[150:153], v[200:203], v[98:101]
	v_mfma_f32_16x16x32_bf16 v[94:97], v[162:165], v[200:203], v[94:97]
	v_mfma_f32_16x16x32_bf16 v[82:85], v[150:153], v[208:211], v[82:85]
	v_mfma_f32_16x16x32_bf16 v[78:81], v[162:165], v[208:211], v[78:81]
	v_mfma_f32_16x16x32_bf16 v[130:133], v[158:161], v[174:177], v[130:133]
	v_mfma_f32_16x16x32_bf16 v[126:129], v[166:169], v[174:177], v[126:129]
	v_mfma_f32_16x16x32_bf16 v[114:117], v[158:161], v[196:199], v[114:117]
	v_mfma_f32_16x16x32_bf16 v[110:113], v[166:169], v[196:199], v[110:113]
	v_mfma_f32_16x16x32_bf16 v[98:101], v[158:161], v[204:207], v[98:101]
	v_mfma_f32_16x16x32_bf16 v[94:97], v[166:169], v[204:207], v[94:97]
	v_mfma_f32_16x16x32_bf16 v[82:85], v[158:161], v[212:215], v[82:85]
	v_mfma_f32_16x16x32_bf16 v[78:81], v[166:169], v[212:215], v[78:81]
	s_barrier
	s_add_i32 s8, 0, 0x14000
	v_add_u32_e32 v154, s8, v13
	s_add_i32 s9, s10, s56
	ds_read_b128 v[216:219], v154
	ds_read_b128 v[220:223], v154 offset:1024
	ds_read_b128 v[236:239], v154 offset:2048
	ds_read_b128 v[240:243], v154 offset:3072
	v_lshl_add_u64 v[154:155], s[48:49], 0, v[136:137]
	s_mov_b32 m0, s9
	v_lshl_add_u64 v[186:187], s[48:49], 0, v[140:141]
	global_load_lds_dwordx4 v[154:155], off
	s_add_i32 m0, s9, 0x2000
	s_nop 0
	global_load_lds_dwordx4 v[186:187], off
	s_barrier
	s_waitcnt lgkmcnt(0)
	s_waitcnt lgkmcnt(0)
	v_mfma_f32_16x16x32_bf16 v[122:125], v[216:219], v[170:173], v[122:125]
	v_mfma_f32_16x16x32_bf16 v[118:121], v[236:239], v[170:173], v[118:121]
	v_mfma_f32_16x16x32_bf16 v[106:109], v[216:219], v[178:181], v[106:109]
	v_mfma_f32_16x16x32_bf16 v[102:105], v[236:239], v[178:181], v[102:105]
	v_mfma_f32_16x16x32_bf16 v[90:93], v[216:219], v[200:203], v[90:93]
	v_mfma_f32_16x16x32_bf16 v[86:89], v[236:239], v[200:203], v[86:89]
	v_mfma_f32_16x16x32_bf16 v[74:77], v[216:219], v[208:211], v[74:77]
	v_mfma_f32_16x16x32_bf16 v[70:73], v[236:239], v[208:211], v[70:73]
	v_mfma_f32_16x16x32_bf16 v[122:125], v[220:223], v[174:177], v[122:125]
	v_mfma_f32_16x16x32_bf16 v[118:121], v[240:243], v[174:177], v[118:121]
	v_mfma_f32_16x16x32_bf16 v[106:109], v[220:223], v[196:199], v[106:109]
	v_mfma_f32_16x16x32_bf16 v[102:105], v[240:243], v[196:199], v[102:105]
	v_mfma_f32_16x16x32_bf16 v[90:93], v[220:223], v[204:207], v[90:93]
	v_mfma_f32_16x16x32_bf16 v[86:89], v[240:243], v[204:207], v[86:89]
	v_mfma_f32_16x16x32_bf16 v[74:77], v[220:223], v[212:215], v[74:77]
	v_mfma_f32_16x16x32_bf16 v[70:73], v[240:243], v[212:215], v[70:73]
	s_mov_b32 m0, s57
	v_lshl_add_u64 v[188:189], s[50:51], 0, v[134:135]
	s_barrier
	ds_read_b128 v[170:173], v157 offset:16384
	ds_read_b128 v[174:177], v157 offset:17408
	ds_read_b128 v[178:181], v157 offset:18432
	ds_read_b128 v[196:199], v157 offset:19456
	ds_read_b128 v[200:203], v157 offset:20480
	ds_read_b128 v[204:207], v157 offset:21504
	ds_read_b128 v[208:211], v157 offset:22528
	ds_read_b128 v[212:215], v157 offset:23552
	global_load_lds_dwordx4 v[188:189], off
	s_mov_b32 m0, s58
	v_lshl_add_u64 v[244:245], s[50:51], 0, v[138:139]
	global_load_lds_dwordx4 v[244:245], off
	s_barrier
	s_waitcnt lgkmcnt(0)
	s_waitcnt lgkmcnt(0)
	v_mfma_f32_16x16x32_bf16 v[66:69], v[150:153], v[170:173], v[66:69]
	v_mfma_f32_16x16x32_bf16 v[62:65], v[162:165], v[170:173], v[62:65]
	v_mfma_f32_16x16x32_bf16 v[50:53], v[150:153], v[178:181], v[50:53]
	v_mfma_f32_16x16x32_bf16 v[46:49], v[162:165], v[178:181], v[46:49]
	v_mfma_f32_16x16x32_bf16 v[34:37], v[150:153], v[200:203], v[34:37]
	v_mfma_f32_16x16x32_bf16 v[30:33], v[162:165], v[200:203], v[30:33]
	v_mfma_f32_16x16x32_bf16 v[18:21], v[150:153], v[208:211], v[18:21]
	v_mfma_f32_16x16x32_bf16 v[8:11], v[162:165], v[208:211], v[8:11]
	v_mfma_f32_16x16x32_bf16 v[66:69], v[158:161], v[174:177], v[66:69]
	v_mfma_f32_16x16x32_bf16 v[62:65], v[166:169], v[174:177], v[62:65]
	v_mfma_f32_16x16x32_bf16 v[50:53], v[158:161], v[196:199], v[50:53]
	v_mfma_f32_16x16x32_bf16 v[46:49], v[166:169], v[196:199], v[46:49]
	v_mfma_f32_16x16x32_bf16 v[34:37], v[158:161], v[204:207], v[34:37]
	v_mfma_f32_16x16x32_bf16 v[30:33], v[166:169], v[204:207], v[30:33]
	v_mfma_f32_16x16x32_bf16 v[18:21], v[158:161], v[212:215], v[18:21]
	v_mfma_f32_16x16x32_bf16 v[8:11], v[166:169], v[212:215], v[8:11]
	s_barrier
	s_add_u32 s66, s48, 0x80000
	s_addc_u32 s67, s49, 0
	s_add_i32 s8, s8, s56
	s_mov_b32 m0, s8
	v_lshl_add_u64 v[150:151], s[66:67], 0, v[136:137]
	global_load_lds_dwordx4 v[150:151], off
	s_add_i32 m0, s8, 0x2000
	v_lshl_add_u64 v[150:151], s[66:67], 0, v[140:141]
	global_load_lds_dwordx4 v[150:151], off
	s_waitcnt vmcnt(6)
	s_barrier
; #define PG8_STAGE(bufoff, gbase, voff) do { _Pragma("unroll") for (int _i = 0; _i < 2; ++_i) \
;         __builtin_amdgcn_global_load_lds((const unsigned*)((const char*)(gbase) + (voff)[_i]), (LAS unsigned*)(lds + (bufoff) + ldsw + _i * 8192), 16, 0, 0); } while (0)
; #define PG8_LDA(dst, b, h) do { _Pragma("unroll") for (int m = 0; m < 4; ++m) _Pragma("unroll") for (int k = 0; k < 2; ++k) dst[m][k] = *(const LAS bf16x8*)(lds + PG8_SA(b, h) + aoff + m * 2048 + k * 1024); } while (0)
; #define PG8_LDB(dst, b, h) do { _Pragma("unroll") for (int n = 0; n < 2; ++n) _Pragma("unroll") for (int k = 0; k < 2; ++k) dst[n][k] = *(const LAS bf16x8*)(lds + PG8_SB(b, h) + boff + n * 2048 + k * 1024); } while (0)
; #define PG8_MMA(ai, bj, At, Bt) do { __builtin_amdgcn_s_setprio(1); _Pragma("unroll") for (int m = 0; m < 4; ++m) _Pragma("unroll") for (int n = 0; n < 2; ++n) _Pragma("unroll") for (int k = 0; k < 2; ++k) \
;         acc[ai][bj][m][n] = __builtin_amdgcn_mfma_f32_16x16x32_bf16(Bt[n][k], At[m][k], acc[ai][bj][m][n], 0, 0, 0); __builtin_amdgcn_s_setprio(0); } while (0)
; #define PG8_WAIT_V(n) asm volatile("s_waitcnt vmcnt(" #n ")" ::: "memory")
; #define PG8_WAIT_L(n) asm volatile("s_waitcnt lgkmcnt(" #n ")" ::: "memory")
; #define PG8_BAR __builtin_amdgcn_s_barrier()
; #define PG8_SCHED __builtin_amdgcn_sched_barrier(0)
; template <class Epi, class Sched>
; __device__ __forceinline__ void gemm_phase(const int TID, LAS unsigned char* lds, const int lda, const int ldb, const Sched& S, const Epi& E) {
;     ...
;             PG8_WAIT_V(6); PG8_BAR; PG8_MMA(1, 1, At, B1); PG8_BAR;
;             PG8_LDB(B0, 1, 0); PG8_SCHED; PG8_LDA(At, 1, 0); PG8_STAGE(PG8_SA(0, 1), a2 + hA, voffA);
;             PG8_WAIT_L(8); PG8_BAR; PG8_WAIT_L(0); PG8_MMA(0, 0, At, B0); PG8_BAR; PG8_SCHED;
;             PG8_LDB(B1, 1, 1); PG8_STAGE(PG8_SB(1, 0), b3, voffB);
;             PG8_BAR; PG8_WAIT_L(0); PG8_MMA(0, 1, At, B1); PG8_BAR;
;             PG8_LDA(At, 1, 1); PG8_STAGE(PG8_SA(1, 0), a3, voffA);
;             PG8_BAR; PG8_WAIT_L(0); PG8_MMA(1, 0, At, B0); PG8_BAR; PG8_SCHED;
	v_add_u32_e32 v166, 0x18000, v13
	v_mfma_f32_16x16x32_bf16 v[58:61], v[216:219], v[170:173], v[58:61]
	v_mfma_f32_16x16x32_bf16 v[54:57], v[236:239], v[170:173], v[54:57]
	v_mfma_f32_16x16x32_bf16 v[42:45], v[216:219], v[178:181], v[42:45]
	v_mfma_f32_16x16x32_bf16 v[38:41], v[236:239], v[178:181], v[38:41]
	ds_read_b128 v[150:153], v166
	v_mfma_f32_16x16x32_bf16 v[26:29], v[216:219], v[200:203], v[26:29]
	v_mfma_f32_16x16x32_bf16 v[22:25], v[236:239], v[200:203], v[22:25]
	ds_read_b128 v[158:161], v166 offset:1024
	v_mfma_f32_16x16x32_bf16 v[4:7], v[216:219], v[208:211], v[4:7]
	v_mfma_f32_16x16x32_bf16 v[0:3], v[236:239], v[208:211], v[0:3]
	ds_read_b128 v[162:165], v166 offset:2048
	v_mfma_f32_16x16x32_bf16 v[58:61], v[220:223], v[174:177], v[58:61]
	v_mfma_f32_16x16x32_bf16 v[54:57], v[240:243], v[174:177], v[54:57]
	ds_read_b128 v[166:169], v166 offset:3072
	v_mfma_f32_16x16x32_bf16 v[42:45], v[220:223], v[196:199], v[42:45]
	v_mfma_f32_16x16x32_bf16 v[38:41], v[240:243], v[196:199], v[38:41]
	v_mfma_f32_16x16x32_bf16 v[26:29], v[220:223], v[204:207], v[26:29]
	v_mfma_f32_16x16x32_bf16 v[22:25], v[240:243], v[204:207], v[22:25]
	v_mfma_f32_16x16x32_bf16 v[4:7], v[220:223], v[212:215], v[4:7]
	v_mfma_f32_16x16x32_bf16 v[0:3], v[240:243], v[212:215], v[0:3]
	s_add_i32 s8, 0, 0x18000
	s_barrier
	s_add_u32 s50, s50, 0x80000
	s_addc_u32 s51, s51, 0
	s_mov_b32 m0, s59
	v_lshl_add_u64 v[216:217], s[50:51], 0, v[134:135]
	ds_read_b128 v[170:173], v157 offset:32768
	ds_read_b128 v[174:177], v157 offset:33792
	ds_read_b128 v[178:181], v157 offset:34816
	ds_read_b128 v[196:199], v157 offset:35840
	ds_read_b128 v[200:203], v157 offset:36864
	ds_read_b128 v[204:207], v157 offset:37888
	ds_read_b128 v[208:211], v157 offset:38912
	ds_read_b128 v[212:215], v157 offset:39936
	global_load_lds_dwordx4 v[216:217], off
	s_mov_b32 m0, s60
	v_lshl_add_u64 v[216:217], s[50:51], 0, v[138:139]
	global_load_lds_dwordx4 v[216:217], off
	s_waitcnt lgkmcnt(8)
	s_barrier
	s_waitcnt lgkmcnt(0)
	s_waitcnt lgkmcnt(0)
	v_mfma_f32_16x16x32_bf16 v[130:133], v[150:153], v[170:173], v[130:133]
	v_mfma_f32_16x16x32_bf16 v[126:129], v[162:165], v[170:173], v[126:129]
	v_mfma_f32_16x16x32_bf16 v[114:117], v[150:153], v[178:181], v[114:117]
	v_mfma_f32_16x16x32_bf16 v[110:113], v[162:165], v[178:181], v[110:113]
	v_mfma_f32_16x16x32_bf16 v[98:101], v[150:153], v[200:203], v[98:101]
	v_mfma_f32_16x16x32_bf16 v[94:97], v[162:165], v[200:203], v[94:97]
	v_mfma_f32_16x16x32_bf16 v[82:85], v[150:153], v[208:211], v[82:85]
	v_mfma_f32_16x16x32_bf16 v[78:81], v[162:165], v[208:211], v[78:81]
	v_mfma_f32_16x16x32_bf16 v[130:133], v[158:161], v[174:177], v[130:133]
	v_mfma_f32_16x16x32_bf16 v[126:129], v[166:169], v[174:177], v[126:129]
	v_mfma_f32_16x16x32_bf16 v[114:117], v[158:161], v[196:199], v[114:117]
	v_mfma_f32_16x16x32_bf16 v[110:113], v[166:169], v[196:199], v[110:113]
	v_mfma_f32_16x16x32_bf16 v[98:101], v[158:161], v[204:207], v[98:101]
	v_mfma_f32_16x16x32_bf16 v[94:97], v[166:169], v[204:207], v[94:97]
	v_mfma_f32_16x16x32_bf16 v[82:85], v[158:161], v[212:215], v[82:85]
	v_mfma_f32_16x16x32_bf16 v[78:81], v[166:169], v[212:215], v[78:81]
	s_barrier
	s_add_i32 s9, 0, 0x1c000
	s_add_i32 s8, s8, s56
	v_add_u32_e32 v182, s9, v13
	v_lshl_add_u64 v[154:155], v[154:155], 0, s[36:37]
	s_mov_b32 m0, s8
	ds_read_b128 v[216:219], v182
	ds_read_b128 v[220:223], v182 offset:1024
	ds_read_b128 v[236:239], v182 offset:2048
	ds_read_b128 v[240:243], v182 offset:3072
	global_load_lds_dwordx4 v[154:155], off
	s_add_i32 m0, s8, 0x2000
	v_lshl_add_u64 v[154:155], v[186:187], 0, s[36:37]
	global_load_lds_dwordx4 v[154:155], off
	s_barrier
	s_waitcnt lgkmcnt(0)
	s_waitcnt lgkmcnt(0)
	v_mfma_f32_16x16x32_bf16 v[122:125], v[216:219], v[170:173], v[122:125]
	v_mfma_f32_16x16x32_bf16 v[118:121], v[236:239], v[170:173], v[118:121]
	v_mfma_f32_16x16x32_bf16 v[106:109], v[216:219], v[178:181], v[106:109]
	v_mfma_f32_16x16x32_bf16 v[102:105], v[236:239], v[178:181], v[102:105]
	v_mfma_f32_16x16x32_bf16 v[90:93], v[216:219], v[200:203], v[90:93]
	v_mfma_f32_16x16x32_bf16 v[86:89], v[236:239], v[200:203], v[86:89]
	v_mfma_f32_16x16x32_bf16 v[74:77], v[216:219], v[208:211], v[74:77]
	v_mfma_f32_16x16x32_bf16 v[70:73], v[236:239], v[208:211], v[70:73]
	v_mfma_f32_16x16x32_bf16 v[122:125], v[220:223], v[174:177], v[122:125]
	v_mfma_f32_16x16x32_bf16 v[118:121], v[240:243], v[174:177], v[118:121]
	v_mfma_f32_16x16x32_bf16 v[106:109], v[220:223], v[196:199], v[106:109]
	v_mfma_f32_16x16x32_bf16 v[102:105], v[240:243], v[196:199], v[102:105]
	v_mfma_f32_16x16x32_bf16 v[90:93], v[220:223], v[204:207], v[90:93]
	v_mfma_f32_16x16x32_bf16 v[86:89], v[240:243], v[204:207], v[86:89]
	v_mfma_f32_16x16x32_bf16 v[74:77], v[220:223], v[212:215], v[74:77]
	v_mfma_f32_16x16x32_bf16 v[70:73], v[240:243], v[212:215], v[70:73]
	s_mov_b32 m0, s62
	v_lshl_add_u64 v[154:155], v[188:189], 0, s[36:37]
	s_barrier
; #define PG8_STAGE(bufoff, gbase, voff) do { _Pragma("unroll") for (int _i = 0; _i < 2; ++_i) \
;         __builtin_amdgcn_global_load_lds((const unsigned*)((const char*)(gbase) + (voff)[_i]), (LAS unsigned*)(lds + (bufoff) + ldsw + _i * 8192), 16, 0, 0); } while (0)
; #define PG8_LDA(dst, b, h) do { _Pragma("unroll") for (int m = 0; m < 4; ++m) _Pragma("unroll") for (int k = 0; k < 2; ++k) dst[m][k] = *(const LAS bf16x8*)(lds + PG8_SA(b, h) + aoff + m * 2048 + k * 1024); } while (0)
; #define PG8_LDB(dst, b, h) do { _Pragma("unroll") for (int n = 0; n < 2; ++n) _Pragma("unroll") for (int k = 0; k < 2; ++k) dst[n][k] = *(const LAS bf16x8*)(lds + PG8_SB(b, h) + boff + n * 2048 + k * 1024); } while (0)
; #define PG8_MMA(ai, bj, At, Bt) do { __builtin_amdgcn_s_setprio(1); _Pragma("unroll") for (int m = 0; m < 4; ++m) _Pragma("unroll") for (int n = 0; n < 2; ++n) _Pragma("unroll") for (int k = 0; k < 2; ++k) \
;         acc[ai][bj][m][n] = __builtin_amdgcn_mfma_f32_16x16x32_bf16(Bt[n][k], At[m][k], acc[ai][bj][m][n], 0, 0, 0); __builtin_amdgcn_s_setprio(0); } while (0)
; #define PG8_WAIT_V(n) asm volatile("s_waitcnt vmcnt(" #n ")" ::: "memory")
; #define PG8_WAIT_L(n) asm volatile("s_waitcnt lgkmcnt(" #n ")" ::: "memory")
; #define PG8_BAR __builtin_amdgcn_s_barrier()
; #define PG8_SCHED __builtin_amdgcn_sched_barrier(0)
; template <class Epi, class Sched>
; __device__ __forceinline__ void gemm_phase(const int TID, LAS unsigned char* lds, const int lda, const int ldb, const Sched& S, const Epi& E) {
;     ...
;             PG8_WAIT_L(8); PG8_BAR; PG8_WAIT_L(0); PG8_MMA(0, 0, At, B0); PG8_BAR; PG8_SCHED;
;             PG8_LDB(B1, 1, 1); PG8_STAGE(PG8_SB(1, 0), b3, voffB);
;             PG8_BAR; PG8_WAIT_L(0); PG8_MMA(0, 1, At, B1); PG8_BAR;
;             PG8_LDA(At, 1, 1); PG8_STAGE(PG8_SA(1, 0), a3, voffA);
;             PG8_BAR; PG8_WAIT_L(0); PG8_MMA(1, 0, At, B0); PG8_BAR; PG8_SCHED;
;             PG8_STAGE(PG8_SB(1, 1), b3 + hB, voffB);
;             PG8_WAIT_V(6); PG8_BAR; PG8_MMA(1, 1, At, B1); PG8_BAR;
;         }
	ds_read_b128 v[170:173], v157 offset:49152
	ds_read_b128 v[174:177], v157 offset:50176
	ds_read_b128 v[178:181], v157 offset:51200
	ds_read_b128 v[196:199], v157 offset:52224
	ds_read_b128 v[200:203], v157 offset:53248
	ds_read_b128 v[204:207], v157 offset:54272
	ds_read_b128 v[208:211], v157 offset:55296
	ds_read_b128 v[212:215], v157 offset:56320
	global_load_lds_dwordx4 v[154:155], off
	s_mov_b32 m0, s63
	v_lshl_add_u64 v[154:155], v[244:245], 0, s[36:37]
	global_load_lds_dwordx4 v[154:155], off
	s_barrier
	s_waitcnt lgkmcnt(0)
	s_waitcnt lgkmcnt(0)
	v_mfma_f32_16x16x32_bf16 v[66:69], v[150:153], v[170:173], v[66:69]
	v_mfma_f32_16x16x32_bf16 v[62:65], v[162:165], v[170:173], v[62:65]
	v_mfma_f32_16x16x32_bf16 v[50:53], v[150:153], v[178:181], v[50:53]
	v_mfma_f32_16x16x32_bf16 v[46:49], v[162:165], v[178:181], v[46:49]
	v_mfma_f32_16x16x32_bf16 v[34:37], v[150:153], v[200:203], v[34:37]
	v_mfma_f32_16x16x32_bf16 v[30:33], v[162:165], v[200:203], v[30:33]
	v_mfma_f32_16x16x32_bf16 v[18:21], v[150:153], v[208:211], v[18:21]
	v_mfma_f32_16x16x32_bf16 v[8:11], v[162:165], v[208:211], v[8:11]
	v_mfma_f32_16x16x32_bf16 v[66:69], v[158:161], v[174:177], v[66:69]
	v_mfma_f32_16x16x32_bf16 v[62:65], v[166:169], v[174:177], v[62:65]
	v_mfma_f32_16x16x32_bf16 v[50:53], v[158:161], v[196:199], v[50:53]
	v_mfma_f32_16x16x32_bf16 v[46:49], v[166:169], v[196:199], v[46:49]
	v_mfma_f32_16x16x32_bf16 v[34:37], v[158:161], v[204:207], v[34:37]
	v_mfma_f32_16x16x32_bf16 v[30:33], v[166:169], v[204:207], v[30:33]
	v_mfma_f32_16x16x32_bf16 v[18:21], v[158:161], v[212:215], v[18:21]
	v_mfma_f32_16x16x32_bf16 v[8:11], v[166:169], v[212:215], v[8:11]
	s_barrier
	s_add_u32 s48, s48, 0x80080
	s_addc_u32 s49, s49, 0
	s_add_i32 s8, s9, s56
	s_mov_b32 m0, s8
	v_lshl_add_u64 v[150:151], s[48:49], 0, v[136:137]
	global_load_lds_dwordx4 v[150:151], off
	s_add_i32 m0, s8, 0x2000
	v_lshl_add_u64 v[150:151], s[48:49], 0, v[140:141]
	global_load_lds_dwordx4 v[150:151], off
	s_waitcnt vmcnt(6)
	s_barrier
	v_add_u32_e32 v154, 0x10000, v13
	v_mfma_f32_16x16x32_bf16 v[58:61], v[216:219], v[170:173], v[58:61]
	v_mfma_f32_16x16x32_bf16 v[54:57], v[236:239], v[170:173], v[54:57]
	v_mfma_f32_16x16x32_bf16 v[42:45], v[216:219], v[178:181], v[42:45]
	v_mfma_f32_16x16x32_bf16 v[38:41], v[236:239], v[178:181], v[38:41]
	ds_read_b128 v[150:153], v154
	v_mfma_f32_16x16x32_bf16 v[26:29], v[216:219], v[200:203], v[26:29]
	v_mfma_f32_16x16x32_bf16 v[22:25], v[236:239], v[200:203], v[22:25]
	ds_read_b128 v[158:161], v154 offset:1024
	v_mfma_f32_16x16x32_bf16 v[4:7], v[216:219], v[208:211], v[4:7]
	v_mfma_f32_16x16x32_bf16 v[0:3], v[236:239], v[208:211], v[0:3]
	ds_read_b128 v[162:165], v154 offset:2048
	v_mfma_f32_16x16x32_bf16 v[58:61], v[220:223], v[174:177], v[58:61]
	v_mfma_f32_16x16x32_bf16 v[54:57], v[240:243], v[174:177], v[54:57]
	ds_read_b128 v[166:169], v154 offset:3072
	v_mfma_f32_16x16x32_bf16 v[42:45], v[220:223], v[196:199], v[42:45]
	v_mfma_f32_16x16x32_bf16 v[38:41], v[240:243], v[196:199], v[38:41]
	v_mfma_f32_16x16x32_bf16 v[26:29], v[220:223], v[204:207], v[26:29]
	v_mfma_f32_16x16x32_bf16 v[22:25], v[240:243], v[204:207], v[22:25]
	v_mfma_f32_16x16x32_bf16 v[4:7], v[220:223], v[212:215], v[4:7]
	v_mfma_f32_16x16x32_bf16 v[0:3], v[240:243], v[212:215], v[0:3]
	s_add_i32 s29, s29, 2
	s_add_u32 s3, s3, 0x100
	s_addc_u32 s24, s24, 0
	s_add_u32 s46, s46, 0x100
	s_addc_u32 s47, s47, 0
	s_cmp_gt_u32 s29, 29
	s_barrier
	s_cbranch_scc0 .Lk1_body
	s_setprio 0
	s_waitcnt lgkmcnt(0)
	s_lshl_b32 s3, s40, 8
	s_sub_i32 s8, s65, 18
	s_add_i32 s3, s3, s61
	s_lshl_b32 s24, s65, 8
	s_cmp_gt_u32 s8, 23
	v_or_b32_e32 v158, s3, v12
	s_mov_b64 s[40:41], -1
	s_cbranch_scc0 .LBB0_1295
	s_cmp_gt_i32 s65, 1
	s_cselect_b64 s[46:47], -1, 0
	v_mad_i64_i32 v[150:151], s[40:41], v158, s4, 0
	v_or_b32_e32 v182, s24, v156
	s_mov_b64 s[40:41], -1
	s_and_b64 vcc, exec, s[46:47]
	v_lshl_add_u64 v[150:151], s[0:1], 0, v[150:151]
	s_cbranch_vccz .LBB0_1232
	v_lshl_add_u64 v[152:153], v[182:183], 1, v[150:151]
	s_mov_b64 s[40:41], 0
